# K-loops: 8 of 16 LDS-DMAs per iteration use the SGPR-base form (global_load_lds_dwordx4 v_off, s[base]) and lose their 64-bit VALU address add (load segments are issue-bound in the partner MFMA shadow
# speedup vs baseline: 1.0002x; 1.0002x over previous
; #define PG8_STAGE(bufoff, gbase, voff) do { _Pragma("unroll") for (int _i = 0; _i < 2; ++_i) \
;         __builtin_amdgcn_global_load_lds((const unsigned*)((const char*)(gbase) + (voff)[_i]), (LAS unsigned*)(lds + (bufoff) + ldsw + _i * 8192), 16, 0, 0); } while (0)
; #define PG8_LDA(dst, b, h) do { _Pragma("unroll") for (int m = 0; m < 4; ++m) _Pragma("unroll") for (int k = 0; k < 2; ++k) dst[m][k] = *(const LAS bf16x8*)(lds + PG8_SA(b, h) + aoff + m * 2048 + k * 1024); } while (0)
; #define PG8_LDB(dst, b, h) do { _Pragma("unroll") for (int n = 0; n < 2; ++n) _Pragma("unroll") for (int k = 0; k < 2; ++k) dst[n][k] = *(const LAS bf16x8*)(lds + PG8_SB(b, h) + boff + n * 2048 + k * 1024); } while (0)
; #define PG8_MMA(ai, bj, At, Bt) do { __builtin_amdgcn_s_setprio(1); _Pragma("unroll") for (int m = 0; m < 4; ++m) _Pragma("unroll") for (int n = 0; n < 2; ++n) _Pragma("unroll") for (int k = 0; k < 2; ++k) \
;         acc[ai][bj][m][n] = __builtin_amdgcn_mfma_f32_16x16x32_bf16(Bt[n][k], At[m][k], acc[ai][bj][m][n], 0, 0, 0); __builtin_amdgcn_s_setprio(0); } while (0)
; #define PG8_WAIT_V(n) asm volatile("s_waitcnt vmcnt(" #n ")" ::: "memory")
; #define PG8_WAIT_L(n) asm volatile("s_waitcnt lgkmcnt(" #n ")" ::: "memory")
; #define PG8_BAR __builtin_amdgcn_s_barrier()
; #define PG8_SCHED __builtin_amdgcn_sched_barrier(0)
; template <class Epi>
; __device__ __forceinline__ void gemm_phase(LAS unsigned char* lds, const int tid, const Gemm g, const StaticOrder& S, const Epi& E) {
;     ...
;         for (int t = 0; t < nt; t += 2) {
;             const bool last = (t == nt - 2);
;             const char* a1 = cA + (size_t)(t + 1) * kstep;
;             const char* a2 = last ? nA : cA + (size_t)(t + 2) * kstep; const char* b2 = last ? nB : cB + (size_t)(t + 2) * kstep;
;             const char* a3 = a2 + kstep; const char* b3 = b2 + kstep;
;             PG8_LDB(B0, 0, 0); PG8_LDB(B1, 0, 1); PG8_SCHED; PG8_LDA(At, 0, 0); PG8_STAGE(PG8_SA(1, 1), a1 + hstepA, voffA);
;             PG8_WAIT_V(8); PG8_WAIT_L(0); PG8_BAR; PG8_MMA(0, 0, At, B0); PG8_MMA(0, 1, At, B1); PG8_BAR; PG8_SCHED;
;             PG8_LDA(At, 0, 1); PG8_STAGE(PG8_SB(0, 0), b2, voffB); PG8_STAGE(PG8_SB(0, 1), b2 + hstepB, voffB); PG8_STAGE(PG8_SA(0, 0), a2, voffA);
;             PG8_WAIT_V(8); PG8_WAIT_L(0); PG8_BAR; PG8_MMA(1, 0, At, B0); PG8_MMA(1, 1, At, B1); PG8_BAR; PG8_SCHED;
.LBB0_414:
	s_add_u32 s10, s68, 0xfffc0080
	s_addc_u32 s11, s69, -1
	s_add_i32 s17, 0, 0x10000
	s_cmp_eq_u32 s16, 12
	s_cselect_b32 s73, s7, s11
	s_cselect_b32 s72, s67, s10
	s_cselect_b32 s71, s5, s76
	s_cselect_b32 s70, vcc_lo, vcc_hi
	s_add_i32 s0, 0, 0x14000
	v_add_u32_e32 v70, s17, v202
	v_add_u32_e32 v160, s0, v202
	ds_read_b128 v[50:53], v70
	ds_read_b128 v[54:57], v70 offset:1024
	ds_read_b128 v[66:69], v70 offset:2048
	ds_read_b128 v[70:73], v70 offset:3072
	ds_read_b128 v[156:159], v160
	ds_read_b128 v[170:173], v160 offset:1024
	ds_read_b128 v[174:177], v160 offset:2048
	ds_read_b128 v[178:181], v160 offset:3072
	s_add_i32 m0, s83, 0xc000
	s_nop 0
	global_load_lds_dwordx4 v152, s[68:69]
	s_add_i32 m0, s83, 0xe000
	s_nop 0
	global_load_lds_dwordx4 v154, s[68:69]
	ds_read_b128 v[216:219], v215
	ds_read_b128 v[220:223], v215 offset:1024
	ds_read_b128 v[224:227], v215 offset:2048
	ds_read_b128 v[228:231], v215 offset:3072
	ds_read_b128 v[232:235], v215 offset:4096
	ds_read_b128 v[236:239], v215 offset:5120
	ds_read_b128 v[240:243], v215 offset:6144
	ds_read_b128 v[244:247], v215 offset:7168
	s_waitcnt vmcnt(8)
	s_waitcnt lgkmcnt(0)
	s_barrier
	s_setprio 1
	s_waitcnt lgkmcnt(0)
	v_mfma_f32_16x16x32_bf16 v[142:145], v[50:53], v[216:219], v[142:145]
	v_mfma_f32_16x16x32_bf16 v[138:141], v[66:69], v[216:219], v[138:141]
	v_mfma_f32_16x16x32_bf16 v[126:129], v[50:53], v[224:227], v[126:129]
	v_mfma_f32_16x16x32_bf16 v[122:125], v[66:69], v[224:227], v[122:125]
	v_mfma_f32_16x16x32_bf16 v[110:113], v[50:53], v[232:235], v[110:113]
	v_mfma_f32_16x16x32_bf16 v[106:109], v[66:69], v[232:235], v[106:109]
	v_mfma_f32_16x16x32_bf16 v[94:97], v[50:53], v[240:243], v[94:97]
	v_mfma_f32_16x16x32_bf16 v[90:93], v[66:69], v[240:243], v[90:93]
	v_mfma_f32_16x16x32_bf16 v[142:145], v[54:57], v[220:223], v[142:145]
	v_mfma_f32_16x16x32_bf16 v[138:141], v[70:73], v[220:223], v[138:141]
	v_mfma_f32_16x16x32_bf16 v[126:129], v[54:57], v[228:231], v[126:129]
	v_mfma_f32_16x16x32_bf16 v[122:125], v[70:73], v[228:231], v[122:125]
	v_mfma_f32_16x16x32_bf16 v[110:113], v[54:57], v[236:239], v[110:113]
	v_mfma_f32_16x16x32_bf16 v[106:109], v[70:73], v[236:239], v[106:109]
	v_mfma_f32_16x16x32_bf16 v[94:97], v[54:57], v[244:247], v[94:97]
	v_mfma_f32_16x16x32_bf16 v[90:93], v[70:73], v[244:247], v[90:93]
	s_setprio 0
	s_setprio 1
	v_mfma_f32_16x16x32_bf16 v[134:137], v[156:159], v[216:219], v[134:137]
	v_mfma_f32_16x16x32_bf16 v[130:133], v[174:177], v[216:219], v[130:133]
	v_mfma_f32_16x16x32_bf16 v[118:121], v[156:159], v[224:227], v[118:121]
	v_mfma_f32_16x16x32_bf16 v[114:117], v[174:177], v[224:227], v[114:117]
	v_mfma_f32_16x16x32_bf16 v[102:105], v[156:159], v[232:235], v[102:105]
	v_mfma_f32_16x16x32_bf16 v[98:101], v[174:177], v[232:235], v[98:101]
	v_mfma_f32_16x16x32_bf16 v[86:89], v[156:159], v[240:243], v[86:89]
	v_mfma_f32_16x16x32_bf16 v[82:85], v[174:177], v[240:243], v[82:85]
	v_mfma_f32_16x16x32_bf16 v[134:137], v[170:173], v[220:223], v[134:137]
	v_mfma_f32_16x16x32_bf16 v[130:133], v[178:181], v[220:223], v[130:133]
	v_mfma_f32_16x16x32_bf16 v[118:121], v[170:173], v[228:231], v[118:121]
	v_mfma_f32_16x16x32_bf16 v[114:117], v[178:181], v[228:231], v[114:117]
	v_mfma_f32_16x16x32_bf16 v[102:105], v[170:173], v[236:239], v[102:105]
	v_mfma_f32_16x16x32_bf16 v[98:101], v[178:181], v[236:239], v[98:101]
	v_mfma_f32_16x16x32_bf16 v[86:89], v[170:173], v[244:247], v[86:89]
	v_mfma_f32_16x16x32_bf16 v[82:85], v[178:181], v[244:247], v[82:85]
	s_setprio 0
	s_barrier
	s_add_i32 s1, s17, s82
	v_lshl_add_u64 v[160:161], s[70:71], 0, v[0:1]
	s_mov_b32 m0, s1
	s_nop 0
	global_load_lds_dwordx4 v[160:161], off
	s_add_i32 m0, s1, 0x2000
	s_add_u32 s10, s70, 0x40000
	v_lshl_add_u64 v[182:183], s[70:71], 0, v[146:147]
	s_addc_u32 s11, s71, 0
	s_add_i32 s0, s0, s82
	global_load_lds_dwordx4 v[182:183], off
	s_mov_b32 m0, s0
	v_lshl_add_u64 v[164:165], s[72:73], 0, v[150:151]
	global_load_lds_dwordx4 v0, s[10:11]
	s_add_i32 m0, s0, 0x2000
	s_nop 0
	global_load_lds_dwordx4 v146, s[10:11]
	v_lshl_add_u64 v[162:163], s[72:73], 0, v[148:149]
	s_mov_b32 m0, s83
	s_nop 0
	global_load_lds_dwordx4 v[162:163], off
	s_mov_b32 m0, s88
	s_nop 0
	global_load_lds_dwordx4 v[164:165], off
	ds_read_b128 v[216:219], v215 offset:16384
	ds_read_b128 v[220:223], v215 offset:17408
	ds_read_b128 v[224:227], v215 offset:18432
	ds_read_b128 v[228:231], v215 offset:19456
	ds_read_b128 v[232:235], v215 offset:20480
	ds_read_b128 v[236:239], v215 offset:21504
	ds_read_b128 v[240:243], v215 offset:22528
	ds_read_b128 v[244:247], v215 offset:23552
	s_waitcnt vmcnt(8)
	s_waitcnt lgkmcnt(0)
	s_barrier
; #define PG8_STAGE(bufoff, gbase, voff) do { _Pragma("unroll") for (int _i = 0; _i < 2; ++_i) \
;         __builtin_amdgcn_global_load_lds((const unsigned*)((const char*)(gbase) + (voff)[_i]), (LAS unsigned*)(lds + (bufoff) + ldsw + _i * 8192), 16, 0, 0); } while (0)
; #define PG8_LDA(dst, b, h) do { _Pragma("unroll") for (int m = 0; m < 4; ++m) _Pragma("unroll") for (int k = 0; k < 2; ++k) dst[m][k] = *(const LAS bf16x8*)(lds + PG8_SA(b, h) + aoff + m * 2048 + k * 1024); } while (0)
; #define PG8_LDB(dst, b, h) do { _Pragma("unroll") for (int n = 0; n < 2; ++n) _Pragma("unroll") for (int k = 0; k < 2; ++k) dst[n][k] = *(const LAS bf16x8*)(lds + PG8_SB(b, h) + boff + n * 2048 + k * 1024); } while (0)
; #define PG8_MMA(ai, bj, At, Bt) do { __builtin_amdgcn_s_setprio(1); _Pragma("unroll") for (int m = 0; m < 4; ++m) _Pragma("unroll") for (int n = 0; n < 2; ++n) _Pragma("unroll") for (int k = 0; k < 2; ++k) \
;         acc[ai][bj][m][n] = __builtin_amdgcn_mfma_f32_16x16x32_bf16(Bt[n][k], At[m][k], acc[ai][bj][m][n], 0, 0, 0); __builtin_amdgcn_s_setprio(0); } while (0)
; #define PG8_WAIT_V(n) asm volatile("s_waitcnt vmcnt(" #n ")" ::: "memory")
; #define PG8_WAIT_L(n) asm volatile("s_waitcnt lgkmcnt(" #n ")" ::: "memory")
; #define PG8_BAR __builtin_amdgcn_s_barrier()
; #define PG8_SCHED __builtin_amdgcn_sched_barrier(0)
; template <class Epi>
; __device__ __forceinline__ void gemm_phase(LAS unsigned char* lds, const int tid, const Gemm g, const StaticOrder& S, const Epi& E) {
;     ...
;             PG8_WAIT_V(8); PG8_WAIT_L(0); PG8_BAR; PG8_MMA(1, 0, At, B0); PG8_MMA(1, 1, At, B1); PG8_BAR; PG8_SCHED;
;             PG8_LDB(B0, 1, 0); PG8_LDB(B1, 1, 1); PG8_SCHED; PG8_LDA(At, 1, 0); PG8_STAGE(PG8_SA(0, 1), a2 + hstepA, voffA);
;             PG8_WAIT_V(8); PG8_WAIT_L(0); PG8_BAR; PG8_MMA(0, 0, At, B0); PG8_MMA(0, 1, At, B1); PG8_BAR; PG8_SCHED;
	s_setprio 1
	s_waitcnt lgkmcnt(0)
	v_mfma_f32_16x16x32_bf16 v[78:81], v[50:53], v[216:219], v[78:81]
	v_mfma_f32_16x16x32_bf16 v[74:77], v[66:69], v[216:219], v[74:77]
	v_mfma_f32_16x16x32_bf16 v[46:49], v[50:53], v[224:227], v[46:49]
	v_mfma_f32_16x16x32_bf16 v[42:45], v[66:69], v[224:227], v[42:45]
	v_mfma_f32_16x16x32_bf16 v[30:33], v[50:53], v[232:235], v[30:33]
	v_mfma_f32_16x16x32_bf16 v[26:29], v[66:69], v[232:235], v[26:29]
	v_mfma_f32_16x16x32_bf16 v[14:17], v[50:53], v[240:243], v[14:17]
	v_mfma_f32_16x16x32_bf16 v[10:13], v[66:69], v[240:243], v[10:13]
	v_mfma_f32_16x16x32_bf16 v[78:81], v[54:57], v[220:223], v[78:81]
	v_mfma_f32_16x16x32_bf16 v[74:77], v[70:73], v[220:223], v[74:77]
	v_mfma_f32_16x16x32_bf16 v[46:49], v[54:57], v[228:231], v[46:49]
	v_mfma_f32_16x16x32_bf16 v[42:45], v[70:73], v[228:231], v[42:45]
	v_mfma_f32_16x16x32_bf16 v[30:33], v[54:57], v[236:239], v[30:33]
	v_mfma_f32_16x16x32_bf16 v[26:29], v[70:73], v[236:239], v[26:29]
	v_mfma_f32_16x16x32_bf16 v[14:17], v[54:57], v[244:247], v[14:17]
	v_mfma_f32_16x16x32_bf16 v[10:13], v[70:73], v[244:247], v[10:13]
	s_setprio 0
	s_setprio 1
	v_mfma_f32_16x16x32_bf16 v[38:41], v[156:159], v[224:227], v[38:41]
	v_mfma_f32_16x16x32_bf16 v[34:37], v[174:177], v[224:227], v[34:37]
	v_mfma_f32_16x16x32_bf16 v[22:25], v[156:159], v[232:235], v[22:25]
	v_mfma_f32_16x16x32_bf16 v[18:21], v[174:177], v[232:235], v[18:21]
	v_mfma_f32_16x16x32_bf16 v[6:9], v[156:159], v[240:243], v[6:9]
	v_mfma_f32_16x16x32_bf16 v[2:5], v[174:177], v[240:243], v[2:5]
	v_mfma_f32_16x16x32_bf16 v[50:53], v[156:159], v[216:219], v[62:65]
	v_mfma_f32_16x16x32_bf16 v[54:57], v[174:177], v[216:219], v[58:61]
	v_mfma_f32_16x16x32_bf16 v[38:41], v[170:173], v[228:231], v[38:41]
	v_mfma_f32_16x16x32_bf16 v[34:37], v[178:181], v[228:231], v[34:37]
	v_mfma_f32_16x16x32_bf16 v[22:25], v[170:173], v[236:239], v[22:25]
	v_mfma_f32_16x16x32_bf16 v[18:21], v[178:181], v[236:239], v[18:21]
	v_mfma_f32_16x16x32_bf16 v[6:9], v[170:173], v[244:247], v[6:9]
	v_mfma_f32_16x16x32_bf16 v[2:5], v[178:181], v[244:247], v[2:5]
	v_mfma_f32_16x16x32_bf16 v[50:53], v[170:173], v[220:223], v[50:53]
	v_mfma_f32_16x16x32_bf16 v[54:57], v[178:181], v[220:223], v[54:57]
	s_setprio 0
	s_barrier
	s_add_i32 s0, 0, 0x18000
	s_add_i32 s1, 0, 0x1c000
	v_add_u32_e32 v70, s0, v202
	v_add_u32_e32 v178, s1, v202
	ds_read_b128 v[58:61], v70
	ds_read_b128 v[62:65], v70 offset:1024
	ds_read_b128 v[66:69], v70 offset:2048
	ds_read_b128 v[70:73], v70 offset:3072
	ds_read_b128 v[156:159], v178
	ds_read_b128 v[170:173], v178 offset:1024
	ds_read_b128 v[174:177], v178 offset:2048
	ds_read_b128 v[178:181], v178 offset:3072
	s_add_u32 s10, s72, 0x40000
	s_addc_u32 s11, s73, 0
	s_mov_b32 m0, s89
	s_nop 0
	global_load_lds_dwordx4 v148, s[10:11]
	s_mov_b32 m0, s92
	s_nop 0
	global_load_lds_dwordx4 v150, s[10:11]
	ds_read_b128 v[216:219], v215 offset:32768
	ds_read_b128 v[220:223], v215 offset:33792
	ds_read_b128 v[224:227], v215 offset:34816
	ds_read_b128 v[228:231], v215 offset:35840
	ds_read_b128 v[232:235], v215 offset:36864
	ds_read_b128 v[236:239], v215 offset:37888
	ds_read_b128 v[240:243], v215 offset:38912
	ds_read_b128 v[244:247], v215 offset:39936
	s_waitcnt vmcnt(8)
	s_waitcnt lgkmcnt(0)
	s_barrier
	s_setprio 1
	s_waitcnt lgkmcnt(0)
	v_mfma_f32_16x16x32_bf16 v[142:145], v[58:61], v[216:219], v[142:145]
	v_mfma_f32_16x16x32_bf16 v[138:141], v[66:69], v[216:219], v[138:141]
	v_mfma_f32_16x16x32_bf16 v[126:129], v[58:61], v[224:227], v[126:129]
	v_mfma_f32_16x16x32_bf16 v[122:125], v[66:69], v[224:227], v[122:125]
	v_mfma_f32_16x16x32_bf16 v[110:113], v[58:61], v[232:235], v[110:113]
	v_mfma_f32_16x16x32_bf16 v[106:109], v[66:69], v[232:235], v[106:109]
	v_mfma_f32_16x16x32_bf16 v[94:97], v[58:61], v[240:243], v[94:97]
	v_mfma_f32_16x16x32_bf16 v[90:93], v[66:69], v[240:243], v[90:93]
	v_mfma_f32_16x16x32_bf16 v[142:145], v[62:65], v[220:223], v[142:145]
	v_mfma_f32_16x16x32_bf16 v[138:141], v[70:73], v[220:223], v[138:141]
	v_mfma_f32_16x16x32_bf16 v[126:129], v[62:65], v[228:231], v[126:129]
	v_mfma_f32_16x16x32_bf16 v[122:125], v[70:73], v[228:231], v[122:125]
	v_mfma_f32_16x16x32_bf16 v[110:113], v[62:65], v[236:239], v[110:113]
	v_mfma_f32_16x16x32_bf16 v[106:109], v[70:73], v[236:239], v[106:109]
	v_mfma_f32_16x16x32_bf16 v[94:97], v[62:65], v[244:247], v[94:97]
	v_mfma_f32_16x16x32_bf16 v[90:93], v[70:73], v[244:247], v[90:93]
	s_setprio 0
	s_setprio 1
	v_mfma_f32_16x16x32_bf16 v[134:137], v[156:159], v[216:219], v[134:137]
	v_mfma_f32_16x16x32_bf16 v[130:133], v[174:177], v[216:219], v[130:133]
	v_mfma_f32_16x16x32_bf16 v[118:121], v[156:159], v[224:227], v[118:121]
	v_mfma_f32_16x16x32_bf16 v[114:117], v[174:177], v[224:227], v[114:117]
	v_mfma_f32_16x16x32_bf16 v[102:105], v[156:159], v[232:235], v[102:105]
	v_mfma_f32_16x16x32_bf16 v[98:101], v[174:177], v[232:235], v[98:101]
	v_mfma_f32_16x16x32_bf16 v[86:89], v[156:159], v[240:243], v[86:89]
	v_mfma_f32_16x16x32_bf16 v[82:85], v[174:177], v[240:243], v[82:85]
	v_mfma_f32_16x16x32_bf16 v[134:137], v[170:173], v[220:223], v[134:137]
	v_mfma_f32_16x16x32_bf16 v[130:133], v[178:181], v[220:223], v[130:133]
	v_mfma_f32_16x16x32_bf16 v[118:121], v[170:173], v[228:231], v[118:121]
	v_mfma_f32_16x16x32_bf16 v[114:117], v[178:181], v[228:231], v[114:117]
	v_mfma_f32_16x16x32_bf16 v[102:105], v[170:173], v[236:239], v[102:105]
	v_mfma_f32_16x16x32_bf16 v[98:101], v[178:181], v[236:239], v[98:101]
	v_mfma_f32_16x16x32_bf16 v[86:89], v[170:173], v[244:247], v[86:89]
	v_mfma_f32_16x16x32_bf16 v[82:85], v[178:181], v[244:247], v[82:85]
	s_setprio 0
	s_barrier
; #define PG8_STAGE(bufoff, gbase, voff) do { _Pragma("unroll") for (int _i = 0; _i < 2; ++_i) \
;         __builtin_amdgcn_global_load_lds((const unsigned*)((const char*)(gbase) + (voff)[_i]), (LAS unsigned*)(lds + (bufoff) + ldsw + _i * 8192), 16, 0, 0); } while (0)
; #define PG8_LDA(dst, b, h) do { _Pragma("unroll") for (int m = 0; m < 4; ++m) _Pragma("unroll") for (int k = 0; k < 2; ++k) dst[m][k] = *(const LAS bf16x8*)(lds + PG8_SA(b, h) + aoff + m * 2048 + k * 1024); } while (0)
; #define PG8_MMA(ai, bj, At, Bt) do { __builtin_amdgcn_s_setprio(1); _Pragma("unroll") for (int m = 0; m < 4; ++m) _Pragma("unroll") for (int n = 0; n < 2; ++n) _Pragma("unroll") for (int k = 0; k < 2; ++k) \
;         acc[ai][bj][m][n] = __builtin_amdgcn_mfma_f32_16x16x32_bf16(Bt[n][k], At[m][k], acc[ai][bj][m][n], 0, 0, 0); __builtin_amdgcn_s_setprio(0); } while (0)
; #define PG8_WAIT_V(n) asm volatile("s_waitcnt vmcnt(" #n ")" ::: "memory")
; #define PG8_WAIT_L(n) asm volatile("s_waitcnt lgkmcnt(" #n ")" ::: "memory")
; #define PG8_BAR __builtin_amdgcn_s_barrier()
; #define PG8_SCHED __builtin_amdgcn_sched_barrier(0)
; template <class Epi>
; __device__ __forceinline__ void gemm_phase(LAS unsigned char* lds, const int tid, const Gemm g, const StaticOrder& S, const Epi& E) {
;     ...
;             PG8_LDA(At, 1, 1); PG8_STAGE(PG8_SB(1, 0), b3, voffB); PG8_STAGE(PG8_SB(1, 1), b3 + hstepB, voffB); PG8_STAGE(PG8_SA(1, 0), a3, voffA);
;             PG8_WAIT_V(8); PG8_WAIT_L(0); PG8_BAR; PG8_MMA(1, 0, At, B0); PG8_MMA(1, 1, At, B1); PG8_BAR; PG8_SCHED;
;         }
;         if (wr == 0) PG8_BAR;
	s_add_i32 s0, s0, s82
	v_lshl_add_u64 v[160:161], v[160:161], 0, s[36:37]
	s_mov_b32 m0, s0
	s_nop 0
	global_load_lds_dwordx4 v[160:161], off
	s_add_i32 m0, s0, 0x2000
	s_add_u32 s10, s70, 0x40080
	v_lshl_add_u64 v[160:161], v[182:183], 0, s[36:37]
	s_addc_u32 s11, s71, 0
	s_add_i32 s0, s1, s82
	global_load_lds_dwordx4 v[160:161], off
	s_mov_b32 m0, s0
	s_nop 0
	global_load_lds_dwordx4 v0, s[10:11]
	s_add_i32 m0, s0, 0x2000
	s_nop 0
	global_load_lds_dwordx4 v146, s[10:11]
	v_lshl_add_u64 v[160:161], v[162:163], 0, s[36:37]
	s_mov_b32 m0, s93
	s_nop 0
	global_load_lds_dwordx4 v[160:161], off
	v_lshl_add_u64 v[160:161], v[164:165], 0, s[36:37]
	s_mov_b32 m0, s74
	s_nop 0
	global_load_lds_dwordx4 v[160:161], off
	ds_read_b128 v[216:219], v215 offset:49152
	ds_read_b128 v[220:223], v215 offset:50176
	ds_read_b128 v[224:227], v215 offset:51200
	ds_read_b128 v[228:231], v215 offset:52224
	ds_read_b128 v[232:235], v215 offset:53248
	ds_read_b128 v[236:239], v215 offset:54272
	ds_read_b128 v[240:243], v215 offset:55296
	ds_read_b128 v[244:247], v215 offset:56320
	s_waitcnt vmcnt(8)
	s_waitcnt lgkmcnt(0)
	s_barrier
	s_setprio 1
	s_waitcnt lgkmcnt(0)
	v_mfma_f32_16x16x32_bf16 v[78:81], v[58:61], v[216:219], v[78:81]
	v_mfma_f32_16x16x32_bf16 v[74:77], v[66:69], v[216:219], v[74:77]
	v_mfma_f32_16x16x32_bf16 v[46:49], v[58:61], v[224:227], v[46:49]
	v_mfma_f32_16x16x32_bf16 v[42:45], v[66:69], v[224:227], v[42:45]
	v_mfma_f32_16x16x32_bf16 v[30:33], v[58:61], v[232:235], v[30:33]
	v_mfma_f32_16x16x32_bf16 v[26:29], v[66:69], v[232:235], v[26:29]
	v_mfma_f32_16x16x32_bf16 v[14:17], v[58:61], v[240:243], v[14:17]
	v_mfma_f32_16x16x32_bf16 v[10:13], v[66:69], v[240:243], v[10:13]
	v_mfma_f32_16x16x32_bf16 v[78:81], v[62:65], v[220:223], v[78:81]
	v_mfma_f32_16x16x32_bf16 v[74:77], v[70:73], v[220:223], v[74:77]
	v_mfma_f32_16x16x32_bf16 v[46:49], v[62:65], v[228:231], v[46:49]
	v_mfma_f32_16x16x32_bf16 v[42:45], v[70:73], v[228:231], v[42:45]
	v_mfma_f32_16x16x32_bf16 v[30:33], v[62:65], v[236:239], v[30:33]
	v_mfma_f32_16x16x32_bf16 v[26:29], v[70:73], v[236:239], v[26:29]
	v_mfma_f32_16x16x32_bf16 v[14:17], v[62:65], v[244:247], v[14:17]
	v_mfma_f32_16x16x32_bf16 v[10:13], v[70:73], v[244:247], v[10:13]
	s_setprio 0
	s_setprio 1
	v_mfma_f32_16x16x32_bf16 v[50:53], v[156:159], v[216:219], v[50:53]
	v_mfma_f32_16x16x32_bf16 v[62:65], v[170:173], v[220:223], v[50:53]
	v_mfma_f32_16x16x32_bf16 v[50:53], v[174:177], v[216:219], v[54:57]
	v_mfma_f32_16x16x32_bf16 v[38:41], v[156:159], v[224:227], v[38:41]
	v_mfma_f32_16x16x32_bf16 v[34:37], v[174:177], v[224:227], v[34:37]
	v_mfma_f32_16x16x32_bf16 v[22:25], v[156:159], v[232:235], v[22:25]
	v_mfma_f32_16x16x32_bf16 v[18:21], v[174:177], v[232:235], v[18:21]
	v_mfma_f32_16x16x32_bf16 v[6:9], v[156:159], v[240:243], v[6:9]
	v_mfma_f32_16x16x32_bf16 v[2:5], v[174:177], v[240:243], v[2:5]
	v_mfma_f32_16x16x32_bf16 v[58:61], v[178:181], v[220:223], v[50:53]
	v_mfma_f32_16x16x32_bf16 v[38:41], v[170:173], v[228:231], v[38:41]
	v_mfma_f32_16x16x32_bf16 v[34:37], v[178:181], v[228:231], v[34:37]
	v_mfma_f32_16x16x32_bf16 v[22:25], v[170:173], v[236:239], v[22:25]
	v_mfma_f32_16x16x32_bf16 v[18:21], v[178:181], v[236:239], v[18:21]
	v_mfma_f32_16x16x32_bf16 v[6:9], v[170:173], v[244:247], v[6:9]
	v_mfma_f32_16x16x32_bf16 v[2:5], v[178:181], v[244:247], v[2:5]
	s_setprio 0
	s_barrier
	s_add_i32 s16, s16, 2
	s_add_u32 s68, s68, 0x100
	s_addc_u32 s69, s69, 0
	s_add_u32 vcc_hi, vcc_hi, 0x100
	s_addc_u32 s76, s76, 0
	s_cmp_gt_u32 s16, 13
	s_cbranch_scc0 .LBB0_414
	s_and_b64 vcc, exec, s[2:3]
	s_cbranch_vccz .LBB0_417
	s_barrier

; #define PG8_STAGE(bufoff, gbase, voff) do { _Pragma("unroll") for (int _i = 0; _i < 2; ++_i) \
;         __builtin_amdgcn_global_load_lds((const unsigned*)((const char*)(gbase) + (voff)[_i]), (LAS unsigned*)(lds + (bufoff) + ldsw + _i * 8192), 16, 0, 0); } while (0)
; #define PG8_LDA(dst, b, h) do { _Pragma("unroll") for (int m = 0; m < 4; ++m) _Pragma("unroll") for (int k = 0; k < 2; ++k) dst[m][k] = *(const LAS bf16x8*)(lds + PG8_SA(b, h) + aoff + m * 2048 + k * 1024); } while (0)
; #define PG8_LDB(dst, b, h) do { _Pragma("unroll") for (int n = 0; n < 2; ++n) _Pragma("unroll") for (int k = 0; k < 2; ++k) dst[n][k] = *(const LAS bf16x8*)(lds + PG8_SB(b, h) + boff + n * 2048 + k * 1024); } while (0)
; #define PG8_MMA(ai, bj, At, Bt) do { __builtin_amdgcn_s_setprio(1); _Pragma("unroll") for (int m = 0; m < 4; ++m) _Pragma("unroll") for (int n = 0; n < 2; ++n) _Pragma("unroll") for (int k = 0; k < 2; ++k) \
;         acc[ai][bj][m][n] = __builtin_amdgcn_mfma_f32_16x16x32_bf16(Bt[n][k], At[m][k], acc[ai][bj][m][n], 0, 0, 0); __builtin_amdgcn_s_setprio(0); } while (0)
; #define PG8_WAIT_V(n) asm volatile("s_waitcnt vmcnt(" #n ")" ::: "memory")
; #define PG8_WAIT_L(n) asm volatile("s_waitcnt lgkmcnt(" #n ")" ::: "memory")
; #define PG8_BAR __builtin_amdgcn_s_barrier()
; #define PG8_SCHED __builtin_amdgcn_sched_barrier(0)
; template <class Epi>
; __device__ __forceinline__ void gemm_phase(LAS unsigned char* lds, const int tid, const Gemm g, const StaticOrder& S, const Epi& E) {
;     ...
;         for (int t = 0; t < nt; t += 2) {
;             const bool last = (t == nt - 2);
;             const char* a1 = cA + (size_t)(t + 1) * kstep;
;             const char* a2 = last ? nA : cA + (size_t)(t + 2) * kstep; const char* b2 = last ? nB : cB + (size_t)(t + 2) * kstep;
;             const char* a3 = a2 + kstep; const char* b3 = b2 + kstep;
;             PG8_LDB(B0, 0, 0); PG8_LDB(B1, 0, 1); PG8_SCHED; PG8_LDA(At, 0, 0); PG8_STAGE(PG8_SA(1, 1), a1 + hstepA, voffA);
;             PG8_WAIT_V(8); PG8_WAIT_L(0); PG8_BAR; PG8_MMA(0, 0, At, B0); PG8_MMA(0, 1, At, B1); PG8_BAR; PG8_SCHED;
;             PG8_LDA(At, 0, 1); PG8_STAGE(PG8_SB(0, 0), b2, voffB); PG8_STAGE(PG8_SB(0, 1), b2 + hstepB, voffB); PG8_STAGE(PG8_SA(0, 0), a2, voffA);
;             PG8_WAIT_V(8); PG8_WAIT_L(0); PG8_BAR; PG8_MMA(1, 0, At, B0); PG8_MMA(1, 1, At, B1); PG8_BAR; PG8_SCHED;
.LBB0_945:
	s_add_u32 s30, s72, 0xfffc0080
	s_addc_u32 s31, s73, -1
	s_add_i32 s76, 0, 0x10000
	s_cmp_eq_u32 vcc_hi, 12
	s_cselect_b32 s75, s9, s31
	s_cselect_b32 s74, s27, s30
	v_add_u32_e32 v0, s76, v178
	s_cselect_b32 s31, s7, vcc_lo
	s_cselect_b32 s30, s28, s65
	s_add_i32 s0, 0, 0x14000
	ds_read_b128 v[18:21], v0
	ds_read_b128 v[22:25], v0 offset:1024
	ds_read_b128 v[26:29], v0 offset:2048
	ds_read_b128 v[30:33], v0 offset:3072
	v_add_u32_e32 v0, s0, v178
	ds_read_b128 v[170:173], v0
	ds_read_b128 v[174:177], v0 offset:1024
	ds_read_b128 v[190:193], v0 offset:2048
	ds_read_b128 v[194:197], v0 offset:3072
	s_add_i32 m0, s71, 0xc000
	s_nop 0
	global_load_lds_dwordx4 v158, s[72:73]
	s_add_i32 m0, s71, 0xe000
	s_nop 0
	global_load_lds_dwordx4 v160, s[72:73]
	ds_read_b128 v[198:201], v189
	ds_read_b128 v[210:213], v189 offset:1024
	ds_read_b128 v[214:217], v189 offset:2048
	ds_read_b128 v[218:221], v189 offset:3072
	ds_read_b128 v[222:225], v189 offset:4096
	ds_read_b128 v[226:229], v189 offset:5120
	ds_read_b128 v[230:233], v189 offset:6144
	ds_read_b128 v[234:237], v189 offset:7168
	s_waitcnt vmcnt(8)
	s_waitcnt lgkmcnt(0)
	s_barrier
	s_setprio 1
	s_waitcnt lgkmcnt(0)
	v_mfma_f32_16x16x32_bf16 v[142:145], v[18:21], v[198:201], v[142:145]
	v_mfma_f32_16x16x32_bf16 v[138:141], v[26:29], v[198:201], v[138:141]
	v_mfma_f32_16x16x32_bf16 v[126:129], v[18:21], v[214:217], v[126:129]
	v_mfma_f32_16x16x32_bf16 v[122:125], v[26:29], v[214:217], v[122:125]
	v_mfma_f32_16x16x32_bf16 v[110:113], v[18:21], v[222:225], v[110:113]
	v_mfma_f32_16x16x32_bf16 v[106:109], v[26:29], v[222:225], v[106:109]
	v_mfma_f32_16x16x32_bf16 v[94:97], v[18:21], v[230:233], v[94:97]
	v_mfma_f32_16x16x32_bf16 v[90:93], v[26:29], v[230:233], v[90:93]
	v_mfma_f32_16x16x32_bf16 v[142:145], v[22:25], v[210:213], v[142:145]
	v_mfma_f32_16x16x32_bf16 v[138:141], v[30:33], v[210:213], v[138:141]
	v_mfma_f32_16x16x32_bf16 v[126:129], v[22:25], v[218:221], v[126:129]
	v_mfma_f32_16x16x32_bf16 v[122:125], v[30:33], v[218:221], v[122:125]
	v_mfma_f32_16x16x32_bf16 v[110:113], v[22:25], v[226:229], v[110:113]
	v_mfma_f32_16x16x32_bf16 v[106:109], v[30:33], v[226:229], v[106:109]
	v_mfma_f32_16x16x32_bf16 v[94:97], v[22:25], v[234:237], v[94:97]
	v_mfma_f32_16x16x32_bf16 v[90:93], v[30:33], v[234:237], v[90:93]
	s_setprio 0
	s_setprio 1
	v_mfma_f32_16x16x32_bf16 v[134:137], v[170:173], v[198:201], v[134:137]
	v_mfma_f32_16x16x32_bf16 v[130:133], v[190:193], v[198:201], v[130:133]
	v_mfma_f32_16x16x32_bf16 v[118:121], v[170:173], v[214:217], v[118:121]
	v_mfma_f32_16x16x32_bf16 v[114:117], v[190:193], v[214:217], v[114:117]
	v_mfma_f32_16x16x32_bf16 v[102:105], v[170:173], v[222:225], v[102:105]
	v_mfma_f32_16x16x32_bf16 v[98:101], v[190:193], v[222:225], v[98:101]
	v_mfma_f32_16x16x32_bf16 v[86:89], v[170:173], v[230:233], v[86:89]
	v_mfma_f32_16x16x32_bf16 v[82:85], v[190:193], v[230:233], v[82:85]
	v_mfma_f32_16x16x32_bf16 v[134:137], v[174:177], v[210:213], v[134:137]
	v_mfma_f32_16x16x32_bf16 v[130:133], v[194:197], v[210:213], v[130:133]
	v_mfma_f32_16x16x32_bf16 v[118:121], v[174:177], v[218:221], v[118:121]
	v_mfma_f32_16x16x32_bf16 v[114:117], v[194:197], v[218:221], v[114:117]
	v_mfma_f32_16x16x32_bf16 v[102:105], v[174:177], v[226:229], v[102:105]
	v_mfma_f32_16x16x32_bf16 v[98:101], v[194:197], v[226:229], v[98:101]
	v_mfma_f32_16x16x32_bf16 v[86:89], v[174:177], v[234:237], v[86:89]
	v_mfma_f32_16x16x32_bf16 v[82:85], v[194:197], v[234:237], v[82:85]
	s_setprio 0
	s_barrier
	s_add_i32 s1, s76, s93
	v_lshl_add_u64 v[162:163], s[30:31], 0, v[150:151]
	s_mov_b32 m0, s1
	s_nop 0
	global_load_lds_dwordx4 v[162:163], off
	s_add_i32 m0, s1, 0x2000
	s_add_u32 s76, s30, 0x40000
	v_lshl_add_u64 v[164:165], s[30:31], 0, v[154:155]
	s_addc_u32 s77, s31, 0
	s_add_i32 s0, s0, s93
	global_load_lds_dwordx4 v[164:165], off
	s_mov_b32 m0, s0
	v_lshl_add_u64 v[206:207], s[74:75], 0, v[152:153]
	global_load_lds_dwordx4 v150, s[76:77]
	s_add_i32 m0, s0, 0x2000
	s_nop 0
	global_load_lds_dwordx4 v154, s[76:77]
	v_lshl_add_u64 v[202:203], s[74:75], 0, v[148:149]
	s_mov_b32 m0, s71
	s_nop 0
	global_load_lds_dwordx4 v[202:203], off
	s_mov_b32 m0, s88
	s_nop 0
	global_load_lds_dwordx4 v[206:207], off
	ds_read_b128 v[198:201], v189 offset:16384
	ds_read_b128 v[210:213], v189 offset:17408
	ds_read_b128 v[214:217], v189 offset:18432
	ds_read_b128 v[218:221], v189 offset:19456
	ds_read_b128 v[222:225], v189 offset:20480
	ds_read_b128 v[226:229], v189 offset:21504
	ds_read_b128 v[230:233], v189 offset:22528
	ds_read_b128 v[234:237], v189 offset:23552
	s_waitcnt vmcnt(8)
	s_waitcnt lgkmcnt(0)
	s_barrier
; #define PG8_STAGE(bufoff, gbase, voff) do { _Pragma("unroll") for (int _i = 0; _i < 2; ++_i) \
;         __builtin_amdgcn_global_load_lds((const unsigned*)((const char*)(gbase) + (voff)[_i]), (LAS unsigned*)(lds + (bufoff) + ldsw + _i * 8192), 16, 0, 0); } while (0)
; #define PG8_LDA(dst, b, h) do { _Pragma("unroll") for (int m = 0; m < 4; ++m) _Pragma("unroll") for (int k = 0; k < 2; ++k) dst[m][k] = *(const LAS bf16x8*)(lds + PG8_SA(b, h) + aoff + m * 2048 + k * 1024); } while (0)
; #define PG8_LDB(dst, b, h) do { _Pragma("unroll") for (int n = 0; n < 2; ++n) _Pragma("unroll") for (int k = 0; k < 2; ++k) dst[n][k] = *(const LAS bf16x8*)(lds + PG8_SB(b, h) + boff + n * 2048 + k * 1024); } while (0)
; #define PG8_MMA(ai, bj, At, Bt) do { __builtin_amdgcn_s_setprio(1); _Pragma("unroll") for (int m = 0; m < 4; ++m) _Pragma("unroll") for (int n = 0; n < 2; ++n) _Pragma("unroll") for (int k = 0; k < 2; ++k) \
;         acc[ai][bj][m][n] = __builtin_amdgcn_mfma_f32_16x16x32_bf16(Bt[n][k], At[m][k], acc[ai][bj][m][n], 0, 0, 0); __builtin_amdgcn_s_setprio(0); } while (0)
; #define PG8_WAIT_V(n) asm volatile("s_waitcnt vmcnt(" #n ")" ::: "memory")
; #define PG8_WAIT_L(n) asm volatile("s_waitcnt lgkmcnt(" #n ")" ::: "memory")
; #define PG8_BAR __builtin_amdgcn_s_barrier()
; #define PG8_SCHED __builtin_amdgcn_sched_barrier(0)
; template <class Epi>
; __device__ __forceinline__ void gemm_phase(LAS unsigned char* lds, const int tid, const Gemm g, const StaticOrder& S, const Epi& E) {
;     ...
;             PG8_WAIT_V(8); PG8_WAIT_L(0); PG8_BAR; PG8_MMA(1, 0, At, B0); PG8_MMA(1, 1, At, B1); PG8_BAR; PG8_SCHED;
;             PG8_LDB(B0, 1, 0); PG8_LDB(B1, 1, 1); PG8_SCHED; PG8_LDA(At, 1, 0); PG8_STAGE(PG8_SA(0, 1), a2 + hstepA, voffA);
;             PG8_WAIT_V(8); PG8_WAIT_L(0); PG8_BAR; PG8_MMA(0, 0, At, B0); PG8_MMA(0, 1, At, B1); PG8_BAR; PG8_SCHED;
	s_setprio 1
	s_waitcnt lgkmcnt(0)
	v_mfma_f32_16x16x32_bf16 v[78:81], v[18:21], v[198:201], v[78:81]
	v_mfma_f32_16x16x32_bf16 v[74:77], v[26:29], v[198:201], v[74:77]
	v_mfma_f32_16x16x32_bf16 v[62:65], v[18:21], v[214:217], v[62:65]
	v_mfma_f32_16x16x32_bf16 v[58:61], v[26:29], v[214:217], v[58:61]
	v_mfma_f32_16x16x32_bf16 v[46:49], v[18:21], v[222:225], v[46:49]
	v_mfma_f32_16x16x32_bf16 v[42:45], v[26:29], v[222:225], v[42:45]
	v_mfma_f32_16x16x32_bf16 v[14:17], v[18:21], v[230:233], v[14:17]
	v_mfma_f32_16x16x32_bf16 v[10:13], v[26:29], v[230:233], v[10:13]
	v_mfma_f32_16x16x32_bf16 v[78:81], v[22:25], v[210:213], v[78:81]
	v_mfma_f32_16x16x32_bf16 v[74:77], v[30:33], v[210:213], v[74:77]
	v_mfma_f32_16x16x32_bf16 v[62:65], v[22:25], v[218:221], v[62:65]
	v_mfma_f32_16x16x32_bf16 v[58:61], v[30:33], v[218:221], v[58:61]
	v_mfma_f32_16x16x32_bf16 v[46:49], v[22:25], v[226:229], v[46:49]
	v_mfma_f32_16x16x32_bf16 v[42:45], v[30:33], v[226:229], v[42:45]
	v_mfma_f32_16x16x32_bf16 v[14:17], v[22:25], v[234:237], v[14:17]
	v_mfma_f32_16x16x32_bf16 v[10:13], v[30:33], v[234:237], v[10:13]
	s_setprio 0
	s_setprio 1
	v_mfma_f32_16x16x32_bf16 v[38:41], v[170:173], v[222:225], v[38:41]
	v_mfma_f32_16x16x32_bf16 v[34:37], v[190:193], v[222:225], v[34:37]
	v_mfma_f32_16x16x32_bf16 v[6:9], v[170:173], v[230:233], v[6:9]
	v_mfma_f32_16x16x32_bf16 v[2:5], v[190:193], v[230:233], v[2:5]
	v_mfma_f32_16x16x32_bf16 v[18:21], v[170:173], v[198:201], v[70:73]
	v_mfma_f32_16x16x32_bf16 v[22:25], v[190:193], v[198:201], v[66:69]
	v_mfma_f32_16x16x32_bf16 v[26:29], v[170:173], v[214:217], v[54:57]
	v_mfma_f32_16x16x32_bf16 v[30:33], v[190:193], v[214:217], v[50:53]
	v_mfma_f32_16x16x32_bf16 v[38:41], v[174:177], v[226:229], v[38:41]
	v_mfma_f32_16x16x32_bf16 v[34:37], v[194:197], v[226:229], v[34:37]
	v_mfma_f32_16x16x32_bf16 v[6:9], v[174:177], v[234:237], v[6:9]
	v_mfma_f32_16x16x32_bf16 v[2:5], v[194:197], v[234:237], v[2:5]
	v_mfma_f32_16x16x32_bf16 v[18:21], v[174:177], v[210:213], v[18:21]
	v_mfma_f32_16x16x32_bf16 v[22:25], v[194:197], v[210:213], v[22:25]
	v_mfma_f32_16x16x32_bf16 v[26:29], v[174:177], v[218:221], v[26:29]
	v_mfma_f32_16x16x32_bf16 v[30:33], v[194:197], v[218:221], v[30:33]
	s_setprio 0
	s_barrier
	s_add_i32 s0, 0, 0x18000
	v_add_u32_e32 v0, s0, v178
	s_add_i32 s1, 0, 0x1c000
	ds_read_b128 v[50:53], v0
	ds_read_b128 v[54:57], v0 offset:1024
	ds_read_b128 v[66:69], v0 offset:2048
	ds_read_b128 v[70:73], v0 offset:3072
	v_add_u32_e32 v0, s1, v178
	ds_read_b128 v[170:173], v0
	ds_read_b128 v[174:177], v0 offset:1024
	ds_read_b128 v[190:193], v0 offset:2048
	ds_read_b128 v[194:197], v0 offset:3072
	s_add_u32 s74, s74, 0x40000
	s_addc_u32 s75, s75, 0
	s_mov_b32 m0, s83
	s_nop 0
	global_load_lds_dwordx4 v148, s[74:75]
	s_mov_b32 m0, s16
	s_nop 0
	global_load_lds_dwordx4 v152, s[74:75]
	ds_read_b128 v[198:201], v189 offset:32768
	ds_read_b128 v[210:213], v189 offset:33792
	ds_read_b128 v[214:217], v189 offset:34816
	ds_read_b128 v[218:221], v189 offset:35840
	ds_read_b128 v[222:225], v189 offset:36864
	ds_read_b128 v[226:229], v189 offset:37888
	ds_read_b128 v[230:233], v189 offset:38912
	ds_read_b128 v[234:237], v189 offset:39936
	s_waitcnt vmcnt(8)
	s_waitcnt lgkmcnt(0)
	s_barrier
	s_setprio 1
	s_waitcnt lgkmcnt(0)
	v_mfma_f32_16x16x32_bf16 v[142:145], v[50:53], v[198:201], v[142:145]
	v_mfma_f32_16x16x32_bf16 v[138:141], v[66:69], v[198:201], v[138:141]
	v_mfma_f32_16x16x32_bf16 v[126:129], v[50:53], v[214:217], v[126:129]
	v_mfma_f32_16x16x32_bf16 v[122:125], v[66:69], v[214:217], v[122:125]
	v_mfma_f32_16x16x32_bf16 v[110:113], v[50:53], v[222:225], v[110:113]
	v_mfma_f32_16x16x32_bf16 v[106:109], v[66:69], v[222:225], v[106:109]
	v_mfma_f32_16x16x32_bf16 v[94:97], v[50:53], v[230:233], v[94:97]
	v_mfma_f32_16x16x32_bf16 v[90:93], v[66:69], v[230:233], v[90:93]
	v_mfma_f32_16x16x32_bf16 v[142:145], v[54:57], v[210:213], v[142:145]
	v_mfma_f32_16x16x32_bf16 v[138:141], v[70:73], v[210:213], v[138:141]
	v_mfma_f32_16x16x32_bf16 v[126:129], v[54:57], v[218:221], v[126:129]
	v_mfma_f32_16x16x32_bf16 v[122:125], v[70:73], v[218:221], v[122:125]
	v_mfma_f32_16x16x32_bf16 v[110:113], v[54:57], v[226:229], v[110:113]
	v_mfma_f32_16x16x32_bf16 v[106:109], v[70:73], v[226:229], v[106:109]
	v_mfma_f32_16x16x32_bf16 v[94:97], v[54:57], v[234:237], v[94:97]
	v_mfma_f32_16x16x32_bf16 v[90:93], v[70:73], v[234:237], v[90:93]
	s_setprio 0
	s_setprio 1
	v_mfma_f32_16x16x32_bf16 v[134:137], v[170:173], v[198:201], v[134:137]
	v_mfma_f32_16x16x32_bf16 v[130:133], v[190:193], v[198:201], v[130:133]
	v_mfma_f32_16x16x32_bf16 v[118:121], v[170:173], v[214:217], v[118:121]
	v_mfma_f32_16x16x32_bf16 v[114:117], v[190:193], v[214:217], v[114:117]
	v_mfma_f32_16x16x32_bf16 v[102:105], v[170:173], v[222:225], v[102:105]
	v_mfma_f32_16x16x32_bf16 v[98:101], v[190:193], v[222:225], v[98:101]
	v_mfma_f32_16x16x32_bf16 v[86:89], v[170:173], v[230:233], v[86:89]
	v_mfma_f32_16x16x32_bf16 v[82:85], v[190:193], v[230:233], v[82:85]
	v_mfma_f32_16x16x32_bf16 v[134:137], v[174:177], v[210:213], v[134:137]
	v_mfma_f32_16x16x32_bf16 v[130:133], v[194:197], v[210:213], v[130:133]
	v_mfma_f32_16x16x32_bf16 v[118:121], v[174:177], v[218:221], v[118:121]
	v_mfma_f32_16x16x32_bf16 v[114:117], v[194:197], v[218:221], v[114:117]
	v_mfma_f32_16x16x32_bf16 v[102:105], v[174:177], v[226:229], v[102:105]
	v_mfma_f32_16x16x32_bf16 v[98:101], v[194:197], v[226:229], v[98:101]
	v_mfma_f32_16x16x32_bf16 v[86:89], v[174:177], v[234:237], v[86:89]
	v_mfma_f32_16x16x32_bf16 v[82:85], v[194:197], v[234:237], v[82:85]
	s_setprio 0
	s_barrier
; #define PG8_STAGE(bufoff, gbase, voff) do { _Pragma("unroll") for (int _i = 0; _i < 2; ++_i) \
;         __builtin_amdgcn_global_load_lds((const unsigned*)((const char*)(gbase) + (voff)[_i]), (LAS unsigned*)(lds + (bufoff) + ldsw + _i * 8192), 16, 0, 0); } while (0)
; #define PG8_LDA(dst, b, h) do { _Pragma("unroll") for (int m = 0; m < 4; ++m) _Pragma("unroll") for (int k = 0; k < 2; ++k) dst[m][k] = *(const LAS bf16x8*)(lds + PG8_SA(b, h) + aoff + m * 2048 + k * 1024); } while (0)
; #define PG8_MMA(ai, bj, At, Bt) do { __builtin_amdgcn_s_setprio(1); _Pragma("unroll") for (int m = 0; m < 4; ++m) _Pragma("unroll") for (int n = 0; n < 2; ++n) _Pragma("unroll") for (int k = 0; k < 2; ++k) \
;         acc[ai][bj][m][n] = __builtin_amdgcn_mfma_f32_16x16x32_bf16(Bt[n][k], At[m][k], acc[ai][bj][m][n], 0, 0, 0); __builtin_amdgcn_s_setprio(0); } while (0)
; #define PG8_WAIT_V(n) asm volatile("s_waitcnt vmcnt(" #n ")" ::: "memory")
; #define PG8_WAIT_L(n) asm volatile("s_waitcnt lgkmcnt(" #n ")" ::: "memory")
; #define PG8_BAR __builtin_amdgcn_s_barrier()
; #define PG8_SCHED __builtin_amdgcn_sched_barrier(0)
; template <class Epi>
; __device__ __forceinline__ void gemm_phase(LAS unsigned char* lds, const int tid, const Gemm g, const StaticOrder& S, const Epi& E) {
;     ...
;             PG8_LDA(At, 1, 1); PG8_STAGE(PG8_SB(1, 0), b3, voffB); PG8_STAGE(PG8_SB(1, 1), b3 + hstepB, voffB); PG8_STAGE(PG8_SA(1, 0), a3, voffA);
;             PG8_WAIT_V(8); PG8_WAIT_L(0); PG8_BAR; PG8_MMA(1, 0, At, B0); PG8_MMA(1, 1, At, B1); PG8_BAR; PG8_SCHED;
;         }
;         if (wr == 0) PG8_BAR;
	s_add_i32 s0, s0, s93
	v_lshl_add_u64 v[162:163], v[162:163], 0, s[36:37]
	s_mov_b32 m0, s0
	s_nop 0
	global_load_lds_dwordx4 v[162:163], off
	s_add_i32 m0, s0, 0x2000
	s_add_u32 s30, s30, 0x40080
	v_lshl_add_u64 v[162:163], v[164:165], 0, s[36:37]
	s_addc_u32 s31, s31, 0
	s_add_i32 s0, s1, s93
	global_load_lds_dwordx4 v[162:163], off
	s_mov_b32 m0, s0
	s_nop 0
	global_load_lds_dwordx4 v150, s[30:31]
	s_add_i32 m0, s0, 0x2000
	s_nop 0
	global_load_lds_dwordx4 v154, s[30:31]
	v_lshl_add_u64 v[162:163], v[202:203], 0, s[36:37]
	s_mov_b32 m0, s92
	s_nop 0
	global_load_lds_dwordx4 v[162:163], off
	v_lshl_add_u64 v[162:163], v[206:207], 0, s[36:37]
	s_mov_b32 m0, s89
	s_nop 0
	global_load_lds_dwordx4 v[162:163], off
	ds_read_b128 v[198:201], v189 offset:49152
	ds_read_b128 v[210:213], v189 offset:50176
	ds_read_b128 v[214:217], v189 offset:51200
	ds_read_b128 v[218:221], v189 offset:52224
	ds_read_b128 v[222:225], v189 offset:53248
	ds_read_b128 v[226:229], v189 offset:54272
	ds_read_b128 v[230:233], v189 offset:55296
	ds_read_b128 v[234:237], v189 offset:56320
	s_waitcnt vmcnt(8)
	s_waitcnt lgkmcnt(0)
	s_barrier
	s_setprio 1
	s_waitcnt lgkmcnt(0)
	v_mfma_f32_16x16x32_bf16 v[78:81], v[50:53], v[198:201], v[78:81]
	v_mfma_f32_16x16x32_bf16 v[74:77], v[66:69], v[198:201], v[74:77]
	v_mfma_f32_16x16x32_bf16 v[62:65], v[50:53], v[214:217], v[62:65]
	v_mfma_f32_16x16x32_bf16 v[58:61], v[66:69], v[214:217], v[58:61]
	v_mfma_f32_16x16x32_bf16 v[46:49], v[50:53], v[222:225], v[46:49]
	v_mfma_f32_16x16x32_bf16 v[42:45], v[66:69], v[222:225], v[42:45]
	v_mfma_f32_16x16x32_bf16 v[14:17], v[50:53], v[230:233], v[14:17]
	v_mfma_f32_16x16x32_bf16 v[10:13], v[66:69], v[230:233], v[10:13]
	v_mfma_f32_16x16x32_bf16 v[78:81], v[54:57], v[210:213], v[78:81]
	v_mfma_f32_16x16x32_bf16 v[74:77], v[70:73], v[210:213], v[74:77]
	v_mfma_f32_16x16x32_bf16 v[62:65], v[54:57], v[218:221], v[62:65]
	v_mfma_f32_16x16x32_bf16 v[58:61], v[70:73], v[218:221], v[58:61]
	v_mfma_f32_16x16x32_bf16 v[46:49], v[54:57], v[226:229], v[46:49]
	v_mfma_f32_16x16x32_bf16 v[42:45], v[70:73], v[226:229], v[42:45]
	v_mfma_f32_16x16x32_bf16 v[14:17], v[54:57], v[234:237], v[14:17]
	v_mfma_f32_16x16x32_bf16 v[10:13], v[70:73], v[234:237], v[10:13]
	s_setprio 0
	s_setprio 1
	v_mfma_f32_16x16x32_bf16 v[18:21], v[170:173], v[198:201], v[18:21]
	v_mfma_f32_16x16x32_bf16 v[70:73], v[174:177], v[210:213], v[18:21]
	v_mfma_f32_16x16x32_bf16 v[18:21], v[190:193], v[198:201], v[22:25]
	v_mfma_f32_16x16x32_bf16 v[66:69], v[194:197], v[210:213], v[18:21]
	v_mfma_f32_16x16x32_bf16 v[18:21], v[170:173], v[214:217], v[26:29]
	v_mfma_f32_16x16x32_bf16 v[54:57], v[174:177], v[218:221], v[18:21]
	v_mfma_f32_16x16x32_bf16 v[18:21], v[190:193], v[214:217], v[30:33]
	v_mfma_f32_16x16x32_bf16 v[50:53], v[194:197], v[218:221], v[18:21]
	v_mfma_f32_16x16x32_bf16 v[18:21], v[170:173], v[222:225], v[38:41]
	v_mfma_f32_16x16x32_bf16 v[38:41], v[174:177], v[226:229], v[18:21]
	v_mfma_f32_16x16x32_bf16 v[18:21], v[190:193], v[222:225], v[34:37]
	v_mfma_f32_16x16x32_bf16 v[6:9], v[170:173], v[230:233], v[6:9]
	v_mfma_f32_16x16x32_bf16 v[2:5], v[190:193], v[230:233], v[2:5]
	v_mfma_f32_16x16x32_bf16 v[34:37], v[194:197], v[226:229], v[18:21]
	v_mfma_f32_16x16x32_bf16 v[6:9], v[174:177], v[234:237], v[6:9]
	v_mfma_f32_16x16x32_bf16 v[2:5], v[194:197], v[234:237], v[2:5]
	s_setprio 0
	s_barrier
	s_add_i32 vcc_hi, vcc_hi, 2
	s_add_u32 s72, s72, 0x100
	s_addc_u32 s73, s73, 0
	s_add_u32 s65, s65, 0x100
	s_addc_u32 vcc_lo, vcc_lo, 0
	s_cmp_gt_u32 vcc_hi, 13
	s_cbranch_scc0 .LBB0_945
	s_and_b64 vcc, exec, s[4:5]
	s_cbranch_vccz .LBB0_948
	s_barrier

; #define PG8_STAGE(bufoff, gbase, voff) do { _Pragma("unroll") for (int _i = 0; _i < 2; ++_i) \
;         __builtin_amdgcn_global_load_lds((const unsigned*)((const char*)(gbase) + (voff)[_i]), (LAS unsigned*)(lds + (bufoff) + ldsw + _i * 8192), 16, 0, 0); } while (0)
; #define PG8_LDA(dst, b, h) do { _Pragma("unroll") for (int m = 0; m < 4; ++m) _Pragma("unroll") for (int k = 0; k < 2; ++k) dst[m][k] = *(const LAS bf16x8*)(lds + PG8_SA(b, h) + aoff + m * 2048 + k * 1024); } while (0)
; #define PG8_LDB(dst, b, h) do { _Pragma("unroll") for (int n = 0; n < 2; ++n) _Pragma("unroll") for (int k = 0; k < 2; ++k) dst[n][k] = *(const LAS bf16x8*)(lds + PG8_SB(b, h) + boff + n * 2048 + k * 1024); } while (0)
; #define PG8_MMA(ai, bj, At, Bt) do { __builtin_amdgcn_s_setprio(1); _Pragma("unroll") for (int m = 0; m < 4; ++m) _Pragma("unroll") for (int n = 0; n < 2; ++n) _Pragma("unroll") for (int k = 0; k < 2; ++k) \
;         acc[ai][bj][m][n] = __builtin_amdgcn_mfma_f32_16x16x32_bf16(Bt[n][k], At[m][k], acc[ai][bj][m][n], 0, 0, 0); __builtin_amdgcn_s_setprio(0); } while (0)
; #define PG8_WAIT_V(n) asm volatile("s_waitcnt vmcnt(" #n ")" ::: "memory")
; #define PG8_WAIT_L(n) asm volatile("s_waitcnt lgkmcnt(" #n ")" ::: "memory")
; #define PG8_BAR __builtin_amdgcn_s_barrier()
; #define PG8_SCHED __builtin_amdgcn_sched_barrier(0)
; template <class Epi>
; __device__ __forceinline__ void gemm_phase(LAS unsigned char* lds, const int tid, const Gemm g, const StaticOrder& S, const Epi& E) {
;     ...
;         for (int t = 0; t < nt; t += 2) {
;             const bool last = (t == nt - 2);
;             const char* a1 = cA + (size_t)(t + 1) * kstep;
;             const char* a2 = last ? nA : cA + (size_t)(t + 2) * kstep; const char* b2 = last ? nB : cB + (size_t)(t + 2) * kstep;
;             const char* a3 = a2 + kstep; const char* b3 = b2 + kstep;
;             PG8_LDB(B0, 0, 0); PG8_LDB(B1, 0, 1); PG8_SCHED; PG8_LDA(At, 0, 0); PG8_STAGE(PG8_SA(1, 1), a1 + hstepA, voffA);
;             PG8_WAIT_V(8); PG8_WAIT_L(0); PG8_BAR; PG8_MMA(0, 0, At, B0); PG8_MMA(0, 1, At, B1); PG8_BAR; PG8_SCHED;
;             PG8_LDA(At, 0, 1); PG8_STAGE(PG8_SB(0, 0), b2, voffB); PG8_STAGE(PG8_SB(0, 1), b2 + hstepB, voffB); PG8_STAGE(PG8_SA(0, 0), a2, voffA);
;             PG8_WAIT_V(8); PG8_WAIT_L(0); PG8_BAR; PG8_MMA(1, 0, At, B0); PG8_MMA(1, 1, At, B1); PG8_BAR; PG8_SCHED;
.LBB0_1284:
	s_add_u32 s2, s66, 0xfff80080
	s_addc_u32 s3, s67, -1
	s_add_i32 vcc_hi, 0, 0x10000
	s_cmp_eq_u32 vcc_lo, 12
	s_cselect_b32 s69, s11, s3
	s_cselect_b32 s68, s88, s2
	v_add_u32_e32 v144, vcc_hi, v171
	s_cselect_b32 s31, s9, s93
	s_cselect_b32 s30, s89, s92
	s_add_i32 s0, 0, 0x14000
	ds_read_b128 v[140:143], v144
	ds_read_b128 v[176:179], v144 offset:1024
	ds_read_b128 v[180:183], v144 offset:2048
	ds_read_b128 v[184:187], v144 offset:3072
	v_add_u32_e32 v144, s0, v171
	ds_read_b128 v[188:191], v144
	ds_read_b128 v[192:195], v144 offset:1024
	ds_read_b128 v[196:199], v144 offset:2048
	ds_read_b128 v[200:203], v144 offset:3072
	s_add_i32 m0, s71, 0xc000
	s_nop 0
	global_load_lds_dwordx4 v136, s[66:67]
	s_add_i32 m0, s71, 0xe000
	s_nop 0
	global_load_lds_dwordx4 v138, s[66:67]
	ds_read_b128 v[210:213], v174
	ds_read_b128 v[214:217], v174 offset:1024
	ds_read_b128 v[218:221], v174 offset:2048
	ds_read_b128 v[222:225], v174 offset:3072
	ds_read_b128 v[226:229], v174 offset:4096
	ds_read_b128 v[230:233], v174 offset:5120
	ds_read_b128 v[234:237], v174 offset:6144
	ds_read_b128 v[238:241], v174 offset:7168
	s_waitcnt vmcnt(8)
	s_waitcnt lgkmcnt(0)
	s_barrier
	s_setprio 1
	s_waitcnt lgkmcnt(0)
	v_mfma_f32_16x16x32_bf16 v[126:129], v[140:143], v[210:213], v[126:129]
	v_mfma_f32_16x16x32_bf16 v[122:125], v[180:183], v[210:213], v[122:125]
	v_mfma_f32_16x16x32_bf16 v[118:121], v[140:143], v[218:221], v[118:121]
	v_mfma_f32_16x16x32_bf16 v[110:113], v[180:183], v[218:221], v[110:113]
	v_mfma_f32_16x16x32_bf16 v[94:97], v[140:143], v[226:229], v[94:97]
	v_mfma_f32_16x16x32_bf16 v[90:93], v[180:183], v[226:229], v[90:93]
	v_mfma_f32_16x16x32_bf16 v[86:89], v[140:143], v[234:237], v[86:89]
	v_mfma_f32_16x16x32_bf16 v[78:81], v[180:183], v[234:237], v[78:81]
	v_mfma_f32_16x16x32_bf16 v[126:129], v[176:179], v[214:217], v[126:129]
	v_mfma_f32_16x16x32_bf16 v[122:125], v[184:187], v[214:217], v[122:125]
	v_mfma_f32_16x16x32_bf16 v[118:121], v[176:179], v[222:225], v[118:121]
	v_mfma_f32_16x16x32_bf16 v[110:113], v[184:187], v[222:225], v[110:113]
	v_mfma_f32_16x16x32_bf16 v[94:97], v[176:179], v[230:233], v[94:97]
	v_mfma_f32_16x16x32_bf16 v[90:93], v[184:187], v[230:233], v[90:93]
	v_mfma_f32_16x16x32_bf16 v[86:89], v[176:179], v[238:241], v[86:89]
	v_mfma_f32_16x16x32_bf16 v[78:81], v[184:187], v[238:241], v[78:81]
	s_setprio 0
	s_setprio 1
	v_mfma_f32_16x16x32_bf16 v[114:117], v[188:191], v[210:213], v[114:117]
	v_mfma_f32_16x16x32_bf16 v[106:109], v[196:199], v[210:213], v[106:109]
	v_mfma_f32_16x16x32_bf16 v[102:105], v[188:191], v[218:221], v[102:105]
	v_mfma_f32_16x16x32_bf16 v[98:101], v[196:199], v[218:221], v[98:101]
	v_mfma_f32_16x16x32_bf16 v[82:85], v[188:191], v[226:229], v[82:85]
	v_mfma_f32_16x16x32_bf16 v[74:77], v[196:199], v[226:229], v[74:77]
	v_mfma_f32_16x16x32_bf16 v[70:73], v[188:191], v[234:237], v[70:73]
	v_mfma_f32_16x16x32_bf16 v[66:69], v[196:199], v[234:237], v[66:69]
	v_mfma_f32_16x16x32_bf16 v[114:117], v[192:195], v[214:217], v[114:117]
	v_mfma_f32_16x16x32_bf16 v[106:109], v[200:203], v[214:217], v[106:109]
	v_mfma_f32_16x16x32_bf16 v[102:105], v[192:195], v[222:225], v[102:105]
	v_mfma_f32_16x16x32_bf16 v[98:101], v[200:203], v[222:225], v[98:101]
	v_mfma_f32_16x16x32_bf16 v[82:85], v[192:195], v[230:233], v[82:85]
	v_mfma_f32_16x16x32_bf16 v[74:77], v[200:203], v[230:233], v[74:77]
	v_mfma_f32_16x16x32_bf16 v[70:73], v[192:195], v[238:241], v[70:73]
	v_mfma_f32_16x16x32_bf16 v[66:69], v[200:203], v[238:241], v[66:69]
	s_setprio 0
	s_barrier
	s_add_i32 s1, vcc_hi, s28
	v_lshl_add_u64 v[144:145], s[30:31], 0, v[0:1]
	s_mov_b32 m0, s1
	s_nop 0
	global_load_lds_dwordx4 v[144:145], off
	s_add_i32 m0, s1, 0x2000
	s_add_u32 s2, s30, 0x40000
	v_lshl_add_u64 v[162:163], s[30:31], 0, v[130:131]
	s_addc_u32 s3, s31, 0
	s_add_i32 s0, s0, s28
	global_load_lds_dwordx4 v[162:163], off
	s_mov_b32 m0, s0
	v_lshl_add_u64 v[206:207], s[68:69], 0, v[132:133]
	global_load_lds_dwordx4 v0, s[2:3]
	s_add_i32 m0, s0, 0x2000
	s_nop 0
	global_load_lds_dwordx4 v130, s[2:3]
	v_lshl_add_u64 v[164:165], s[68:69], 0, v[134:135]
	s_mov_b32 m0, s71
	s_nop 0
	global_load_lds_dwordx4 v[164:165], off
	s_mov_b32 m0, s72
	s_nop 0
	global_load_lds_dwordx4 v[206:207], off
	ds_read_b128 v[210:213], v174 offset:16384
	ds_read_b128 v[214:217], v174 offset:17408
	ds_read_b128 v[218:221], v174 offset:18432
	ds_read_b128 v[222:225], v174 offset:19456
	ds_read_b128 v[226:229], v174 offset:20480
	ds_read_b128 v[230:233], v174 offset:21504
	ds_read_b128 v[234:237], v174 offset:22528
	ds_read_b128 v[238:241], v174 offset:23552
	s_waitcnt vmcnt(8)
	s_waitcnt lgkmcnt(0)
	s_barrier
; #define PG8_STAGE(bufoff, gbase, voff) do { _Pragma("unroll") for (int _i = 0; _i < 2; ++_i) \
;         __builtin_amdgcn_global_load_lds((const unsigned*)((const char*)(gbase) + (voff)[_i]), (LAS unsigned*)(lds + (bufoff) + ldsw + _i * 8192), 16, 0, 0); } while (0)
; #define PG8_LDA(dst, b, h) do { _Pragma("unroll") for (int m = 0; m < 4; ++m) _Pragma("unroll") for (int k = 0; k < 2; ++k) dst[m][k] = *(const LAS bf16x8*)(lds + PG8_SA(b, h) + aoff + m * 2048 + k * 1024); } while (0)
; #define PG8_LDB(dst, b, h) do { _Pragma("unroll") for (int n = 0; n < 2; ++n) _Pragma("unroll") for (int k = 0; k < 2; ++k) dst[n][k] = *(const LAS bf16x8*)(lds + PG8_SB(b, h) + boff + n * 2048 + k * 1024); } while (0)
; #define PG8_MMA(ai, bj, At, Bt) do { __builtin_amdgcn_s_setprio(1); _Pragma("unroll") for (int m = 0; m < 4; ++m) _Pragma("unroll") for (int n = 0; n < 2; ++n) _Pragma("unroll") for (int k = 0; k < 2; ++k) \
;         acc[ai][bj][m][n] = __builtin_amdgcn_mfma_f32_16x16x32_bf16(Bt[n][k], At[m][k], acc[ai][bj][m][n], 0, 0, 0); __builtin_amdgcn_s_setprio(0); } while (0)
; #define PG8_WAIT_V(n) asm volatile("s_waitcnt vmcnt(" #n ")" ::: "memory")
; #define PG8_WAIT_L(n) asm volatile("s_waitcnt lgkmcnt(" #n ")" ::: "memory")
; #define PG8_BAR __builtin_amdgcn_s_barrier()
; #define PG8_SCHED __builtin_amdgcn_sched_barrier(0)
; template <class Epi>
; __device__ __forceinline__ void gemm_phase(LAS unsigned char* lds, const int tid, const Gemm g, const StaticOrder& S, const Epi& E) {
;     ...
;             PG8_WAIT_V(8); PG8_WAIT_L(0); PG8_BAR; PG8_MMA(1, 0, At, B0); PG8_MMA(1, 1, At, B1); PG8_BAR; PG8_SCHED;
;             PG8_LDB(B0, 1, 0); PG8_LDB(B1, 1, 1); PG8_SCHED; PG8_LDA(At, 1, 0); PG8_STAGE(PG8_SA(0, 1), a2 + hstepA, voffA);
;             PG8_WAIT_V(8); PG8_WAIT_L(0); PG8_BAR; PG8_MMA(0, 0, At, B0); PG8_MMA(0, 1, At, B1); PG8_BAR; PG8_SCHED;
	s_setprio 1
	s_waitcnt lgkmcnt(0)
	v_mfma_f32_16x16x32_bf16 v[62:65], v[140:143], v[210:213], v[62:65]
	v_mfma_f32_16x16x32_bf16 v[58:61], v[180:183], v[210:213], v[58:61]
	v_mfma_f32_16x16x32_bf16 v[54:57], v[140:143], v[218:221], v[54:57]
	v_mfma_f32_16x16x32_bf16 v[46:49], v[180:183], v[218:221], v[46:49]
	v_mfma_f32_16x16x32_bf16 v[30:33], v[140:143], v[226:229], v[30:33]
	v_mfma_f32_16x16x32_bf16 v[26:29], v[180:183], v[226:229], v[26:29]
	v_mfma_f32_16x16x32_bf16 v[22:25], v[140:143], v[234:237], v[22:25]
	v_mfma_f32_16x16x32_bf16 v[14:17], v[180:183], v[234:237], v[14:17]
	v_mfma_f32_16x16x32_bf16 v[62:65], v[176:179], v[214:217], v[62:65]
	v_mfma_f32_16x16x32_bf16 v[58:61], v[184:187], v[214:217], v[58:61]
	v_mfma_f32_16x16x32_bf16 v[54:57], v[176:179], v[222:225], v[54:57]
	v_mfma_f32_16x16x32_bf16 v[46:49], v[184:187], v[222:225], v[46:49]
	v_mfma_f32_16x16x32_bf16 v[30:33], v[176:179], v[230:233], v[30:33]
	v_mfma_f32_16x16x32_bf16 v[26:29], v[184:187], v[230:233], v[26:29]
	v_mfma_f32_16x16x32_bf16 v[22:25], v[176:179], v[238:241], v[22:25]
	v_mfma_f32_16x16x32_bf16 v[14:17], v[184:187], v[238:241], v[14:17]
	s_setprio 0
	s_setprio 1
	v_mfma_f32_16x16x32_bf16 v[50:53], v[188:191], v[210:213], v[50:53]
	v_mfma_f32_16x16x32_bf16 v[42:45], v[196:199], v[210:213], v[42:45]
	v_mfma_f32_16x16x32_bf16 v[38:41], v[188:191], v[218:221], v[38:41]
	v_mfma_f32_16x16x32_bf16 v[34:37], v[196:199], v[218:221], v[34:37]
	v_mfma_f32_16x16x32_bf16 v[18:21], v[188:191], v[226:229], v[18:21]
	v_mfma_f32_16x16x32_bf16 v[10:13], v[196:199], v[226:229], v[10:13]
	v_mfma_f32_16x16x32_bf16 v[6:9], v[188:191], v[234:237], v[6:9]
	v_mfma_f32_16x16x32_bf16 v[2:5], v[196:199], v[234:237], v[2:5]
	v_mfma_f32_16x16x32_bf16 v[50:53], v[192:195], v[214:217], v[50:53]
	v_mfma_f32_16x16x32_bf16 v[42:45], v[200:203], v[214:217], v[42:45]
	v_mfma_f32_16x16x32_bf16 v[38:41], v[192:195], v[222:225], v[38:41]
	v_mfma_f32_16x16x32_bf16 v[34:37], v[200:203], v[222:225], v[34:37]
	v_mfma_f32_16x16x32_bf16 v[18:21], v[192:195], v[230:233], v[18:21]
	v_mfma_f32_16x16x32_bf16 v[10:13], v[200:203], v[230:233], v[10:13]
	v_mfma_f32_16x16x32_bf16 v[6:9], v[192:195], v[238:241], v[6:9]
	v_mfma_f32_16x16x32_bf16 v[2:5], v[200:203], v[238:241], v[2:5]
	s_setprio 0
	s_barrier
	s_add_i32 s0, 0, 0x18000
	v_add_u32_e32 v175, s0, v171
	s_add_i32 s1, 0, 0x1c000
	ds_read_b128 v[140:143], v175
	ds_read_b128 v[176:179], v175 offset:1024
	ds_read_b128 v[180:183], v175 offset:2048
	ds_read_b128 v[184:187], v175 offset:3072
	v_add_u32_e32 v175, s1, v171
	ds_read_b128 v[188:191], v175
	ds_read_b128 v[192:195], v175 offset:1024
	ds_read_b128 v[196:199], v175 offset:2048
	ds_read_b128 v[200:203], v175 offset:3072
	s_add_u32 s2, s68, 0x80000
	s_addc_u32 s3, s69, 0
	s_mov_b32 m0, s73
	s_nop 0
	global_load_lds_dwordx4 v134, s[2:3]
	s_mov_b32 m0, s74
	s_nop 0
	global_load_lds_dwordx4 v132, s[2:3]
	ds_read_b128 v[210:213], v174 offset:32768
	ds_read_b128 v[214:217], v174 offset:33792
	ds_read_b128 v[218:221], v174 offset:34816
	ds_read_b128 v[222:225], v174 offset:35840
	ds_read_b128 v[226:229], v174 offset:36864
	ds_read_b128 v[230:233], v174 offset:37888
	ds_read_b128 v[234:237], v174 offset:38912
	ds_read_b128 v[238:241], v174 offset:39936
	s_waitcnt vmcnt(8)
	s_waitcnt lgkmcnt(0)
	s_barrier
	s_setprio 1
	s_waitcnt lgkmcnt(0)
	v_mfma_f32_16x16x32_bf16 v[126:129], v[140:143], v[210:213], v[126:129]
	v_mfma_f32_16x16x32_bf16 v[122:125], v[180:183], v[210:213], v[122:125]
	v_mfma_f32_16x16x32_bf16 v[118:121], v[140:143], v[218:221], v[118:121]
	v_mfma_f32_16x16x32_bf16 v[110:113], v[180:183], v[218:221], v[110:113]
	v_mfma_f32_16x16x32_bf16 v[94:97], v[140:143], v[226:229], v[94:97]
	v_mfma_f32_16x16x32_bf16 v[90:93], v[180:183], v[226:229], v[90:93]
	v_mfma_f32_16x16x32_bf16 v[86:89], v[140:143], v[234:237], v[86:89]
	v_mfma_f32_16x16x32_bf16 v[78:81], v[180:183], v[234:237], v[78:81]
	v_mfma_f32_16x16x32_bf16 v[126:129], v[176:179], v[214:217], v[126:129]
	v_mfma_f32_16x16x32_bf16 v[122:125], v[184:187], v[214:217], v[122:125]
	v_mfma_f32_16x16x32_bf16 v[118:121], v[176:179], v[222:225], v[118:121]
	v_mfma_f32_16x16x32_bf16 v[110:113], v[184:187], v[222:225], v[110:113]
	v_mfma_f32_16x16x32_bf16 v[94:97], v[176:179], v[230:233], v[94:97]
	v_mfma_f32_16x16x32_bf16 v[90:93], v[184:187], v[230:233], v[90:93]
	v_mfma_f32_16x16x32_bf16 v[86:89], v[176:179], v[238:241], v[86:89]
	v_mfma_f32_16x16x32_bf16 v[78:81], v[184:187], v[238:241], v[78:81]
	s_setprio 0
	s_setprio 1
	v_mfma_f32_16x16x32_bf16 v[114:117], v[188:191], v[210:213], v[114:117]
	v_mfma_f32_16x16x32_bf16 v[106:109], v[196:199], v[210:213], v[106:109]
	v_mfma_f32_16x16x32_bf16 v[102:105], v[188:191], v[218:221], v[102:105]
	v_mfma_f32_16x16x32_bf16 v[98:101], v[196:199], v[218:221], v[98:101]
	v_mfma_f32_16x16x32_bf16 v[82:85], v[188:191], v[226:229], v[82:85]
	v_mfma_f32_16x16x32_bf16 v[74:77], v[196:199], v[226:229], v[74:77]
	v_mfma_f32_16x16x32_bf16 v[70:73], v[188:191], v[234:237], v[70:73]
	v_mfma_f32_16x16x32_bf16 v[66:69], v[196:199], v[234:237], v[66:69]
	v_mfma_f32_16x16x32_bf16 v[114:117], v[192:195], v[214:217], v[114:117]
	v_mfma_f32_16x16x32_bf16 v[106:109], v[200:203], v[214:217], v[106:109]
	v_mfma_f32_16x16x32_bf16 v[102:105], v[192:195], v[222:225], v[102:105]
	v_mfma_f32_16x16x32_bf16 v[98:101], v[200:203], v[222:225], v[98:101]
	v_mfma_f32_16x16x32_bf16 v[82:85], v[192:195], v[230:233], v[82:85]
	v_mfma_f32_16x16x32_bf16 v[74:77], v[200:203], v[230:233], v[74:77]
	v_mfma_f32_16x16x32_bf16 v[70:73], v[192:195], v[238:241], v[70:73]
	v_mfma_f32_16x16x32_bf16 v[66:69], v[200:203], v[238:241], v[66:69]
	s_setprio 0
	s_barrier
; #define PG8_STAGE(bufoff, gbase, voff) do { _Pragma("unroll") for (int _i = 0; _i < 2; ++_i) \
;         __builtin_amdgcn_global_load_lds((const unsigned*)((const char*)(gbase) + (voff)[_i]), (LAS unsigned*)(lds + (bufoff) + ldsw + _i * 8192), 16, 0, 0); } while (0)
; #define PG8_LDA(dst, b, h) do { _Pragma("unroll") for (int m = 0; m < 4; ++m) _Pragma("unroll") for (int k = 0; k < 2; ++k) dst[m][k] = *(const LAS bf16x8*)(lds + PG8_SA(b, h) + aoff + m * 2048 + k * 1024); } while (0)
; #define PG8_MMA(ai, bj, At, Bt) do { __builtin_amdgcn_s_setprio(1); _Pragma("unroll") for (int m = 0; m < 4; ++m) _Pragma("unroll") for (int n = 0; n < 2; ++n) _Pragma("unroll") for (int k = 0; k < 2; ++k) \
;         acc[ai][bj][m][n] = __builtin_amdgcn_mfma_f32_16x16x32_bf16(Bt[n][k], At[m][k], acc[ai][bj][m][n], 0, 0, 0); __builtin_amdgcn_s_setprio(0); } while (0)
; #define PG8_WAIT_V(n) asm volatile("s_waitcnt vmcnt(" #n ")" ::: "memory")
; #define PG8_WAIT_L(n) asm volatile("s_waitcnt lgkmcnt(" #n ")" ::: "memory")
; #define PG8_BAR __builtin_amdgcn_s_barrier()
; #define PG8_SCHED __builtin_amdgcn_sched_barrier(0)
; template <class Epi>
; __device__ __forceinline__ void gemm_phase(LAS unsigned char* lds, const int tid, const Gemm g, const StaticOrder& S, const Epi& E) {
;     ...
;             PG8_LDA(At, 1, 1); PG8_STAGE(PG8_SB(1, 0), b3, voffB); PG8_STAGE(PG8_SB(1, 1), b3 + hstepB, voffB); PG8_STAGE(PG8_SA(1, 0), a3, voffA);
;             PG8_WAIT_V(8); PG8_WAIT_L(0); PG8_BAR; PG8_MMA(1, 0, At, B0); PG8_MMA(1, 1, At, B1); PG8_BAR; PG8_SCHED;
;         }
;         if (wr == 0) PG8_BAR;
	s_add_i32 s0, s0, s28
	v_lshl_add_u64 v[144:145], v[144:145], 0, s[36:37]
	s_mov_b32 m0, s0
	s_nop 0
	global_load_lds_dwordx4 v[144:145], off
	s_add_i32 m0, s0, 0x2000
	s_add_u32 s2, s30, 0x40080
	v_lshl_add_u64 v[144:145], v[162:163], 0, s[36:37]
	s_addc_u32 s3, s31, 0
	s_add_i32 s0, s1, s28
	global_load_lds_dwordx4 v[144:145], off
	s_mov_b32 m0, s0
	s_nop 0
	global_load_lds_dwordx4 v0, s[2:3]
	s_add_i32 m0, s0, 0x2000
	s_nop 0
	global_load_lds_dwordx4 v130, s[2:3]
	v_lshl_add_u64 v[144:145], v[164:165], 0, s[36:37]
	s_mov_b32 m0, s75
	s_nop 0
	global_load_lds_dwordx4 v[144:145], off
	v_lshl_add_u64 v[144:145], v[206:207], 0, s[36:37]
	s_mov_b32 m0, s76
	s_nop 0
	global_load_lds_dwordx4 v[144:145], off
	ds_read_b128 v[210:213], v174 offset:49152
	ds_read_b128 v[214:217], v174 offset:50176
	ds_read_b128 v[218:221], v174 offset:51200
	ds_read_b128 v[222:225], v174 offset:52224
	ds_read_b128 v[226:229], v174 offset:53248
	ds_read_b128 v[230:233], v174 offset:54272
	ds_read_b128 v[234:237], v174 offset:55296
	ds_read_b128 v[238:241], v174 offset:56320
	s_waitcnt vmcnt(8)
	s_waitcnt lgkmcnt(0)
	s_barrier
	s_setprio 1
	s_waitcnt lgkmcnt(0)
	v_mfma_f32_16x16x32_bf16 v[62:65], v[140:143], v[210:213], v[62:65]
	v_mfma_f32_16x16x32_bf16 v[58:61], v[180:183], v[210:213], v[58:61]
	v_mfma_f32_16x16x32_bf16 v[54:57], v[140:143], v[218:221], v[54:57]
	v_mfma_f32_16x16x32_bf16 v[46:49], v[180:183], v[218:221], v[46:49]
	v_mfma_f32_16x16x32_bf16 v[30:33], v[140:143], v[226:229], v[30:33]
	v_mfma_f32_16x16x32_bf16 v[26:29], v[180:183], v[226:229], v[26:29]
	v_mfma_f32_16x16x32_bf16 v[22:25], v[140:143], v[234:237], v[22:25]
	v_mfma_f32_16x16x32_bf16 v[14:17], v[180:183], v[234:237], v[14:17]
	v_mfma_f32_16x16x32_bf16 v[62:65], v[176:179], v[214:217], v[62:65]
	v_mfma_f32_16x16x32_bf16 v[58:61], v[184:187], v[214:217], v[58:61]
	v_mfma_f32_16x16x32_bf16 v[54:57], v[176:179], v[222:225], v[54:57]
	v_mfma_f32_16x16x32_bf16 v[46:49], v[184:187], v[222:225], v[46:49]
	v_mfma_f32_16x16x32_bf16 v[30:33], v[176:179], v[230:233], v[30:33]
	v_mfma_f32_16x16x32_bf16 v[26:29], v[184:187], v[230:233], v[26:29]
	v_mfma_f32_16x16x32_bf16 v[22:25], v[176:179], v[238:241], v[22:25]
	v_mfma_f32_16x16x32_bf16 v[14:17], v[184:187], v[238:241], v[14:17]
	s_setprio 0
	s_setprio 1
	v_mfma_f32_16x16x32_bf16 v[50:53], v[188:191], v[210:213], v[50:53]
	v_mfma_f32_16x16x32_bf16 v[42:45], v[196:199], v[210:213], v[42:45]
	v_mfma_f32_16x16x32_bf16 v[38:41], v[188:191], v[218:221], v[38:41]
	v_mfma_f32_16x16x32_bf16 v[34:37], v[196:199], v[218:221], v[34:37]
	v_mfma_f32_16x16x32_bf16 v[18:21], v[188:191], v[226:229], v[18:21]
	v_mfma_f32_16x16x32_bf16 v[10:13], v[196:199], v[226:229], v[10:13]
	v_mfma_f32_16x16x32_bf16 v[6:9], v[188:191], v[234:237], v[6:9]
	v_mfma_f32_16x16x32_bf16 v[2:5], v[196:199], v[234:237], v[2:5]
	v_mfma_f32_16x16x32_bf16 v[50:53], v[192:195], v[214:217], v[50:53]
	v_mfma_f32_16x16x32_bf16 v[42:45], v[200:203], v[214:217], v[42:45]
	v_mfma_f32_16x16x32_bf16 v[38:41], v[192:195], v[222:225], v[38:41]
	v_mfma_f32_16x16x32_bf16 v[34:37], v[200:203], v[222:225], v[34:37]
	v_mfma_f32_16x16x32_bf16 v[18:21], v[192:195], v[230:233], v[18:21]
	v_mfma_f32_16x16x32_bf16 v[10:13], v[200:203], v[230:233], v[10:13]
	v_mfma_f32_16x16x32_bf16 v[6:9], v[192:195], v[238:241], v[6:9]
	v_mfma_f32_16x16x32_bf16 v[2:5], v[200:203], v[238:241], v[2:5]
	s_setprio 0
	s_barrier
	s_add_i32 vcc_lo, vcc_lo, 2
	s_add_u32 s66, s66, 0x100
	s_addc_u32 s67, s67, 0
	s_add_u32 s92, s92, 0x100
	s_addc_u32 s93, s93, 0
	s_cmp_gt_u32 vcc_lo, 13
	s_cbranch_scc0 .LBB0_1284
	s_and_b64 vcc, exec, s[6:7]
	s_mov_b32 s92, 0x2c000
	s_mov_b32 s93, 0x2e000
	s_cbranch_vccz .LBB0_1287
	s_barrier

; #define PG8_STAGE(bufoff, gbase, voff) do { _Pragma("unroll") for (int _i = 0; _i < 2; ++_i) \
;         __builtin_amdgcn_global_load_lds((const unsigned*)((const char*)(gbase) + (voff)[_i]), (LAS unsigned*)(lds + (bufoff) + ldsw + _i * 8192), 16, 0, 0); } while (0)
; #define PG8_LDA(dst, b, h) do { _Pragma("unroll") for (int m = 0; m < 4; ++m) _Pragma("unroll") for (int k = 0; k < 2; ++k) dst[m][k] = *(const LAS bf16x8*)(lds + PG8_SA(b, h) + aoff + m * 2048 + k * 1024); } while (0)
; #define PG8_LDB(dst, b, h) do { _Pragma("unroll") for (int n = 0; n < 2; ++n) _Pragma("unroll") for (int k = 0; k < 2; ++k) dst[n][k] = *(const LAS bf16x8*)(lds + PG8_SB(b, h) + boff + n * 2048 + k * 1024); } while (0)
; #define PG8_MMA(ai, bj, At, Bt) do { __builtin_amdgcn_s_setprio(1); _Pragma("unroll") for (int m = 0; m < 4; ++m) _Pragma("unroll") for (int n = 0; n < 2; ++n) _Pragma("unroll") for (int k = 0; k < 2; ++k) \
;         acc[ai][bj][m][n] = __builtin_amdgcn_mfma_f32_16x16x32_bf16(Bt[n][k], At[m][k], acc[ai][bj][m][n], 0, 0, 0); __builtin_amdgcn_s_setprio(0); } while (0)
; #define PG8_WAIT_V(n) asm volatile("s_waitcnt vmcnt(" #n ")" ::: "memory")
; #define PG8_WAIT_L(n) asm volatile("s_waitcnt lgkmcnt(" #n ")" ::: "memory")
; #define PG8_BAR __builtin_amdgcn_s_barrier()
; #define PG8_SCHED __builtin_amdgcn_sched_barrier(0)
; template <class Epi>
; __device__ __forceinline__ void gemm_phase(LAS unsigned char* lds, const int tid, const Gemm g, const StaticOrder& S, const Epi& E) {
;     ...
;         for (int t = 0; t < nt; t += 2) {
;             const bool last = (t == nt - 2);
;             const char* a1 = cA + (size_t)(t + 1) * kstep;
;             const char* a2 = last ? nA : cA + (size_t)(t + 2) * kstep; const char* b2 = last ? nB : cB + (size_t)(t + 2) * kstep;
;             const char* a3 = a2 + kstep; const char* b3 = b2 + kstep;
;             PG8_LDB(B0, 0, 0); PG8_LDB(B1, 0, 1); PG8_SCHED; PG8_LDA(At, 0, 0); PG8_STAGE(PG8_SA(1, 1), a1 + hstepA, voffA);
;             PG8_WAIT_V(8); PG8_WAIT_L(0); PG8_BAR; PG8_MMA(0, 0, At, B0); PG8_MMA(0, 1, At, B1); PG8_BAR; PG8_SCHED;
;             PG8_LDA(At, 0, 1); PG8_STAGE(PG8_SB(0, 0), b2, voffB); PG8_STAGE(PG8_SB(0, 1), b2 + hstepB, voffB); PG8_STAGE(PG8_SA(0, 0), a2, voffA);
;             PG8_WAIT_V(8); PG8_WAIT_L(0); PG8_BAR; PG8_MMA(1, 0, At, B0); PG8_MMA(1, 1, At, B1); PG8_BAR; PG8_SCHED;
.LBB0_1333:
	s_add_u32 s0, s66, 0xfff80080
	s_addc_u32 s1, s67, -1
	s_add_i32 s2, 0, 0x10000
	s_cmp_eq_u32 vcc_lo, 12
	s_cselect_b32 s69, s11, s1
	s_cselect_b32 s68, s88, s0
	s_cselect_b32 s31, s9, s93
	s_cselect_b32 s30, s89, s92
	s_add_i32 s0, 0, 0x14000
	v_add_u32_e32 v142, s2, v189
	v_add_u32_e32 v162, s0, v189
	ds_read_b128 v[130:133], v142
	ds_read_b128 v[134:137], v142 offset:1024
	ds_read_b128 v[138:141], v142 offset:2048
	ds_read_b128 v[142:145], v142 offset:3072
	ds_read_b128 v[158:161], v162
	ds_read_b128 v[192:195], v162 offset:1024
	ds_read_b128 v[196:199], v162 offset:2048
	ds_read_b128 v[200:203], v162 offset:3072
	s_add_i32 m0, s71, 0xc000
	s_nop 0
	global_load_lds_dwordx4 v154, s[66:67]
	s_add_i32 m0, s71, 0xe000
	s_nop 0
	global_load_lds_dwordx4 v156, s[66:67]
	ds_read_b128 v[210:213], v191
	ds_read_b128 v[214:217], v191 offset:1024
	ds_read_b128 v[218:221], v191 offset:2048
	ds_read_b128 v[222:225], v191 offset:3072
	ds_read_b128 v[226:229], v191 offset:4096
	ds_read_b128 v[230:233], v191 offset:5120
	ds_read_b128 v[234:237], v191 offset:6144
	ds_read_b128 v[238:241], v191 offset:7168
	s_waitcnt vmcnt(8)
	s_waitcnt lgkmcnt(0)
	s_barrier
	s_setprio 1
	s_waitcnt lgkmcnt(0)
	v_mfma_f32_16x16x32_bf16 v[126:129], v[130:133], v[210:213], v[126:129]
	v_mfma_f32_16x16x32_bf16 v[122:125], v[138:141], v[210:213], v[122:125]
	v_mfma_f32_16x16x32_bf16 v[110:113], v[130:133], v[218:221], v[110:113]
	v_mfma_f32_16x16x32_bf16 v[106:109], v[138:141], v[218:221], v[106:109]
	v_mfma_f32_16x16x32_bf16 v[94:97], v[130:133], v[226:229], v[94:97]
	v_mfma_f32_16x16x32_bf16 v[90:93], v[138:141], v[226:229], v[90:93]
	v_mfma_f32_16x16x32_bf16 v[78:81], v[130:133], v[234:237], v[78:81]
	v_mfma_f32_16x16x32_bf16 v[74:77], v[138:141], v[234:237], v[74:77]
	v_mfma_f32_16x16x32_bf16 v[126:129], v[134:137], v[214:217], v[126:129]
	v_mfma_f32_16x16x32_bf16 v[122:125], v[142:145], v[214:217], v[122:125]
	v_mfma_f32_16x16x32_bf16 v[110:113], v[134:137], v[222:225], v[110:113]
	v_mfma_f32_16x16x32_bf16 v[106:109], v[142:145], v[222:225], v[106:109]
	v_mfma_f32_16x16x32_bf16 v[94:97], v[134:137], v[230:233], v[94:97]
	v_mfma_f32_16x16x32_bf16 v[90:93], v[142:145], v[230:233], v[90:93]
	v_mfma_f32_16x16x32_bf16 v[78:81], v[134:137], v[238:241], v[78:81]
	v_mfma_f32_16x16x32_bf16 v[74:77], v[142:145], v[238:241], v[74:77]
	s_setprio 0
	s_setprio 1
	v_mfma_f32_16x16x32_bf16 v[118:121], v[158:161], v[210:213], v[118:121]
	v_mfma_f32_16x16x32_bf16 v[114:117], v[196:199], v[210:213], v[114:117]
	v_mfma_f32_16x16x32_bf16 v[102:105], v[158:161], v[218:221], v[102:105]
	v_mfma_f32_16x16x32_bf16 v[98:101], v[196:199], v[218:221], v[98:101]
	v_mfma_f32_16x16x32_bf16 v[86:89], v[158:161], v[226:229], v[86:89]
	v_mfma_f32_16x16x32_bf16 v[82:85], v[196:199], v[226:229], v[82:85]
	v_mfma_f32_16x16x32_bf16 v[70:73], v[158:161], v[234:237], v[70:73]
	v_mfma_f32_16x16x32_bf16 v[66:69], v[196:199], v[234:237], v[66:69]
	v_mfma_f32_16x16x32_bf16 v[118:121], v[192:195], v[214:217], v[118:121]
	v_mfma_f32_16x16x32_bf16 v[114:117], v[200:203], v[214:217], v[114:117]
	v_mfma_f32_16x16x32_bf16 v[102:105], v[192:195], v[222:225], v[102:105]
	v_mfma_f32_16x16x32_bf16 v[98:101], v[200:203], v[222:225], v[98:101]
	v_mfma_f32_16x16x32_bf16 v[86:89], v[192:195], v[230:233], v[86:89]
	v_mfma_f32_16x16x32_bf16 v[82:85], v[200:203], v[230:233], v[82:85]
	v_mfma_f32_16x16x32_bf16 v[70:73], v[192:195], v[238:241], v[70:73]
	v_mfma_f32_16x16x32_bf16 v[66:69], v[200:203], v[238:241], v[66:69]
	s_setprio 0
	s_barrier
	s_add_i32 s1, s2, s28
	v_lshl_add_u64 v[162:163], s[30:31], 0, v[0:1]
	s_mov_b32 m0, s1
	s_nop 0
	global_load_lds_dwordx4 v[162:163], off
	s_add_i32 m0, s1, 0x2000
	s_add_u32 s2, s30, 0x40000
	v_lshl_add_u64 v[164:165], s[30:31], 0, v[148:149]
	s_addc_u32 s3, s31, 0
	s_add_i32 s0, s0, s28
	global_load_lds_dwordx4 v[164:165], off
	s_mov_b32 m0, s0
	v_lshl_add_u64 v[206:207], s[68:69], 0, v[150:151]
	global_load_lds_dwordx4 v0, s[2:3]
	s_add_i32 m0, s0, 0x2000
	s_nop 0
	global_load_lds_dwordx4 v148, s[2:3]
	v_lshl_add_u64 v[170:171], s[68:69], 0, v[152:153]
	s_mov_b32 m0, s71
	s_nop 0
	global_load_lds_dwordx4 v[170:171], off
	s_mov_b32 m0, s72
	s_nop 0
	global_load_lds_dwordx4 v[206:207], off
	ds_read_b128 v[210:213], v191 offset:16384
	ds_read_b128 v[214:217], v191 offset:17408
	ds_read_b128 v[218:221], v191 offset:18432
	ds_read_b128 v[222:225], v191 offset:19456
	ds_read_b128 v[226:229], v191 offset:20480
	ds_read_b128 v[230:233], v191 offset:21504
	ds_read_b128 v[234:237], v191 offset:22528
	ds_read_b128 v[238:241], v191 offset:23552
	s_waitcnt vmcnt(8)
	s_waitcnt lgkmcnt(0)
	s_barrier
; #define PG8_STAGE(bufoff, gbase, voff) do { _Pragma("unroll") for (int _i = 0; _i < 2; ++_i) \
;         __builtin_amdgcn_global_load_lds((const unsigned*)((const char*)(gbase) + (voff)[_i]), (LAS unsigned*)(lds + (bufoff) + ldsw + _i * 8192), 16, 0, 0); } while (0)
; #define PG8_LDA(dst, b, h) do { _Pragma("unroll") for (int m = 0; m < 4; ++m) _Pragma("unroll") for (int k = 0; k < 2; ++k) dst[m][k] = *(const LAS bf16x8*)(lds + PG8_SA(b, h) + aoff + m * 2048 + k * 1024); } while (0)
; #define PG8_LDB(dst, b, h) do { _Pragma("unroll") for (int n = 0; n < 2; ++n) _Pragma("unroll") for (int k = 0; k < 2; ++k) dst[n][k] = *(const LAS bf16x8*)(lds + PG8_SB(b, h) + boff + n * 2048 + k * 1024); } while (0)
; #define PG8_MMA(ai, bj, At, Bt) do { __builtin_amdgcn_s_setprio(1); _Pragma("unroll") for (int m = 0; m < 4; ++m) _Pragma("unroll") for (int n = 0; n < 2; ++n) _Pragma("unroll") for (int k = 0; k < 2; ++k) \
;         acc[ai][bj][m][n] = __builtin_amdgcn_mfma_f32_16x16x32_bf16(Bt[n][k], At[m][k], acc[ai][bj][m][n], 0, 0, 0); __builtin_amdgcn_s_setprio(0); } while (0)
; #define PG8_WAIT_V(n) asm volatile("s_waitcnt vmcnt(" #n ")" ::: "memory")
; #define PG8_WAIT_L(n) asm volatile("s_waitcnt lgkmcnt(" #n ")" ::: "memory")
; #define PG8_BAR __builtin_amdgcn_s_barrier()
; #define PG8_SCHED __builtin_amdgcn_sched_barrier(0)
; template <class Epi>
; __device__ __forceinline__ void gemm_phase(LAS unsigned char* lds, const int tid, const Gemm g, const StaticOrder& S, const Epi& E) {
;     ...
;             PG8_WAIT_V(8); PG8_WAIT_L(0); PG8_BAR; PG8_MMA(1, 0, At, B0); PG8_MMA(1, 1, At, B1); PG8_BAR; PG8_SCHED;
;             PG8_LDB(B0, 1, 0); PG8_LDB(B1, 1, 1); PG8_SCHED; PG8_LDA(At, 1, 0); PG8_STAGE(PG8_SA(0, 1), a2 + hstepA, voffA);
;             PG8_WAIT_V(8); PG8_WAIT_L(0); PG8_BAR; PG8_MMA(0, 0, At, B0); PG8_MMA(0, 1, At, B1); PG8_BAR; PG8_SCHED;
	s_setprio 1
	s_waitcnt lgkmcnt(0)
	v_mfma_f32_16x16x32_bf16 v[62:65], v[130:133], v[210:213], v[62:65]
	v_mfma_f32_16x16x32_bf16 v[58:61], v[138:141], v[210:213], v[58:61]
	v_mfma_f32_16x16x32_bf16 v[46:49], v[130:133], v[218:221], v[46:49]
	v_mfma_f32_16x16x32_bf16 v[42:45], v[138:141], v[218:221], v[42:45]
	v_mfma_f32_16x16x32_bf16 v[30:33], v[130:133], v[226:229], v[30:33]
	v_mfma_f32_16x16x32_bf16 v[26:29], v[138:141], v[226:229], v[26:29]
	v_mfma_f32_16x16x32_bf16 v[14:17], v[130:133], v[234:237], v[14:17]
	v_mfma_f32_16x16x32_bf16 v[10:13], v[138:141], v[234:237], v[10:13]
	v_mfma_f32_16x16x32_bf16 v[62:65], v[134:137], v[214:217], v[62:65]
	v_mfma_f32_16x16x32_bf16 v[58:61], v[142:145], v[214:217], v[58:61]
	v_mfma_f32_16x16x32_bf16 v[46:49], v[134:137], v[222:225], v[46:49]
	v_mfma_f32_16x16x32_bf16 v[42:45], v[142:145], v[222:225], v[42:45]
	v_mfma_f32_16x16x32_bf16 v[30:33], v[134:137], v[230:233], v[30:33]
	v_mfma_f32_16x16x32_bf16 v[26:29], v[142:145], v[230:233], v[26:29]
	v_mfma_f32_16x16x32_bf16 v[14:17], v[134:137], v[238:241], v[14:17]
	v_mfma_f32_16x16x32_bf16 v[10:13], v[142:145], v[238:241], v[10:13]
	s_setprio 0
	s_setprio 1
	v_mfma_f32_16x16x32_bf16 v[54:57], v[158:161], v[210:213], v[54:57]
	v_mfma_f32_16x16x32_bf16 v[50:53], v[196:199], v[210:213], v[50:53]
	v_mfma_f32_16x16x32_bf16 v[38:41], v[158:161], v[218:221], v[38:41]
	v_mfma_f32_16x16x32_bf16 v[34:37], v[196:199], v[218:221], v[34:37]
	v_mfma_f32_16x16x32_bf16 v[22:25], v[158:161], v[226:229], v[22:25]
	v_mfma_f32_16x16x32_bf16 v[18:21], v[196:199], v[226:229], v[18:21]
	v_mfma_f32_16x16x32_bf16 v[6:9], v[158:161], v[234:237], v[6:9]
	v_mfma_f32_16x16x32_bf16 v[2:5], v[196:199], v[234:237], v[2:5]
	v_mfma_f32_16x16x32_bf16 v[54:57], v[192:195], v[214:217], v[54:57]
	v_mfma_f32_16x16x32_bf16 v[50:53], v[200:203], v[214:217], v[50:53]
	v_mfma_f32_16x16x32_bf16 v[38:41], v[192:195], v[222:225], v[38:41]
	v_mfma_f32_16x16x32_bf16 v[34:37], v[200:203], v[222:225], v[34:37]
	v_mfma_f32_16x16x32_bf16 v[22:25], v[192:195], v[230:233], v[22:25]
	v_mfma_f32_16x16x32_bf16 v[18:21], v[200:203], v[230:233], v[18:21]
	v_mfma_f32_16x16x32_bf16 v[6:9], v[192:195], v[238:241], v[6:9]
	v_mfma_f32_16x16x32_bf16 v[2:5], v[200:203], v[238:241], v[2:5]
	s_setprio 0
	s_barrier
	s_add_i32 s0, 0, 0x18000
	s_add_i32 s1, 0, 0x1c000
	v_add_u32_e32 v142, s0, v189
	v_add_u32_e32 v200, s1, v189
	ds_read_b128 v[130:133], v142
	ds_read_b128 v[134:137], v142 offset:1024
	ds_read_b128 v[138:141], v142 offset:2048
	ds_read_b128 v[142:145], v142 offset:3072
	ds_read_b128 v[158:161], v200
	ds_read_b128 v[192:195], v200 offset:1024
	ds_read_b128 v[196:199], v200 offset:2048
	ds_read_b128 v[200:203], v200 offset:3072
	s_add_u32 s2, s68, 0x80000
	s_addc_u32 s3, s69, 0
	s_mov_b32 m0, s73
	s_nop 0
	global_load_lds_dwordx4 v152, s[2:3]
	s_mov_b32 m0, s74
	s_nop 0
	global_load_lds_dwordx4 v150, s[2:3]
	ds_read_b128 v[210:213], v191 offset:32768
	ds_read_b128 v[214:217], v191 offset:33792
	ds_read_b128 v[218:221], v191 offset:34816
	ds_read_b128 v[222:225], v191 offset:35840
	ds_read_b128 v[226:229], v191 offset:36864
	ds_read_b128 v[230:233], v191 offset:37888
	ds_read_b128 v[234:237], v191 offset:38912
	ds_read_b128 v[238:241], v191 offset:39936
	s_waitcnt vmcnt(8)
	s_waitcnt lgkmcnt(0)
	s_barrier
	s_setprio 1
	s_waitcnt lgkmcnt(0)
	v_mfma_f32_16x16x32_bf16 v[126:129], v[130:133], v[210:213], v[126:129]
	v_mfma_f32_16x16x32_bf16 v[122:125], v[138:141], v[210:213], v[122:125]
	v_mfma_f32_16x16x32_bf16 v[110:113], v[130:133], v[218:221], v[110:113]
	v_mfma_f32_16x16x32_bf16 v[106:109], v[138:141], v[218:221], v[106:109]
	v_mfma_f32_16x16x32_bf16 v[94:97], v[130:133], v[226:229], v[94:97]
	v_mfma_f32_16x16x32_bf16 v[90:93], v[138:141], v[226:229], v[90:93]
	v_mfma_f32_16x16x32_bf16 v[78:81], v[130:133], v[234:237], v[78:81]
	v_mfma_f32_16x16x32_bf16 v[74:77], v[138:141], v[234:237], v[74:77]
	v_mfma_f32_16x16x32_bf16 v[126:129], v[134:137], v[214:217], v[126:129]
	v_mfma_f32_16x16x32_bf16 v[122:125], v[142:145], v[214:217], v[122:125]
	v_mfma_f32_16x16x32_bf16 v[110:113], v[134:137], v[222:225], v[110:113]
	v_mfma_f32_16x16x32_bf16 v[106:109], v[142:145], v[222:225], v[106:109]
	v_mfma_f32_16x16x32_bf16 v[94:97], v[134:137], v[230:233], v[94:97]
	v_mfma_f32_16x16x32_bf16 v[90:93], v[142:145], v[230:233], v[90:93]
	v_mfma_f32_16x16x32_bf16 v[78:81], v[134:137], v[238:241], v[78:81]
	v_mfma_f32_16x16x32_bf16 v[74:77], v[142:145], v[238:241], v[74:77]
	s_setprio 0
	s_setprio 1
	v_mfma_f32_16x16x32_bf16 v[118:121], v[158:161], v[210:213], v[118:121]
	v_mfma_f32_16x16x32_bf16 v[114:117], v[196:199], v[210:213], v[114:117]
	v_mfma_f32_16x16x32_bf16 v[102:105], v[158:161], v[218:221], v[102:105]
	v_mfma_f32_16x16x32_bf16 v[98:101], v[196:199], v[218:221], v[98:101]
	v_mfma_f32_16x16x32_bf16 v[86:89], v[158:161], v[226:229], v[86:89]
	v_mfma_f32_16x16x32_bf16 v[82:85], v[196:199], v[226:229], v[82:85]
	v_mfma_f32_16x16x32_bf16 v[70:73], v[158:161], v[234:237], v[70:73]
	v_mfma_f32_16x16x32_bf16 v[66:69], v[196:199], v[234:237], v[66:69]
	v_mfma_f32_16x16x32_bf16 v[118:121], v[192:195], v[214:217], v[118:121]
	v_mfma_f32_16x16x32_bf16 v[114:117], v[200:203], v[214:217], v[114:117]
	v_mfma_f32_16x16x32_bf16 v[102:105], v[192:195], v[222:225], v[102:105]
	v_mfma_f32_16x16x32_bf16 v[98:101], v[200:203], v[222:225], v[98:101]
	v_mfma_f32_16x16x32_bf16 v[86:89], v[192:195], v[230:233], v[86:89]
	v_mfma_f32_16x16x32_bf16 v[82:85], v[200:203], v[230:233], v[82:85]
	v_mfma_f32_16x16x32_bf16 v[70:73], v[192:195], v[238:241], v[70:73]
	v_mfma_f32_16x16x32_bf16 v[66:69], v[200:203], v[238:241], v[66:69]
	s_setprio 0
	s_barrier
; #define PG8_STAGE(bufoff, gbase, voff) do { _Pragma("unroll") for (int _i = 0; _i < 2; ++_i) \
;         __builtin_amdgcn_global_load_lds((const unsigned*)((const char*)(gbase) + (voff)[_i]), (LAS unsigned*)(lds + (bufoff) + ldsw + _i * 8192), 16, 0, 0); } while (0)
; #define PG8_LDA(dst, b, h) do { _Pragma("unroll") for (int m = 0; m < 4; ++m) _Pragma("unroll") for (int k = 0; k < 2; ++k) dst[m][k] = *(const LAS bf16x8*)(lds + PG8_SA(b, h) + aoff + m * 2048 + k * 1024); } while (0)
; #define PG8_MMA(ai, bj, At, Bt) do { __builtin_amdgcn_s_setprio(1); _Pragma("unroll") for (int m = 0; m < 4; ++m) _Pragma("unroll") for (int n = 0; n < 2; ++n) _Pragma("unroll") for (int k = 0; k < 2; ++k) \
;         acc[ai][bj][m][n] = __builtin_amdgcn_mfma_f32_16x16x32_bf16(Bt[n][k], At[m][k], acc[ai][bj][m][n], 0, 0, 0); __builtin_amdgcn_s_setprio(0); } while (0)
; #define PG8_WAIT_V(n) asm volatile("s_waitcnt vmcnt(" #n ")" ::: "memory")
; #define PG8_WAIT_L(n) asm volatile("s_waitcnt lgkmcnt(" #n ")" ::: "memory")
; #define PG8_BAR __builtin_amdgcn_s_barrier()
; #define PG8_SCHED __builtin_amdgcn_sched_barrier(0)
; template <class Epi>
; __device__ __forceinline__ void gemm_phase(LAS unsigned char* lds, const int tid, const Gemm g, const StaticOrder& S, const Epi& E) {
;     ...
;             PG8_LDA(At, 1, 1); PG8_STAGE(PG8_SB(1, 0), b3, voffB); PG8_STAGE(PG8_SB(1, 1), b3 + hstepB, voffB); PG8_STAGE(PG8_SA(1, 0), a3, voffA);
;             PG8_WAIT_V(8); PG8_WAIT_L(0); PG8_BAR; PG8_MMA(1, 0, At, B0); PG8_MMA(1, 1, At, B1); PG8_BAR; PG8_SCHED;
;         }
;         if (wr == 0) PG8_BAR;
	s_add_i32 s0, s0, s28
	v_lshl_add_u64 v[162:163], v[162:163], 0, s[36:37]
	s_mov_b32 m0, s0
	s_nop 0
	global_load_lds_dwordx4 v[162:163], off
	s_add_i32 m0, s0, 0x2000
	s_add_u32 s2, s30, 0x40080
	v_lshl_add_u64 v[162:163], v[164:165], 0, s[36:37]
	s_addc_u32 s3, s31, 0
	s_add_i32 s0, s1, s28
	global_load_lds_dwordx4 v[162:163], off
	s_mov_b32 m0, s0
	s_nop 0
	global_load_lds_dwordx4 v0, s[2:3]
	s_add_i32 m0, s0, 0x2000
	s_nop 0
	global_load_lds_dwordx4 v148, s[2:3]
	v_lshl_add_u64 v[162:163], v[170:171], 0, s[36:37]
	s_mov_b32 m0, s75
	s_nop 0
	global_load_lds_dwordx4 v[162:163], off
	v_lshl_add_u64 v[162:163], v[206:207], 0, s[36:37]
	s_mov_b32 m0, s76
	s_nop 0
	global_load_lds_dwordx4 v[162:163], off
	ds_read_b128 v[210:213], v191 offset:49152
	ds_read_b128 v[214:217], v191 offset:50176
	ds_read_b128 v[218:221], v191 offset:51200
	ds_read_b128 v[222:225], v191 offset:52224
	ds_read_b128 v[226:229], v191 offset:53248
	ds_read_b128 v[230:233], v191 offset:54272
	ds_read_b128 v[234:237], v191 offset:55296
	ds_read_b128 v[238:241], v191 offset:56320
	s_waitcnt vmcnt(8)
	s_waitcnt lgkmcnt(0)
	s_barrier
	s_setprio 1
	s_waitcnt lgkmcnt(0)
	v_mfma_f32_16x16x32_bf16 v[62:65], v[130:133], v[210:213], v[62:65]
	v_mfma_f32_16x16x32_bf16 v[58:61], v[138:141], v[210:213], v[58:61]
	v_mfma_f32_16x16x32_bf16 v[46:49], v[130:133], v[218:221], v[46:49]
	v_mfma_f32_16x16x32_bf16 v[42:45], v[138:141], v[218:221], v[42:45]
	v_mfma_f32_16x16x32_bf16 v[30:33], v[130:133], v[226:229], v[30:33]
	v_mfma_f32_16x16x32_bf16 v[26:29], v[138:141], v[226:229], v[26:29]
	v_mfma_f32_16x16x32_bf16 v[14:17], v[130:133], v[234:237], v[14:17]
	v_mfma_f32_16x16x32_bf16 v[10:13], v[138:141], v[234:237], v[10:13]
	v_mfma_f32_16x16x32_bf16 v[62:65], v[134:137], v[214:217], v[62:65]
	v_mfma_f32_16x16x32_bf16 v[58:61], v[142:145], v[214:217], v[58:61]
	v_mfma_f32_16x16x32_bf16 v[46:49], v[134:137], v[222:225], v[46:49]
	v_mfma_f32_16x16x32_bf16 v[42:45], v[142:145], v[222:225], v[42:45]
	v_mfma_f32_16x16x32_bf16 v[30:33], v[134:137], v[230:233], v[30:33]
	v_mfma_f32_16x16x32_bf16 v[26:29], v[142:145], v[230:233], v[26:29]
	v_mfma_f32_16x16x32_bf16 v[14:17], v[134:137], v[238:241], v[14:17]
	v_mfma_f32_16x16x32_bf16 v[10:13], v[142:145], v[238:241], v[10:13]
	s_setprio 0
	s_setprio 1
	v_mfma_f32_16x16x32_bf16 v[54:57], v[158:161], v[210:213], v[54:57]
	v_mfma_f32_16x16x32_bf16 v[50:53], v[196:199], v[210:213], v[50:53]
	v_mfma_f32_16x16x32_bf16 v[38:41], v[158:161], v[218:221], v[38:41]
	v_mfma_f32_16x16x32_bf16 v[34:37], v[196:199], v[218:221], v[34:37]
	v_mfma_f32_16x16x32_bf16 v[22:25], v[158:161], v[226:229], v[22:25]
	v_mfma_f32_16x16x32_bf16 v[18:21], v[196:199], v[226:229], v[18:21]
	v_mfma_f32_16x16x32_bf16 v[6:9], v[158:161], v[234:237], v[6:9]
	v_mfma_f32_16x16x32_bf16 v[2:5], v[196:199], v[234:237], v[2:5]
	v_mfma_f32_16x16x32_bf16 v[54:57], v[192:195], v[214:217], v[54:57]
	v_mfma_f32_16x16x32_bf16 v[50:53], v[200:203], v[214:217], v[50:53]
	v_mfma_f32_16x16x32_bf16 v[38:41], v[192:195], v[222:225], v[38:41]
	v_mfma_f32_16x16x32_bf16 v[34:37], v[200:203], v[222:225], v[34:37]
	v_mfma_f32_16x16x32_bf16 v[22:25], v[192:195], v[230:233], v[22:25]
	v_mfma_f32_16x16x32_bf16 v[18:21], v[200:203], v[230:233], v[18:21]
	v_mfma_f32_16x16x32_bf16 v[6:9], v[192:195], v[238:241], v[6:9]
	v_mfma_f32_16x16x32_bf16 v[2:5], v[200:203], v[238:241], v[2:5]
	s_setprio 0
	s_barrier
	s_add_i32 vcc_lo, vcc_lo, 2
	s_add_u32 s66, s66, 0x100
	s_addc_u32 s67, s67, 0
	s_add_u32 s92, s92, 0x100
	s_addc_u32 s93, s93, 0
	s_cmp_gt_u32 vcc_lo, 13
	s_cbranch_scc0 .LBB0_1333
	s_and_b64 vcc, exec, s[6:7]
	s_cbranch_vccz .LBB0_1336
	s_barrier

; #define PG8_STAGE(bufoff, gbase, voff) do { _Pragma("unroll") for (int _i = 0; _i < 2; ++_i) \
;         __builtin_amdgcn_global_load_lds((const unsigned*)((const char*)(gbase) + (voff)[_i]), (LAS unsigned*)(lds + (bufoff) + ldsw + _i * 8192), 16, 0, 0); } while (0)
; #define PG8_LDA(dst, b, h) do { _Pragma("unroll") for (int m = 0; m < 4; ++m) _Pragma("unroll") for (int k = 0; k < 2; ++k) dst[m][k] = *(const LAS bf16x8*)(lds + PG8_SA(b, h) + aoff + m * 2048 + k * 1024); } while (0)
; #define PG8_LDB(dst, b, h) do { _Pragma("unroll") for (int n = 0; n < 2; ++n) _Pragma("unroll") for (int k = 0; k < 2; ++k) dst[n][k] = *(const LAS bf16x8*)(lds + PG8_SB(b, h) + boff + n * 2048 + k * 1024); } while (0)
; #define PG8_MMA(ai, bj, At, Bt) do { __builtin_amdgcn_s_setprio(1); _Pragma("unroll") for (int m = 0; m < 4; ++m) _Pragma("unroll") for (int n = 0; n < 2; ++n) _Pragma("unroll") for (int k = 0; k < 2; ++k) \
;         acc[ai][bj][m][n] = __builtin_amdgcn_mfma_f32_16x16x32_bf16(Bt[n][k], At[m][k], acc[ai][bj][m][n], 0, 0, 0); __builtin_amdgcn_s_setprio(0); } while (0)
; #define PG8_WAIT_V(n) asm volatile("s_waitcnt vmcnt(" #n ")" ::: "memory")
; #define PG8_WAIT_L(n) asm volatile("s_waitcnt lgkmcnt(" #n ")" ::: "memory")
; #define PG8_BAR __builtin_amdgcn_s_barrier()
; #define PG8_SCHED __builtin_amdgcn_sched_barrier(0)
; template <class Epi>
; __device__ __forceinline__ void gemm_phase(LAS unsigned char* lds, const int tid, const Gemm g, const StaticOrder& S, const Epi& E) {
;     ...
;         for (int t = 0; t < nt; t += 2) {
;             const bool last = (t == nt - 2);
;             const char* a1 = cA + (size_t)(t + 1) * kstep;
;             const char* a2 = last ? nA : cA + (size_t)(t + 2) * kstep; const char* b2 = last ? nB : cB + (size_t)(t + 2) * kstep;
;             const char* a3 = a2 + kstep; const char* b3 = b2 + kstep;
;             PG8_LDB(B0, 0, 0); PG8_LDB(B1, 0, 1); PG8_SCHED; PG8_LDA(At, 0, 0); PG8_STAGE(PG8_SA(1, 1), a1 + hstepA, voffA);
;             PG8_WAIT_V(8); PG8_WAIT_L(0); PG8_BAR; PG8_MMA(0, 0, At, B0); PG8_MMA(0, 1, At, B1); PG8_BAR; PG8_SCHED;
;             PG8_LDA(At, 0, 1); PG8_STAGE(PG8_SB(0, 0), b2, voffB); PG8_STAGE(PG8_SB(0, 1), b2 + hstepB, voffB); PG8_STAGE(PG8_SA(0, 0), a2, voffA);
;             PG8_WAIT_V(8); PG8_WAIT_L(0); PG8_BAR; PG8_MMA(1, 0, At, B0); PG8_MMA(1, 1, At, B1); PG8_BAR; PG8_SCHED;
.LBB0_1487:
	s_add_u32 s27, s68, 0xfffc0080
	s_addc_u32 s30, s69, -1
	s_add_i32 s62, 0, 0x10000
	s_cmp_eq_u32 s26, 12
	s_cselect_b32 vcc_hi, s28, s30
	s_cselect_b32 vcc_lo, s71, s27
	s_cselect_b32 s31, s5, s83
	s_cselect_b32 s30, s73, s75
	s_add_i32 s27, 0, 0x14000
	v_add_u32_e32 v142, s62, v216
	v_add_u32_e32 v158, s27, v216
	ds_read_b128 v[130:133], v142
	ds_read_b128 v[134:137], v142 offset:1024
	ds_read_b128 v[138:141], v142 offset:2048
	ds_read_b128 v[142:145], v142 offset:3072
	ds_read_b128 v[146:149], v158
	ds_read_b128 v[150:153], v158 offset:1024
	ds_read_b128 v[154:157], v158 offset:2048
	ds_read_b128 v[158:161], v158 offset:3072
	s_add_i32 m0, s1, 0xc000
	s_nop 0
	global_load_lds_dwordx4 v176, s[68:69]
	s_add_i32 m0, s1, 0xe000
	s_nop 0
	global_load_lds_dwordx4 v178, s[68:69]
	ds_read_b128 v[180:183], v218
	ds_read_b128 v[184:187], v218 offset:1024
	ds_read_b128 v[220:223], v218 offset:2048
	ds_read_b128 v[224:227], v218 offset:3072
	ds_read_b128 v[228:231], v218 offset:4096
	ds_read_b128 v[232:235], v218 offset:5120
	ds_read_b128 v[236:239], v218 offset:6144
	ds_read_b128 v[240:243], v218 offset:7168
	s_waitcnt vmcnt(8)
	s_waitcnt lgkmcnt(0)
	s_barrier
	s_setprio 1
	s_waitcnt lgkmcnt(0)
	v_mfma_f32_16x16x32_bf16 v[126:129], v[130:133], v[180:183], v[126:129]
	v_mfma_f32_16x16x32_bf16 v[122:125], v[138:141], v[180:183], v[122:125]
	v_mfma_f32_16x16x32_bf16 v[110:113], v[130:133], v[220:223], v[110:113]
	v_mfma_f32_16x16x32_bf16 v[106:109], v[138:141], v[220:223], v[106:109]
	v_mfma_f32_16x16x32_bf16 v[94:97], v[130:133], v[228:231], v[94:97]
	v_mfma_f32_16x16x32_bf16 v[90:93], v[138:141], v[228:231], v[90:93]
	v_mfma_f32_16x16x32_bf16 v[78:81], v[130:133], v[236:239], v[78:81]
	v_mfma_f32_16x16x32_bf16 v[74:77], v[138:141], v[236:239], v[74:77]
	v_mfma_f32_16x16x32_bf16 v[126:129], v[134:137], v[184:187], v[126:129]
	v_mfma_f32_16x16x32_bf16 v[122:125], v[142:145], v[184:187], v[122:125]
	v_mfma_f32_16x16x32_bf16 v[110:113], v[134:137], v[224:227], v[110:113]
	v_mfma_f32_16x16x32_bf16 v[106:109], v[142:145], v[224:227], v[106:109]
	v_mfma_f32_16x16x32_bf16 v[94:97], v[134:137], v[232:235], v[94:97]
	v_mfma_f32_16x16x32_bf16 v[90:93], v[142:145], v[232:235], v[90:93]
	v_mfma_f32_16x16x32_bf16 v[78:81], v[134:137], v[240:243], v[78:81]
	v_mfma_f32_16x16x32_bf16 v[74:77], v[142:145], v[240:243], v[74:77]
	s_setprio 0
	s_setprio 1
	v_mfma_f32_16x16x32_bf16 v[118:121], v[146:149], v[180:183], v[118:121]
	v_mfma_f32_16x16x32_bf16 v[114:117], v[154:157], v[180:183], v[114:117]
	v_mfma_f32_16x16x32_bf16 v[102:105], v[146:149], v[220:223], v[102:105]
	v_mfma_f32_16x16x32_bf16 v[98:101], v[154:157], v[220:223], v[98:101]
	v_mfma_f32_16x16x32_bf16 v[86:89], v[146:149], v[228:231], v[86:89]
	v_mfma_f32_16x16x32_bf16 v[82:85], v[154:157], v[228:231], v[82:85]
	v_mfma_f32_16x16x32_bf16 v[70:73], v[146:149], v[236:239], v[70:73]
	v_mfma_f32_16x16x32_bf16 v[66:69], v[154:157], v[236:239], v[66:69]
	v_mfma_f32_16x16x32_bf16 v[118:121], v[150:153], v[184:187], v[118:121]
	v_mfma_f32_16x16x32_bf16 v[114:117], v[158:161], v[184:187], v[114:117]
	v_mfma_f32_16x16x32_bf16 v[102:105], v[150:153], v[224:227], v[102:105]
	v_mfma_f32_16x16x32_bf16 v[98:101], v[158:161], v[224:227], v[98:101]
	v_mfma_f32_16x16x32_bf16 v[86:89], v[150:153], v[232:235], v[86:89]
	v_mfma_f32_16x16x32_bf16 v[82:85], v[158:161], v[232:235], v[82:85]
	v_mfma_f32_16x16x32_bf16 v[70:73], v[150:153], v[240:243], v[70:73]
	v_mfma_f32_16x16x32_bf16 v[66:69], v[158:161], v[240:243], v[66:69]
	s_setprio 0
	s_barrier
	s_add_i32 s62, s62, s0
	v_lshl_add_u64 v[162:163], s[30:31], 0, v[0:1]
	s_mov_b32 m0, s62
	s_nop 0
	global_load_lds_dwordx4 v[162:163], off
	s_add_i32 m0, s62, 0x2000
	s_add_u32 s62, s30, 0x40000
	v_lshl_add_u64 v[164:165], s[30:31], 0, v[170:171]
	s_addc_u32 s63, s31, 0
	s_add_i32 s27, s27, s0
	global_load_lds_dwordx4 v[164:165], off
	s_mov_b32 m0, s27
	v_lshl_add_u64 v[244:245], vcc, 0, v[174:175]
	global_load_lds_dwordx4 v0, s[62:63]
	s_add_i32 m0, s27, 0x2000
	s_nop 0
	global_load_lds_dwordx4 v170, s[62:63]
	v_lshl_add_u64 v[206:207], vcc, 0, v[172:173]
	s_mov_b32 m0, s1
	s_nop 0
	global_load_lds_dwordx4 v[206:207], off
	s_mov_b32 m0, s2
	s_nop 0
	global_load_lds_dwordx4 v[244:245], off
	ds_read_b128 v[180:183], v218 offset:16384
	ds_read_b128 v[184:187], v218 offset:17408
	ds_read_b128 v[220:223], v218 offset:18432
	ds_read_b128 v[224:227], v218 offset:19456
	ds_read_b128 v[228:231], v218 offset:20480
	ds_read_b128 v[232:235], v218 offset:21504
	ds_read_b128 v[236:239], v218 offset:22528
	ds_read_b128 v[240:243], v218 offset:23552
	s_waitcnt vmcnt(8)
	s_waitcnt lgkmcnt(0)
	s_barrier
; #define PG8_STAGE(bufoff, gbase, voff) do { _Pragma("unroll") for (int _i = 0; _i < 2; ++_i) \
;         __builtin_amdgcn_global_load_lds((const unsigned*)((const char*)(gbase) + (voff)[_i]), (LAS unsigned*)(lds + (bufoff) + ldsw + _i * 8192), 16, 0, 0); } while (0)
; #define PG8_LDA(dst, b, h) do { _Pragma("unroll") for (int m = 0; m < 4; ++m) _Pragma("unroll") for (int k = 0; k < 2; ++k) dst[m][k] = *(const LAS bf16x8*)(lds + PG8_SA(b, h) + aoff + m * 2048 + k * 1024); } while (0)
; #define PG8_LDB(dst, b, h) do { _Pragma("unroll") for (int n = 0; n < 2; ++n) _Pragma("unroll") for (int k = 0; k < 2; ++k) dst[n][k] = *(const LAS bf16x8*)(lds + PG8_SB(b, h) + boff + n * 2048 + k * 1024); } while (0)
; #define PG8_MMA(ai, bj, At, Bt) do { __builtin_amdgcn_s_setprio(1); _Pragma("unroll") for (int m = 0; m < 4; ++m) _Pragma("unroll") for (int n = 0; n < 2; ++n) _Pragma("unroll") for (int k = 0; k < 2; ++k) \
;         acc[ai][bj][m][n] = __builtin_amdgcn_mfma_f32_16x16x32_bf16(Bt[n][k], At[m][k], acc[ai][bj][m][n], 0, 0, 0); __builtin_amdgcn_s_setprio(0); } while (0)
; #define PG8_WAIT_V(n) asm volatile("s_waitcnt vmcnt(" #n ")" ::: "memory")
; #define PG8_WAIT_L(n) asm volatile("s_waitcnt lgkmcnt(" #n ")" ::: "memory")
; #define PG8_BAR __builtin_amdgcn_s_barrier()
; #define PG8_SCHED __builtin_amdgcn_sched_barrier(0)
; template <class Epi>
; __device__ __forceinline__ void gemm_phase(LAS unsigned char* lds, const int tid, const Gemm g, const StaticOrder& S, const Epi& E) {
;     ...
;             PG8_WAIT_V(8); PG8_WAIT_L(0); PG8_BAR; PG8_MMA(1, 0, At, B0); PG8_MMA(1, 1, At, B1); PG8_BAR; PG8_SCHED;
;             PG8_LDB(B0, 1, 0); PG8_LDB(B1, 1, 1); PG8_SCHED; PG8_LDA(At, 1, 0); PG8_STAGE(PG8_SA(0, 1), a2 + hstepA, voffA);
;             PG8_WAIT_V(8); PG8_WAIT_L(0); PG8_BAR; PG8_MMA(0, 0, At, B0); PG8_MMA(0, 1, At, B1); PG8_BAR; PG8_SCHED;
	s_setprio 1
	s_waitcnt lgkmcnt(0)
	v_mfma_f32_16x16x32_bf16 v[62:65], v[130:133], v[180:183], v[62:65]
	v_mfma_f32_16x16x32_bf16 v[58:61], v[138:141], v[180:183], v[58:61]
	v_mfma_f32_16x16x32_bf16 v[46:49], v[130:133], v[220:223], v[46:49]
	v_mfma_f32_16x16x32_bf16 v[42:45], v[138:141], v[220:223], v[42:45]
	v_mfma_f32_16x16x32_bf16 v[30:33], v[130:133], v[228:231], v[30:33]
	v_mfma_f32_16x16x32_bf16 v[26:29], v[138:141], v[228:231], v[26:29]
	v_mfma_f32_16x16x32_bf16 v[14:17], v[130:133], v[236:239], v[14:17]
	v_mfma_f32_16x16x32_bf16 v[10:13], v[138:141], v[236:239], v[10:13]
	v_mfma_f32_16x16x32_bf16 v[62:65], v[134:137], v[184:187], v[62:65]
	v_mfma_f32_16x16x32_bf16 v[58:61], v[142:145], v[184:187], v[58:61]
	v_mfma_f32_16x16x32_bf16 v[46:49], v[134:137], v[224:227], v[46:49]
	v_mfma_f32_16x16x32_bf16 v[42:45], v[142:145], v[224:227], v[42:45]
	v_mfma_f32_16x16x32_bf16 v[30:33], v[134:137], v[232:235], v[30:33]
	v_mfma_f32_16x16x32_bf16 v[26:29], v[142:145], v[232:235], v[26:29]
	v_mfma_f32_16x16x32_bf16 v[14:17], v[134:137], v[240:243], v[14:17]
	v_mfma_f32_16x16x32_bf16 v[10:13], v[142:145], v[240:243], v[10:13]
	s_setprio 0
	s_setprio 1
	v_mfma_f32_16x16x32_bf16 v[54:57], v[146:149], v[180:183], v[54:57]
	v_mfma_f32_16x16x32_bf16 v[50:53], v[154:157], v[180:183], v[50:53]
	v_mfma_f32_16x16x32_bf16 v[38:41], v[146:149], v[220:223], v[38:41]
	v_mfma_f32_16x16x32_bf16 v[34:37], v[154:157], v[220:223], v[34:37]
	v_mfma_f32_16x16x32_bf16 v[22:25], v[146:149], v[228:231], v[22:25]
	v_mfma_f32_16x16x32_bf16 v[18:21], v[154:157], v[228:231], v[18:21]
	v_mfma_f32_16x16x32_bf16 v[6:9], v[146:149], v[236:239], v[6:9]
	v_mfma_f32_16x16x32_bf16 v[2:5], v[154:157], v[236:239], v[2:5]
	v_mfma_f32_16x16x32_bf16 v[54:57], v[150:153], v[184:187], v[54:57]
	v_mfma_f32_16x16x32_bf16 v[50:53], v[158:161], v[184:187], v[50:53]
	v_mfma_f32_16x16x32_bf16 v[38:41], v[150:153], v[224:227], v[38:41]
	v_mfma_f32_16x16x32_bf16 v[34:37], v[158:161], v[224:227], v[34:37]
	v_mfma_f32_16x16x32_bf16 v[22:25], v[150:153], v[232:235], v[22:25]
	v_mfma_f32_16x16x32_bf16 v[18:21], v[158:161], v[232:235], v[18:21]
	v_mfma_f32_16x16x32_bf16 v[6:9], v[150:153], v[240:243], v[6:9]
	v_mfma_f32_16x16x32_bf16 v[2:5], v[158:161], v[240:243], v[2:5]
	s_setprio 0
	s_barrier
	s_add_i32 s27, 0, 0x18000
	s_add_i32 s17, 0, 0x1c000
	v_add_u32_e32 v142, s27, v216
	v_add_u32_e32 v158, s17, v216
	ds_read_b128 v[130:133], v142
	ds_read_b128 v[134:137], v142 offset:1024
	ds_read_b128 v[138:141], v142 offset:2048
	ds_read_b128 v[142:145], v142 offset:3072
	ds_read_b128 v[146:149], v158
	ds_read_b128 v[150:153], v158 offset:1024
	ds_read_b128 v[154:157], v158 offset:2048
	ds_read_b128 v[158:161], v158 offset:3072
	s_add_u32 s62, vcc_lo, 0x40000
	s_addc_u32 s63, vcc_hi, 0
	s_mov_b32 m0, s3
	s_nop 0
	global_load_lds_dwordx4 v172, s[62:63]
	s_mov_b32 m0, s16
	s_nop 0
	global_load_lds_dwordx4 v174, s[62:63]
	ds_read_b128 v[180:183], v218 offset:32768
	ds_read_b128 v[184:187], v218 offset:33792
	ds_read_b128 v[220:223], v218 offset:34816
	ds_read_b128 v[224:227], v218 offset:35840
	ds_read_b128 v[228:231], v218 offset:36864
	ds_read_b128 v[232:235], v218 offset:37888
	ds_read_b128 v[236:239], v218 offset:38912
	ds_read_b128 v[240:243], v218 offset:39936
	s_waitcnt vmcnt(8)
	s_waitcnt lgkmcnt(0)
	s_barrier
	s_setprio 1
	s_waitcnt lgkmcnt(0)
	v_mfma_f32_16x16x32_bf16 v[126:129], v[130:133], v[180:183], v[126:129]
	v_mfma_f32_16x16x32_bf16 v[122:125], v[138:141], v[180:183], v[122:125]
	v_mfma_f32_16x16x32_bf16 v[110:113], v[130:133], v[220:223], v[110:113]
	v_mfma_f32_16x16x32_bf16 v[106:109], v[138:141], v[220:223], v[106:109]
	v_mfma_f32_16x16x32_bf16 v[94:97], v[130:133], v[228:231], v[94:97]
	v_mfma_f32_16x16x32_bf16 v[90:93], v[138:141], v[228:231], v[90:93]
	v_mfma_f32_16x16x32_bf16 v[78:81], v[130:133], v[236:239], v[78:81]
	v_mfma_f32_16x16x32_bf16 v[74:77], v[138:141], v[236:239], v[74:77]
	v_mfma_f32_16x16x32_bf16 v[126:129], v[134:137], v[184:187], v[126:129]
	v_mfma_f32_16x16x32_bf16 v[122:125], v[142:145], v[184:187], v[122:125]
	v_mfma_f32_16x16x32_bf16 v[110:113], v[134:137], v[224:227], v[110:113]
	v_mfma_f32_16x16x32_bf16 v[106:109], v[142:145], v[224:227], v[106:109]
	v_mfma_f32_16x16x32_bf16 v[94:97], v[134:137], v[232:235], v[94:97]
	v_mfma_f32_16x16x32_bf16 v[90:93], v[142:145], v[232:235], v[90:93]
	v_mfma_f32_16x16x32_bf16 v[78:81], v[134:137], v[240:243], v[78:81]
	v_mfma_f32_16x16x32_bf16 v[74:77], v[142:145], v[240:243], v[74:77]
	s_setprio 0
	s_setprio 1
	v_mfma_f32_16x16x32_bf16 v[118:121], v[146:149], v[180:183], v[118:121]
	v_mfma_f32_16x16x32_bf16 v[114:117], v[154:157], v[180:183], v[114:117]
	v_mfma_f32_16x16x32_bf16 v[102:105], v[146:149], v[220:223], v[102:105]
	v_mfma_f32_16x16x32_bf16 v[98:101], v[154:157], v[220:223], v[98:101]
	v_mfma_f32_16x16x32_bf16 v[86:89], v[146:149], v[228:231], v[86:89]
	v_mfma_f32_16x16x32_bf16 v[82:85], v[154:157], v[228:231], v[82:85]
	v_mfma_f32_16x16x32_bf16 v[70:73], v[146:149], v[236:239], v[70:73]
	v_mfma_f32_16x16x32_bf16 v[66:69], v[154:157], v[236:239], v[66:69]
	v_mfma_f32_16x16x32_bf16 v[118:121], v[150:153], v[184:187], v[118:121]
	v_mfma_f32_16x16x32_bf16 v[114:117], v[158:161], v[184:187], v[114:117]
	v_mfma_f32_16x16x32_bf16 v[102:105], v[150:153], v[224:227], v[102:105]
	v_mfma_f32_16x16x32_bf16 v[98:101], v[158:161], v[224:227], v[98:101]
	v_mfma_f32_16x16x32_bf16 v[86:89], v[150:153], v[232:235], v[86:89]
	v_mfma_f32_16x16x32_bf16 v[82:85], v[158:161], v[232:235], v[82:85]
	v_mfma_f32_16x16x32_bf16 v[70:73], v[150:153], v[240:243], v[70:73]
	v_mfma_f32_16x16x32_bf16 v[66:69], v[158:161], v[240:243], v[66:69]
	s_setprio 0
	s_barrier
; #define PG8_STAGE(bufoff, gbase, voff) do { _Pragma("unroll") for (int _i = 0; _i < 2; ++_i) \
;         __builtin_amdgcn_global_load_lds((const unsigned*)((const char*)(gbase) + (voff)[_i]), (LAS unsigned*)(lds + (bufoff) + ldsw + _i * 8192), 16, 0, 0); } while (0)
; #define PG8_LDA(dst, b, h) do { _Pragma("unroll") for (int m = 0; m < 4; ++m) _Pragma("unroll") for (int k = 0; k < 2; ++k) dst[m][k] = *(const LAS bf16x8*)(lds + PG8_SA(b, h) + aoff + m * 2048 + k * 1024); } while (0)
; #define PG8_MMA(ai, bj, At, Bt) do { __builtin_amdgcn_s_setprio(1); _Pragma("unroll") for (int m = 0; m < 4; ++m) _Pragma("unroll") for (int n = 0; n < 2; ++n) _Pragma("unroll") for (int k = 0; k < 2; ++k) \
;         acc[ai][bj][m][n] = __builtin_amdgcn_mfma_f32_16x16x32_bf16(Bt[n][k], At[m][k], acc[ai][bj][m][n], 0, 0, 0); __builtin_amdgcn_s_setprio(0); } while (0)
; #define PG8_WAIT_V(n) asm volatile("s_waitcnt vmcnt(" #n ")" ::: "memory")
; #define PG8_WAIT_L(n) asm volatile("s_waitcnt lgkmcnt(" #n ")" ::: "memory")
; #define PG8_BAR __builtin_amdgcn_s_barrier()
; #define PG8_SCHED __builtin_amdgcn_sched_barrier(0)
; template <class Epi>
; __device__ __forceinline__ void gemm_phase(LAS unsigned char* lds, const int tid, const Gemm g, const StaticOrder& S, const Epi& E) {
;     ...
;             PG8_LDA(At, 1, 1); PG8_STAGE(PG8_SB(1, 0), b3, voffB); PG8_STAGE(PG8_SB(1, 1), b3 + hstepB, voffB); PG8_STAGE(PG8_SA(1, 0), a3, voffA);
;             PG8_WAIT_V(8); PG8_WAIT_L(0); PG8_BAR; PG8_MMA(1, 0, At, B0); PG8_MMA(1, 1, At, B1); PG8_BAR; PG8_SCHED;
;         }
;         if (wr == 0) PG8_BAR;
	s_add_i32 s27, s27, s0
	v_lshl_add_u64 v[162:163], v[162:163], 0, s[36:37]
	s_mov_b32 m0, s27
	s_nop 0
	global_load_lds_dwordx4 v[162:163], off
	s_add_i32 m0, s27, 0x2000
	s_add_u32 s30, s30, 0x40080
	v_lshl_add_u64 v[162:163], v[164:165], 0, s[36:37]
	s_addc_u32 s31, s31, 0
	s_add_i32 s17, s17, s0
	global_load_lds_dwordx4 v[162:163], off
	s_mov_b32 m0, s17
	s_nop 0
	global_load_lds_dwordx4 v0, s[30:31]
	s_add_i32 m0, s17, 0x2000
	s_nop 0
	global_load_lds_dwordx4 v170, s[30:31]
	v_lshl_add_u64 v[162:163], v[206:207], 0, s[36:37]
	s_mov_b32 m0, s10
	s_nop 0
	global_load_lds_dwordx4 v[162:163], off
	v_lshl_add_u64 v[162:163], v[244:245], 0, s[36:37]
	s_mov_b32 m0, s11
	s_nop 0
	global_load_lds_dwordx4 v[162:163], off
	ds_read_b128 v[180:183], v218 offset:49152
	ds_read_b128 v[184:187], v218 offset:50176
	ds_read_b128 v[220:223], v218 offset:51200
	ds_read_b128 v[224:227], v218 offset:52224
	ds_read_b128 v[228:231], v218 offset:53248
	ds_read_b128 v[232:235], v218 offset:54272
	ds_read_b128 v[236:239], v218 offset:55296
	ds_read_b128 v[240:243], v218 offset:56320
	s_waitcnt vmcnt(8)
	s_waitcnt lgkmcnt(0)
	s_barrier
	s_setprio 1
	s_waitcnt lgkmcnt(0)
	v_mfma_f32_16x16x32_bf16 v[62:65], v[130:133], v[180:183], v[62:65]
	v_mfma_f32_16x16x32_bf16 v[58:61], v[138:141], v[180:183], v[58:61]
	v_mfma_f32_16x16x32_bf16 v[46:49], v[130:133], v[220:223], v[46:49]
	v_mfma_f32_16x16x32_bf16 v[42:45], v[138:141], v[220:223], v[42:45]
	v_mfma_f32_16x16x32_bf16 v[30:33], v[130:133], v[228:231], v[30:33]
	v_mfma_f32_16x16x32_bf16 v[26:29], v[138:141], v[228:231], v[26:29]
	v_mfma_f32_16x16x32_bf16 v[14:17], v[130:133], v[236:239], v[14:17]
	v_mfma_f32_16x16x32_bf16 v[10:13], v[138:141], v[236:239], v[10:13]
	v_mfma_f32_16x16x32_bf16 v[62:65], v[134:137], v[184:187], v[62:65]
	v_mfma_f32_16x16x32_bf16 v[58:61], v[142:145], v[184:187], v[58:61]
	v_mfma_f32_16x16x32_bf16 v[46:49], v[134:137], v[224:227], v[46:49]
	v_mfma_f32_16x16x32_bf16 v[42:45], v[142:145], v[224:227], v[42:45]
	v_mfma_f32_16x16x32_bf16 v[30:33], v[134:137], v[232:235], v[30:33]
	v_mfma_f32_16x16x32_bf16 v[26:29], v[142:145], v[232:235], v[26:29]
	v_mfma_f32_16x16x32_bf16 v[14:17], v[134:137], v[240:243], v[14:17]
	v_mfma_f32_16x16x32_bf16 v[10:13], v[142:145], v[240:243], v[10:13]
	s_setprio 0
	s_setprio 1
	v_mfma_f32_16x16x32_bf16 v[54:57], v[146:149], v[180:183], v[54:57]
	v_mfma_f32_16x16x32_bf16 v[50:53], v[154:157], v[180:183], v[50:53]
	v_mfma_f32_16x16x32_bf16 v[38:41], v[146:149], v[220:223], v[38:41]
	v_mfma_f32_16x16x32_bf16 v[34:37], v[154:157], v[220:223], v[34:37]
	v_mfma_f32_16x16x32_bf16 v[22:25], v[146:149], v[228:231], v[22:25]
	v_mfma_f32_16x16x32_bf16 v[18:21], v[154:157], v[228:231], v[18:21]
	v_mfma_f32_16x16x32_bf16 v[6:9], v[146:149], v[236:239], v[6:9]
	v_mfma_f32_16x16x32_bf16 v[2:5], v[154:157], v[236:239], v[2:5]
	v_mfma_f32_16x16x32_bf16 v[54:57], v[150:153], v[184:187], v[54:57]
	v_mfma_f32_16x16x32_bf16 v[50:53], v[158:161], v[184:187], v[50:53]
	v_mfma_f32_16x16x32_bf16 v[38:41], v[150:153], v[224:227], v[38:41]
	v_mfma_f32_16x16x32_bf16 v[34:37], v[158:161], v[224:227], v[34:37]
	v_mfma_f32_16x16x32_bf16 v[22:25], v[150:153], v[232:235], v[22:25]
	v_mfma_f32_16x16x32_bf16 v[18:21], v[158:161], v[232:235], v[18:21]
	v_mfma_f32_16x16x32_bf16 v[6:9], v[150:153], v[240:243], v[6:9]
	v_mfma_f32_16x16x32_bf16 v[2:5], v[158:161], v[240:243], v[2:5]
	s_setprio 0
	s_barrier
	s_add_i32 s26, s26, 2
	s_add_u32 s68, s68, 0x100
	s_addc_u32 s69, s69, 0
	s_add_u32 s75, s75, 0x100
	s_addc_u32 s83, s83, 0
	s_cmp_gt_u32 s26, 13
	s_cbranch_scc0 .LBB0_1487
	v_readlane_b32 s26, v255, 55
	v_readlane_b32 s27, v255, 56
	s_and_b64 vcc, exec, s[26:27]
	s_cbranch_vccz .LBB0_1490
	s_barrier

; #define PG8_STAGE(bufoff, gbase, voff) do { _Pragma("unroll") for (int _i = 0; _i < 2; ++_i) \
;         __builtin_amdgcn_global_load_lds((const unsigned*)((const char*)(gbase) + (voff)[_i]), (LAS unsigned*)(lds + (bufoff) + ldsw + _i * 8192), 16, 0, 0); } while (0)
; #define PG8_LDA(dst, b, h) do { _Pragma("unroll") for (int m = 0; m < 4; ++m) _Pragma("unroll") for (int k = 0; k < 2; ++k) dst[m][k] = *(const LAS bf16x8*)(lds + PG8_SA(b, h) + aoff + m * 2048 + k * 1024); } while (0)
; #define PG8_LDB(dst, b, h) do { _Pragma("unroll") for (int n = 0; n < 2; ++n) _Pragma("unroll") for (int k = 0; k < 2; ++k) dst[n][k] = *(const LAS bf16x8*)(lds + PG8_SB(b, h) + boff + n * 2048 + k * 1024); } while (0)
; #define PG8_MMA(ai, bj, At, Bt) do { __builtin_amdgcn_s_setprio(1); _Pragma("unroll") for (int m = 0; m < 4; ++m) _Pragma("unroll") for (int n = 0; n < 2; ++n) _Pragma("unroll") for (int k = 0; k < 2; ++k) \
;         acc[ai][bj][m][n] = __builtin_amdgcn_mfma_f32_16x16x32_bf16(Bt[n][k], At[m][k], acc[ai][bj][m][n], 0, 0, 0); __builtin_amdgcn_s_setprio(0); } while (0)
; #define PG8_WAIT_V(n) asm volatile("s_waitcnt vmcnt(" #n ")" ::: "memory")
; #define PG8_WAIT_L(n) asm volatile("s_waitcnt lgkmcnt(" #n ")" ::: "memory")
; #define PG8_BAR __builtin_amdgcn_s_barrier()
; #define PG8_SCHED __builtin_amdgcn_sched_barrier(0)
; template <class Epi>
; __device__ __forceinline__ void gemm_phase(LAS unsigned char* lds, const int tid, const Gemm g, const StaticOrder& S, const Epi& E) {
;     ...
;         for (int t = 0; t < nt; t += 2) {
;             const bool last = (t == nt - 2);
;             const char* a1 = cA + (size_t)(t + 1) * kstep;
;             const char* a2 = last ? nA : cA + (size_t)(t + 2) * kstep; const char* b2 = last ? nB : cB + (size_t)(t + 2) * kstep;
;             const char* a3 = a2 + kstep; const char* b3 = b2 + kstep;
;             PG8_LDB(B0, 0, 0); PG8_LDB(B1, 0, 1); PG8_SCHED; PG8_LDA(At, 0, 0); PG8_STAGE(PG8_SA(1, 1), a1 + hstepA, voffA);
;             PG8_WAIT_V(8); PG8_WAIT_L(0); PG8_BAR; PG8_MMA(0, 0, At, B0); PG8_MMA(0, 1, At, B1); PG8_BAR; PG8_SCHED;
;             PG8_LDA(At, 0, 1); PG8_STAGE(PG8_SB(0, 0), b2, voffB); PG8_STAGE(PG8_SB(0, 1), b2 + hstepB, voffB); PG8_STAGE(PG8_SA(0, 0), a2, voffA);
;             PG8_WAIT_V(8); PG8_WAIT_L(0); PG8_BAR; PG8_MMA(1, 0, At, B0); PG8_MMA(1, 1, At, B1); PG8_BAR; PG8_SCHED;
.LBB0_1912:
	s_add_u32 s30, s82, 0xfffc0080
	s_addc_u32 s31, s83, -1
	s_add_i32 s92, 0, 0x10000
	s_cmp_eq_u32 s17, 12
	s_cselect_b32 s89, s7, s31
	s_cselect_b32 s88, s65, s30
	s_cselect_b32 s31, s5, s27
	s_cselect_b32 s30, vcc_lo, vcc_hi
	s_add_i32 s11, 0, 0x14000
	v_add_u32_e32 v110, s92, v158
	v_add_u32_e32 v162, s11, v158
	ds_read_b128 v[98:101], v110
	ds_read_b128 v[102:105], v110 offset:1024
	ds_read_b128 v[106:109], v110 offset:2048
	ds_read_b128 v[110:113], v110 offset:3072
	ds_read_b128 v[174:177], v162
	ds_read_b128 v[178:181], v162 offset:1024
	ds_read_b128 v[182:185], v162 offset:2048
	ds_read_b128 v[186:189], v162 offset:3072
	s_add_i32 m0, s66, 0xc000
	s_nop 0
	global_load_lds_dwordx4 v152, s[82:83]
	s_add_i32 m0, s66, 0xe000
	s_nop 0
	global_load_lds_dwordx4 v154, s[82:83]
	ds_read_b128 v[190:193], v172
	ds_read_b128 v[194:197], v172 offset:1024
	ds_read_b128 v[198:201], v172 offset:2048
	ds_read_b128 v[210:213], v172 offset:3072
	ds_read_b128 v[214:217], v172 offset:4096
	ds_read_b128 v[218:221], v172 offset:5120
	ds_read_b128 v[222:225], v172 offset:6144
	ds_read_b128 v[226:229], v172 offset:7168
	s_waitcnt vmcnt(8)
	s_waitcnt lgkmcnt(0)
	s_barrier
	s_setprio 1
	s_waitcnt lgkmcnt(0)
	v_mfma_f32_16x16x32_bf16 v[142:145], v[98:101], v[190:193], v[142:145]
	v_mfma_f32_16x16x32_bf16 v[138:141], v[106:109], v[190:193], v[138:141]
	v_mfma_f32_16x16x32_bf16 v[134:137], v[98:101], v[198:201], v[134:137]
	v_mfma_f32_16x16x32_bf16 v[130:133], v[106:109], v[198:201], v[130:133]
	v_mfma_f32_16x16x32_bf16 v[94:97], v[98:101], v[214:217], v[94:97]
	v_mfma_f32_16x16x32_bf16 v[90:93], v[106:109], v[214:217], v[90:93]
	v_mfma_f32_16x16x32_bf16 v[78:81], v[98:101], v[222:225], v[78:81]
	v_mfma_f32_16x16x32_bf16 v[74:77], v[106:109], v[222:225], v[74:77]
	v_mfma_f32_16x16x32_bf16 v[142:145], v[102:105], v[194:197], v[142:145]
	v_mfma_f32_16x16x32_bf16 v[138:141], v[110:113], v[194:197], v[138:141]
	v_mfma_f32_16x16x32_bf16 v[134:137], v[102:105], v[210:213], v[134:137]
	v_mfma_f32_16x16x32_bf16 v[130:133], v[110:113], v[210:213], v[130:133]
	v_mfma_f32_16x16x32_bf16 v[94:97], v[102:105], v[218:221], v[94:97]
	v_mfma_f32_16x16x32_bf16 v[90:93], v[110:113], v[218:221], v[90:93]
	v_mfma_f32_16x16x32_bf16 v[78:81], v[102:105], v[226:229], v[78:81]
	v_mfma_f32_16x16x32_bf16 v[74:77], v[110:113], v[226:229], v[74:77]
	s_setprio 0
	s_setprio 1
	v_mfma_f32_16x16x32_bf16 v[126:129], v[174:177], v[190:193], v[126:129]
	v_mfma_f32_16x16x32_bf16 v[122:125], v[182:185], v[190:193], v[122:125]
	v_mfma_f32_16x16x32_bf16 v[118:121], v[174:177], v[198:201], v[118:121]
	v_mfma_f32_16x16x32_bf16 v[114:117], v[182:185], v[198:201], v[114:117]
	v_mfma_f32_16x16x32_bf16 v[86:89], v[174:177], v[214:217], v[86:89]
	v_mfma_f32_16x16x32_bf16 v[82:85], v[182:185], v[214:217], v[82:85]
	v_mfma_f32_16x16x32_bf16 v[70:73], v[174:177], v[222:225], v[70:73]
	v_mfma_f32_16x16x32_bf16 v[66:69], v[182:185], v[222:225], v[66:69]
	v_mfma_f32_16x16x32_bf16 v[126:129], v[178:181], v[194:197], v[126:129]
	v_mfma_f32_16x16x32_bf16 v[122:125], v[186:189], v[194:197], v[122:125]
	v_mfma_f32_16x16x32_bf16 v[118:121], v[178:181], v[210:213], v[118:121]
	v_mfma_f32_16x16x32_bf16 v[114:117], v[186:189], v[210:213], v[114:117]
	v_mfma_f32_16x16x32_bf16 v[86:89], v[178:181], v[218:221], v[86:89]
	v_mfma_f32_16x16x32_bf16 v[82:85], v[186:189], v[218:221], v[82:85]
	v_mfma_f32_16x16x32_bf16 v[70:73], v[178:181], v[226:229], v[70:73]
	v_mfma_f32_16x16x32_bf16 v[66:69], v[186:189], v[226:229], v[66:69]
	s_setprio 0
	s_barrier
	s_add_i32 s92, s92, s28
	v_lshl_add_u64 v[162:163], s[30:31], 0, v[0:1]
	s_mov_b32 m0, s92
	s_nop 0
	global_load_lds_dwordx4 v[162:163], off
	s_add_i32 m0, s92, 0x2000
	s_add_u32 s92, s30, 0x40000
	v_lshl_add_u64 v[164:165], s[30:31], 0, v[146:147]
	s_addc_u32 s93, s31, 0
	s_add_i32 s11, s11, s28
	global_load_lds_dwordx4 v[164:165], off
	s_mov_b32 m0, s11
	v_lshl_add_u64 v[206:207], s[88:89], 0, v[148:149]
	global_load_lds_dwordx4 v0, s[92:93]
	s_add_i32 m0, s11, 0x2000
	s_nop 0
	global_load_lds_dwordx4 v146, s[92:93]
	v_lshl_add_u64 v[202:203], s[88:89], 0, v[150:151]
	s_mov_b32 m0, s66
	s_nop 0
	global_load_lds_dwordx4 v[202:203], off
	s_mov_b32 m0, s67
	s_nop 0
	global_load_lds_dwordx4 v[206:207], off
	ds_read_b128 v[190:193], v172 offset:16384
	ds_read_b128 v[194:197], v172 offset:17408
	ds_read_b128 v[198:201], v172 offset:18432
	ds_read_b128 v[210:213], v172 offset:19456
	ds_read_b128 v[214:217], v172 offset:20480
	ds_read_b128 v[218:221], v172 offset:21504
	ds_read_b128 v[222:225], v172 offset:22528
	ds_read_b128 v[226:229], v172 offset:23552
	s_waitcnt vmcnt(8)
	s_waitcnt lgkmcnt(0)
	s_barrier
; #define PG8_STAGE(bufoff, gbase, voff) do { _Pragma("unroll") for (int _i = 0; _i < 2; ++_i) \
;         __builtin_amdgcn_global_load_lds((const unsigned*)((const char*)(gbase) + (voff)[_i]), (LAS unsigned*)(lds + (bufoff) + ldsw + _i * 8192), 16, 0, 0); } while (0)
; #define PG8_LDA(dst, b, h) do { _Pragma("unroll") for (int m = 0; m < 4; ++m) _Pragma("unroll") for (int k = 0; k < 2; ++k) dst[m][k] = *(const LAS bf16x8*)(lds + PG8_SA(b, h) + aoff + m * 2048 + k * 1024); } while (0)
; #define PG8_LDB(dst, b, h) do { _Pragma("unroll") for (int n = 0; n < 2; ++n) _Pragma("unroll") for (int k = 0; k < 2; ++k) dst[n][k] = *(const LAS bf16x8*)(lds + PG8_SB(b, h) + boff + n * 2048 + k * 1024); } while (0)
; #define PG8_MMA(ai, bj, At, Bt) do { __builtin_amdgcn_s_setprio(1); _Pragma("unroll") for (int m = 0; m < 4; ++m) _Pragma("unroll") for (int n = 0; n < 2; ++n) _Pragma("unroll") for (int k = 0; k < 2; ++k) \
;         acc[ai][bj][m][n] = __builtin_amdgcn_mfma_f32_16x16x32_bf16(Bt[n][k], At[m][k], acc[ai][bj][m][n], 0, 0, 0); __builtin_amdgcn_s_setprio(0); } while (0)
; #define PG8_WAIT_V(n) asm volatile("s_waitcnt vmcnt(" #n ")" ::: "memory")
; #define PG8_WAIT_L(n) asm volatile("s_waitcnt lgkmcnt(" #n ")" ::: "memory")
; #define PG8_BAR __builtin_amdgcn_s_barrier()
; #define PG8_SCHED __builtin_amdgcn_sched_barrier(0)
; template <class Epi>
; __device__ __forceinline__ void gemm_phase(LAS unsigned char* lds, const int tid, const Gemm g, const StaticOrder& S, const Epi& E) {
;     ...
;             PG8_WAIT_V(8); PG8_WAIT_L(0); PG8_BAR; PG8_MMA(1, 0, At, B0); PG8_MMA(1, 1, At, B1); PG8_BAR; PG8_SCHED;
;             PG8_LDB(B0, 1, 0); PG8_LDB(B1, 1, 1); PG8_SCHED; PG8_LDA(At, 1, 0); PG8_STAGE(PG8_SA(0, 1), a2 + hstepA, voffA);
;             PG8_WAIT_V(8); PG8_WAIT_L(0); PG8_BAR; PG8_MMA(0, 0, At, B0); PG8_MMA(0, 1, At, B1); PG8_BAR; PG8_SCHED;
	s_setprio 1
	s_waitcnt lgkmcnt(0)
	v_mfma_f32_16x16x32_bf16 v[62:65], v[98:101], v[190:193], v[62:65]
	v_mfma_f32_16x16x32_bf16 v[58:61], v[106:109], v[190:193], v[58:61]
	v_mfma_f32_16x16x32_bf16 v[54:57], v[98:101], v[198:201], v[54:57]
	v_mfma_f32_16x16x32_bf16 v[46:49], v[106:109], v[198:201], v[46:49]
	v_mfma_f32_16x16x32_bf16 v[30:33], v[98:101], v[214:217], v[30:33]
	v_mfma_f32_16x16x32_bf16 v[26:29], v[106:109], v[214:217], v[26:29]
	v_mfma_f32_16x16x32_bf16 v[22:25], v[98:101], v[222:225], v[22:25]
	v_mfma_f32_16x16x32_bf16 v[14:17], v[106:109], v[222:225], v[14:17]
	v_mfma_f32_16x16x32_bf16 v[62:65], v[102:105], v[194:197], v[62:65]
	v_mfma_f32_16x16x32_bf16 v[58:61], v[110:113], v[194:197], v[58:61]
	v_mfma_f32_16x16x32_bf16 v[54:57], v[102:105], v[210:213], v[54:57]
	v_mfma_f32_16x16x32_bf16 v[46:49], v[110:113], v[210:213], v[46:49]
	v_mfma_f32_16x16x32_bf16 v[30:33], v[102:105], v[218:221], v[30:33]
	v_mfma_f32_16x16x32_bf16 v[26:29], v[110:113], v[218:221], v[26:29]
	v_mfma_f32_16x16x32_bf16 v[22:25], v[102:105], v[226:229], v[22:25]
	v_mfma_f32_16x16x32_bf16 v[14:17], v[110:113], v[226:229], v[14:17]
	s_setprio 0
	s_setprio 1
	v_mfma_f32_16x16x32_bf16 v[50:53], v[174:177], v[190:193], v[50:53]
	v_mfma_f32_16x16x32_bf16 v[42:45], v[182:185], v[190:193], v[42:45]
	v_mfma_f32_16x16x32_bf16 v[38:41], v[174:177], v[198:201], v[38:41]
	v_mfma_f32_16x16x32_bf16 v[34:37], v[182:185], v[198:201], v[34:37]
	v_mfma_f32_16x16x32_bf16 v[18:21], v[174:177], v[214:217], v[18:21]
	v_mfma_f32_16x16x32_bf16 v[10:13], v[182:185], v[214:217], v[10:13]
	v_mfma_f32_16x16x32_bf16 v[6:9], v[174:177], v[222:225], v[6:9]
	v_mfma_f32_16x16x32_bf16 v[2:5], v[182:185], v[222:225], v[2:5]
	v_mfma_f32_16x16x32_bf16 v[50:53], v[178:181], v[194:197], v[50:53]
	v_mfma_f32_16x16x32_bf16 v[42:45], v[186:189], v[194:197], v[42:45]
	v_mfma_f32_16x16x32_bf16 v[38:41], v[178:181], v[210:213], v[38:41]
	v_mfma_f32_16x16x32_bf16 v[34:37], v[186:189], v[210:213], v[34:37]
	v_mfma_f32_16x16x32_bf16 v[18:21], v[178:181], v[218:221], v[18:21]
	v_mfma_f32_16x16x32_bf16 v[10:13], v[186:189], v[218:221], v[10:13]
	v_mfma_f32_16x16x32_bf16 v[6:9], v[178:181], v[226:229], v[6:9]
	v_mfma_f32_16x16x32_bf16 v[2:5], v[186:189], v[226:229], v[2:5]
	s_setprio 0
	s_barrier
	s_add_i32 s11, 0, 0x18000
	s_add_i32 s92, 0, 0x1c000
	v_add_u32_e32 v110, s11, v158
	v_add_u32_e32 v173, s92, v158
	ds_read_b128 v[98:101], v110
	ds_read_b128 v[102:105], v110 offset:1024
	ds_read_b128 v[106:109], v110 offset:2048
	ds_read_b128 v[110:113], v110 offset:3072
	ds_read_b128 v[174:177], v173
	ds_read_b128 v[178:181], v173 offset:1024
	ds_read_b128 v[182:185], v173 offset:2048
	ds_read_b128 v[186:189], v173 offset:3072
	s_add_u32 s88, s88, 0x40000
	s_addc_u32 s89, s89, 0
	s_mov_b32 m0, s70
	s_nop 0
	global_load_lds_dwordx4 v150, s[88:89]
	s_mov_b32 m0, s71
	s_nop 0
	global_load_lds_dwordx4 v148, s[88:89]
	ds_read_b128 v[190:193], v172 offset:32768
	ds_read_b128 v[194:197], v172 offset:33792
	ds_read_b128 v[198:201], v172 offset:34816
	ds_read_b128 v[210:213], v172 offset:35840
	ds_read_b128 v[214:217], v172 offset:36864
	ds_read_b128 v[218:221], v172 offset:37888
	ds_read_b128 v[222:225], v172 offset:38912
	ds_read_b128 v[226:229], v172 offset:39936
	s_waitcnt vmcnt(8)
	s_waitcnt lgkmcnt(0)
	s_barrier
	s_setprio 1
	s_waitcnt lgkmcnt(0)
	v_mfma_f32_16x16x32_bf16 v[142:145], v[98:101], v[190:193], v[142:145]
	v_mfma_f32_16x16x32_bf16 v[138:141], v[106:109], v[190:193], v[138:141]
	v_mfma_f32_16x16x32_bf16 v[134:137], v[98:101], v[198:201], v[134:137]
	v_mfma_f32_16x16x32_bf16 v[130:133], v[106:109], v[198:201], v[130:133]
	v_mfma_f32_16x16x32_bf16 v[94:97], v[98:101], v[214:217], v[94:97]
	v_mfma_f32_16x16x32_bf16 v[90:93], v[106:109], v[214:217], v[90:93]
	v_mfma_f32_16x16x32_bf16 v[78:81], v[98:101], v[222:225], v[78:81]
	v_mfma_f32_16x16x32_bf16 v[74:77], v[106:109], v[222:225], v[74:77]
	v_mfma_f32_16x16x32_bf16 v[142:145], v[102:105], v[194:197], v[142:145]
	v_mfma_f32_16x16x32_bf16 v[138:141], v[110:113], v[194:197], v[138:141]
	v_mfma_f32_16x16x32_bf16 v[134:137], v[102:105], v[210:213], v[134:137]
	v_mfma_f32_16x16x32_bf16 v[130:133], v[110:113], v[210:213], v[130:133]
	v_mfma_f32_16x16x32_bf16 v[94:97], v[102:105], v[218:221], v[94:97]
	v_mfma_f32_16x16x32_bf16 v[90:93], v[110:113], v[218:221], v[90:93]
	v_mfma_f32_16x16x32_bf16 v[78:81], v[102:105], v[226:229], v[78:81]
	v_mfma_f32_16x16x32_bf16 v[74:77], v[110:113], v[226:229], v[74:77]
	s_setprio 0
	s_setprio 1
	v_mfma_f32_16x16x32_bf16 v[126:129], v[174:177], v[190:193], v[126:129]
	v_mfma_f32_16x16x32_bf16 v[122:125], v[182:185], v[190:193], v[122:125]
	v_mfma_f32_16x16x32_bf16 v[118:121], v[174:177], v[198:201], v[118:121]
	v_mfma_f32_16x16x32_bf16 v[114:117], v[182:185], v[198:201], v[114:117]
	v_mfma_f32_16x16x32_bf16 v[86:89], v[174:177], v[214:217], v[86:89]
	v_mfma_f32_16x16x32_bf16 v[82:85], v[182:185], v[214:217], v[82:85]
	v_mfma_f32_16x16x32_bf16 v[70:73], v[174:177], v[222:225], v[70:73]
	v_mfma_f32_16x16x32_bf16 v[66:69], v[182:185], v[222:225], v[66:69]
	v_mfma_f32_16x16x32_bf16 v[126:129], v[178:181], v[194:197], v[126:129]
	v_mfma_f32_16x16x32_bf16 v[122:125], v[186:189], v[194:197], v[122:125]
	v_mfma_f32_16x16x32_bf16 v[118:121], v[178:181], v[210:213], v[118:121]
	v_mfma_f32_16x16x32_bf16 v[114:117], v[186:189], v[210:213], v[114:117]
	v_mfma_f32_16x16x32_bf16 v[86:89], v[178:181], v[218:221], v[86:89]
	v_mfma_f32_16x16x32_bf16 v[82:85], v[186:189], v[218:221], v[82:85]
	v_mfma_f32_16x16x32_bf16 v[70:73], v[178:181], v[226:229], v[70:73]
	v_mfma_f32_16x16x32_bf16 v[66:69], v[186:189], v[226:229], v[66:69]
	s_setprio 0
	s_barrier
; #define PG8_STAGE(bufoff, gbase, voff) do { _Pragma("unroll") for (int _i = 0; _i < 2; ++_i) \
;         __builtin_amdgcn_global_load_lds((const unsigned*)((const char*)(gbase) + (voff)[_i]), (LAS unsigned*)(lds + (bufoff) + ldsw + _i * 8192), 16, 0, 0); } while (0)
; #define PG8_LDA(dst, b, h) do { _Pragma("unroll") for (int m = 0; m < 4; ++m) _Pragma("unroll") for (int k = 0; k < 2; ++k) dst[m][k] = *(const LAS bf16x8*)(lds + PG8_SA(b, h) + aoff + m * 2048 + k * 1024); } while (0)
; #define PG8_MMA(ai, bj, At, Bt) do { __builtin_amdgcn_s_setprio(1); _Pragma("unroll") for (int m = 0; m < 4; ++m) _Pragma("unroll") for (int n = 0; n < 2; ++n) _Pragma("unroll") for (int k = 0; k < 2; ++k) \
;         acc[ai][bj][m][n] = __builtin_amdgcn_mfma_f32_16x16x32_bf16(Bt[n][k], At[m][k], acc[ai][bj][m][n], 0, 0, 0); __builtin_amdgcn_s_setprio(0); } while (0)
; #define PG8_WAIT_V(n) asm volatile("s_waitcnt vmcnt(" #n ")" ::: "memory")
; #define PG8_WAIT_L(n) asm volatile("s_waitcnt lgkmcnt(" #n ")" ::: "memory")
; #define PG8_BAR __builtin_amdgcn_s_barrier()
; #define PG8_SCHED __builtin_amdgcn_sched_barrier(0)
; template <class Epi>
; __device__ __forceinline__ void gemm_phase(LAS unsigned char* lds, const int tid, const Gemm g, const StaticOrder& S, const Epi& E) {
;     ...
;             PG8_LDA(At, 1, 1); PG8_STAGE(PG8_SB(1, 0), b3, voffB); PG8_STAGE(PG8_SB(1, 1), b3 + hstepB, voffB); PG8_STAGE(PG8_SA(1, 0), a3, voffA);
;             PG8_WAIT_V(8); PG8_WAIT_L(0); PG8_BAR; PG8_MMA(1, 0, At, B0); PG8_MMA(1, 1, At, B1); PG8_BAR; PG8_SCHED;
;         }
;         if (wr == 0) PG8_BAR;
	s_add_i32 s11, s11, s28
	v_lshl_add_u64 v[162:163], v[162:163], 0, s[36:37]
	s_mov_b32 m0, s11
	s_nop 0
	global_load_lds_dwordx4 v[162:163], off
	s_add_i32 m0, s11, 0x2000
	s_add_u32 s30, s30, 0x40080
	v_lshl_add_u64 v[162:163], v[164:165], 0, s[36:37]
	s_addc_u32 s31, s31, 0
	s_add_i32 s11, s92, s28
	global_load_lds_dwordx4 v[162:163], off
	s_mov_b32 m0, s11
	s_nop 0
	global_load_lds_dwordx4 v0, s[30:31]
	s_add_i32 m0, s11, 0x2000
	s_nop 0
	global_load_lds_dwordx4 v146, s[30:31]
	v_lshl_add_u64 v[162:163], v[202:203], 0, s[36:37]
	s_mov_b32 m0, s72
	s_nop 0
	global_load_lds_dwordx4 v[162:163], off
	v_lshl_add_u64 v[162:163], v[206:207], 0, s[36:37]
	s_mov_b32 m0, s73
	s_nop 0
	global_load_lds_dwordx4 v[162:163], off
	ds_read_b128 v[190:193], v172 offset:49152
	ds_read_b128 v[194:197], v172 offset:50176
	ds_read_b128 v[198:201], v172 offset:51200
	ds_read_b128 v[210:213], v172 offset:52224
	ds_read_b128 v[214:217], v172 offset:53248
	ds_read_b128 v[218:221], v172 offset:54272
	ds_read_b128 v[222:225], v172 offset:55296
	ds_read_b128 v[226:229], v172 offset:56320
	s_waitcnt vmcnt(8)
	s_waitcnt lgkmcnt(0)
	s_barrier
	s_setprio 1
	s_waitcnt lgkmcnt(0)
	v_mfma_f32_16x16x32_bf16 v[62:65], v[98:101], v[190:193], v[62:65]
	v_mfma_f32_16x16x32_bf16 v[58:61], v[106:109], v[190:193], v[58:61]
	v_mfma_f32_16x16x32_bf16 v[54:57], v[98:101], v[198:201], v[54:57]
	v_mfma_f32_16x16x32_bf16 v[46:49], v[106:109], v[198:201], v[46:49]
	v_mfma_f32_16x16x32_bf16 v[30:33], v[98:101], v[214:217], v[30:33]
	v_mfma_f32_16x16x32_bf16 v[26:29], v[106:109], v[214:217], v[26:29]
	v_mfma_f32_16x16x32_bf16 v[22:25], v[98:101], v[222:225], v[22:25]
	v_mfma_f32_16x16x32_bf16 v[14:17], v[106:109], v[222:225], v[14:17]
	v_mfma_f32_16x16x32_bf16 v[62:65], v[102:105], v[194:197], v[62:65]
	v_mfma_f32_16x16x32_bf16 v[58:61], v[110:113], v[194:197], v[58:61]
	v_mfma_f32_16x16x32_bf16 v[54:57], v[102:105], v[210:213], v[54:57]
	v_mfma_f32_16x16x32_bf16 v[46:49], v[110:113], v[210:213], v[46:49]
	v_mfma_f32_16x16x32_bf16 v[30:33], v[102:105], v[218:221], v[30:33]
	v_mfma_f32_16x16x32_bf16 v[26:29], v[110:113], v[218:221], v[26:29]
	v_mfma_f32_16x16x32_bf16 v[22:25], v[102:105], v[226:229], v[22:25]
	v_mfma_f32_16x16x32_bf16 v[14:17], v[110:113], v[226:229], v[14:17]
	s_setprio 0
	s_setprio 1
	v_mfma_f32_16x16x32_bf16 v[50:53], v[174:177], v[190:193], v[50:53]
	v_mfma_f32_16x16x32_bf16 v[42:45], v[182:185], v[190:193], v[42:45]
	v_mfma_f32_16x16x32_bf16 v[38:41], v[174:177], v[198:201], v[38:41]
	v_mfma_f32_16x16x32_bf16 v[34:37], v[182:185], v[198:201], v[34:37]
	v_mfma_f32_16x16x32_bf16 v[18:21], v[174:177], v[214:217], v[18:21]
	v_mfma_f32_16x16x32_bf16 v[10:13], v[182:185], v[214:217], v[10:13]
	v_mfma_f32_16x16x32_bf16 v[6:9], v[174:177], v[222:225], v[6:9]
	v_mfma_f32_16x16x32_bf16 v[2:5], v[182:185], v[222:225], v[2:5]
	v_mfma_f32_16x16x32_bf16 v[50:53], v[178:181], v[194:197], v[50:53]
	v_mfma_f32_16x16x32_bf16 v[42:45], v[186:189], v[194:197], v[42:45]
	v_mfma_f32_16x16x32_bf16 v[38:41], v[178:181], v[210:213], v[38:41]
	v_mfma_f32_16x16x32_bf16 v[34:37], v[186:189], v[210:213], v[34:37]
	v_mfma_f32_16x16x32_bf16 v[18:21], v[178:181], v[218:221], v[18:21]
	v_mfma_f32_16x16x32_bf16 v[10:13], v[186:189], v[218:221], v[10:13]
	v_mfma_f32_16x16x32_bf16 v[6:9], v[178:181], v[226:229], v[6:9]
	v_mfma_f32_16x16x32_bf16 v[2:5], v[186:189], v[226:229], v[2:5]
	s_setprio 0
	s_barrier
	s_add_i32 s17, s17, 2
	s_add_u32 s82, s82, 0x100
	s_addc_u32 s83, s83, 0
	s_add_u32 vcc_hi, vcc_hi, 0x100
	s_addc_u32 s27, s27, 0
	s_cmp_gt_u32 s17, 13
	s_cbranch_scc0 .LBB0_1912
	s_and_b64 vcc, exec, s[2:3]
	s_cbranch_vccz .LBB0_1915
	s_barrier

; #define PG8_STAGE(bufoff, gbase, voff) do { _Pragma("unroll") for (int _i = 0; _i < 2; ++_i) \
;         __builtin_amdgcn_global_load_lds((const unsigned*)((const char*)(gbase) + (voff)[_i]), (LAS unsigned*)(lds + (bufoff) + ldsw + _i * 8192), 16, 0, 0); } while (0)
; #define PG8_LDA(dst, b, h) do { _Pragma("unroll") for (int m = 0; m < 4; ++m) _Pragma("unroll") for (int k = 0; k < 2; ++k) dst[m][k] = *(const LAS bf16x8*)(lds + PG8_SA(b, h) + aoff + m * 2048 + k * 1024); } while (0)
; #define PG8_LDB(dst, b, h) do { _Pragma("unroll") for (int n = 0; n < 2; ++n) _Pragma("unroll") for (int k = 0; k < 2; ++k) dst[n][k] = *(const LAS bf16x8*)(lds + PG8_SB(b, h) + boff + n * 2048 + k * 1024); } while (0)
; #define PG8_MMA(ai, bj, At, Bt) do { __builtin_amdgcn_s_setprio(1); _Pragma("unroll") for (int m = 0; m < 4; ++m) _Pragma("unroll") for (int n = 0; n < 2; ++n) _Pragma("unroll") for (int k = 0; k < 2; ++k) \
;         acc[ai][bj][m][n] = __builtin_amdgcn_mfma_f32_16x16x32_bf16(Bt[n][k], At[m][k], acc[ai][bj][m][n], 0, 0, 0); __builtin_amdgcn_s_setprio(0); } while (0)
; #define PG8_WAIT_V(n) asm volatile("s_waitcnt vmcnt(" #n ")" ::: "memory")
; #define PG8_WAIT_L(n) asm volatile("s_waitcnt lgkmcnt(" #n ")" ::: "memory")
; #define PG8_BAR __builtin_amdgcn_s_barrier()
; #define PG8_SCHED __builtin_amdgcn_sched_barrier(0)
; template <class Epi>
; __device__ __forceinline__ void gemm_phase(LAS unsigned char* lds, const int tid, const Gemm g, const StaticOrder& S, const Epi& E) {
;     ...
;         for (int t = 0; t < nt; t += 2) {
;             const bool last = (t == nt - 2);
;             const char* a1 = cA + (size_t)(t + 1) * kstep;
;             const char* a2 = last ? nA : cA + (size_t)(t + 2) * kstep; const char* b2 = last ? nB : cB + (size_t)(t + 2) * kstep;
;             const char* a3 = a2 + kstep; const char* b3 = b2 + kstep;
;             PG8_LDB(B0, 0, 0); PG8_LDB(B1, 0, 1); PG8_SCHED; PG8_LDA(At, 0, 0); PG8_STAGE(PG8_SA(1, 1), a1 + hstepA, voffA);
;             PG8_WAIT_V(8); PG8_WAIT_L(0); PG8_BAR; PG8_MMA(0, 0, At, B0); PG8_MMA(0, 1, At, B1); PG8_BAR; PG8_SCHED;
;             PG8_LDA(At, 0, 1); PG8_STAGE(PG8_SB(0, 0), b2, voffB); PG8_STAGE(PG8_SB(0, 1), b2 + hstepB, voffB); PG8_STAGE(PG8_SA(0, 0), a2, voffA);
;             PG8_WAIT_V(8); PG8_WAIT_L(0); PG8_BAR; PG8_MMA(1, 0, At, B0); PG8_MMA(1, 1, At, B1); PG8_BAR; PG8_SCHED;
.LBB0_2193:
	s_add_u32 s70, s30, 0x100
	s_addc_u32 s71, s31, 0
	s_add_i32 s76, 0, 0x10000
	s_cmp_eq_u32 vcc_hi, 40
	s_cselect_b32 s75, s1, s71
	s_cselect_b32 s74, s0, s70
	s_cselect_b32 s73, s69, vcc_lo
	s_cselect_b32 s72, s68, s28
	s_add_i32 s2, 0, 0x14000
	v_add_u32_e32 v154, s76, v179
	v_add_u32_e32 v162, s2, v179
	ds_read_b128 v[130:133], v154
	ds_read_b128 v[134:137], v154 offset:1024
	ds_read_b128 v[138:141], v154 offset:2048
	ds_read_b128 v[154:157], v154 offset:3072
	ds_read_b128 v[158:161], v162
	ds_read_b128 v[170:173], v162 offset:1024
	ds_read_b128 v[174:177], v162 offset:2048
	ds_read_b128 v[184:187], v162 offset:3072
	s_add_i32 m0, s5, 0xc000
	s_nop 0
	global_load_lds_dwordx4 v150, s[30:31]
	s_add_i32 m0, s5, 0xe000
	s_nop 0
	global_load_lds_dwordx4 v152, s[30:31]
	ds_read_b128 v[188:191], v181
	ds_read_b128 v[192:195], v181 offset:1024
	ds_read_b128 v[196:199], v181 offset:2048
	ds_read_b128 v[200:203], v181 offset:3072
	ds_read_b128 v[212:215], v181 offset:4096
	ds_read_b128 v[216:219], v181 offset:5120
	ds_read_b128 v[220:223], v181 offset:6144
	ds_read_b128 v[224:227], v181 offset:7168
	s_waitcnt vmcnt(8)
	s_waitcnt lgkmcnt(0)
	s_barrier
	s_setprio 1
	s_waitcnt lgkmcnt(0)
	v_mfma_f32_16x16x32_bf16 v[126:129], v[130:133], v[188:191], v[126:129]
	v_mfma_f32_16x16x32_bf16 v[122:125], v[138:141], v[188:191], v[122:125]
	v_mfma_f32_16x16x32_bf16 v[110:113], v[130:133], v[196:199], v[110:113]
	v_mfma_f32_16x16x32_bf16 v[106:109], v[138:141], v[196:199], v[106:109]
	v_mfma_f32_16x16x32_bf16 v[94:97], v[130:133], v[212:215], v[94:97]
	v_mfma_f32_16x16x32_bf16 v[90:93], v[138:141], v[212:215], v[90:93]
	v_mfma_f32_16x16x32_bf16 v[78:81], v[130:133], v[220:223], v[78:81]
	v_mfma_f32_16x16x32_bf16 v[74:77], v[138:141], v[220:223], v[74:77]
	v_mfma_f32_16x16x32_bf16 v[126:129], v[134:137], v[192:195], v[126:129]
	v_mfma_f32_16x16x32_bf16 v[122:125], v[154:157], v[192:195], v[122:125]
	v_mfma_f32_16x16x32_bf16 v[110:113], v[134:137], v[200:203], v[110:113]
	v_mfma_f32_16x16x32_bf16 v[106:109], v[154:157], v[200:203], v[106:109]
	v_mfma_f32_16x16x32_bf16 v[94:97], v[134:137], v[216:219], v[94:97]
	v_mfma_f32_16x16x32_bf16 v[90:93], v[154:157], v[216:219], v[90:93]
	v_mfma_f32_16x16x32_bf16 v[78:81], v[134:137], v[224:227], v[78:81]
	v_mfma_f32_16x16x32_bf16 v[74:77], v[154:157], v[224:227], v[74:77]
	s_setprio 0
	s_setprio 1
	v_mfma_f32_16x16x32_bf16 v[118:121], v[158:161], v[188:191], v[118:121]
	v_mfma_f32_16x16x32_bf16 v[114:117], v[174:177], v[188:191], v[114:117]
	v_mfma_f32_16x16x32_bf16 v[102:105], v[158:161], v[196:199], v[102:105]
	v_mfma_f32_16x16x32_bf16 v[98:101], v[174:177], v[196:199], v[98:101]
	v_mfma_f32_16x16x32_bf16 v[86:89], v[158:161], v[212:215], v[86:89]
	v_mfma_f32_16x16x32_bf16 v[82:85], v[174:177], v[212:215], v[82:85]
	v_mfma_f32_16x16x32_bf16 v[70:73], v[158:161], v[220:223], v[70:73]
	v_mfma_f32_16x16x32_bf16 v[66:69], v[174:177], v[220:223], v[66:69]
	v_mfma_f32_16x16x32_bf16 v[118:121], v[170:173], v[192:195], v[118:121]
	v_mfma_f32_16x16x32_bf16 v[114:117], v[184:187], v[192:195], v[114:117]
	v_mfma_f32_16x16x32_bf16 v[102:105], v[170:173], v[200:203], v[102:105]
	v_mfma_f32_16x16x32_bf16 v[98:101], v[184:187], v[200:203], v[98:101]
	v_mfma_f32_16x16x32_bf16 v[86:89], v[170:173], v[216:219], v[86:89]
	v_mfma_f32_16x16x32_bf16 v[82:85], v[184:187], v[216:219], v[82:85]
	v_mfma_f32_16x16x32_bf16 v[70:73], v[170:173], v[224:227], v[70:73]
	v_mfma_f32_16x16x32_bf16 v[66:69], v[184:187], v[224:227], v[66:69]
	s_setprio 0
	s_barrier
	s_add_i32 s3, s76, s4
	v_lshl_add_u64 v[162:163], s[72:73], 0, v[0:1]
	s_mov_b32 m0, s3
	s_nop 0
	global_load_lds_dwordx4 v[162:163], off
	s_add_i32 m0, s3, 0x2000
	s_add_u32 s30, s72, 0xb0000
	v_lshl_add_u64 v[164:165], s[72:73], 0, v[148:149]
	s_addc_u32 s31, s73, 0
	s_add_i32 s2, s2, s4
	global_load_lds_dwordx4 v[164:165], off
	s_mov_b32 m0, s2
	v_lshl_add_u64 v[228:229], s[74:75], 0, v[144:145]
	global_load_lds_dwordx4 v0, s[30:31]
	s_add_i32 m0, s2, 0x2000
	s_nop 0
	global_load_lds_dwordx4 v148, s[30:31]
	v_lshl_add_u64 v[206:207], s[74:75], 0, v[142:143]
	s_mov_b32 m0, s5
	s_nop 0
	global_load_lds_dwordx4 v[206:207], off
	s_mov_b32 m0, s6
	s_nop 0
	global_load_lds_dwordx4 v[228:229], off
	ds_read_b128 v[188:191], v181 offset:16384
	ds_read_b128 v[192:195], v181 offset:17408
	ds_read_b128 v[196:199], v181 offset:18432
	ds_read_b128 v[200:203], v181 offset:19456
	ds_read_b128 v[212:215], v181 offset:20480
	ds_read_b128 v[216:219], v181 offset:21504
	ds_read_b128 v[220:223], v181 offset:22528
	ds_read_b128 v[224:227], v181 offset:23552
	s_waitcnt vmcnt(8)
	s_waitcnt lgkmcnt(0)
	s_barrier
; #define PG8_STAGE(bufoff, gbase, voff) do { _Pragma("unroll") for (int _i = 0; _i < 2; ++_i) \
;         __builtin_amdgcn_global_load_lds((const unsigned*)((const char*)(gbase) + (voff)[_i]), (LAS unsigned*)(lds + (bufoff) + ldsw + _i * 8192), 16, 0, 0); } while (0)
; #define PG8_LDA(dst, b, h) do { _Pragma("unroll") for (int m = 0; m < 4; ++m) _Pragma("unroll") for (int k = 0; k < 2; ++k) dst[m][k] = *(const LAS bf16x8*)(lds + PG8_SA(b, h) + aoff + m * 2048 + k * 1024); } while (0)
; #define PG8_LDB(dst, b, h) do { _Pragma("unroll") for (int n = 0; n < 2; ++n) _Pragma("unroll") for (int k = 0; k < 2; ++k) dst[n][k] = *(const LAS bf16x8*)(lds + PG8_SB(b, h) + boff + n * 2048 + k * 1024); } while (0)
; #define PG8_MMA(ai, bj, At, Bt) do { __builtin_amdgcn_s_setprio(1); _Pragma("unroll") for (int m = 0; m < 4; ++m) _Pragma("unroll") for (int n = 0; n < 2; ++n) _Pragma("unroll") for (int k = 0; k < 2; ++k) \
;         acc[ai][bj][m][n] = __builtin_amdgcn_mfma_f32_16x16x32_bf16(Bt[n][k], At[m][k], acc[ai][bj][m][n], 0, 0, 0); __builtin_amdgcn_s_setprio(0); } while (0)
; #define PG8_WAIT_V(n) asm volatile("s_waitcnt vmcnt(" #n ")" ::: "memory")
; #define PG8_WAIT_L(n) asm volatile("s_waitcnt lgkmcnt(" #n ")" ::: "memory")
; #define PG8_BAR __builtin_amdgcn_s_barrier()
; #define PG8_SCHED __builtin_amdgcn_sched_barrier(0)
; template <class Epi>
; __device__ __forceinline__ void gemm_phase(LAS unsigned char* lds, const int tid, const Gemm g, const StaticOrder& S, const Epi& E) {
;     ...
;             PG8_WAIT_V(8); PG8_WAIT_L(0); PG8_BAR; PG8_MMA(1, 0, At, B0); PG8_MMA(1, 1, At, B1); PG8_BAR; PG8_SCHED;
;             PG8_LDB(B0, 1, 0); PG8_LDB(B1, 1, 1); PG8_SCHED; PG8_LDA(At, 1, 0); PG8_STAGE(PG8_SA(0, 1), a2 + hstepA, voffA);
;             PG8_WAIT_V(8); PG8_WAIT_L(0); PG8_BAR; PG8_MMA(0, 0, At, B0); PG8_MMA(0, 1, At, B1); PG8_BAR; PG8_SCHED;
	s_setprio 1
	s_waitcnt lgkmcnt(0)
	v_mfma_f32_16x16x32_bf16 v[62:65], v[130:133], v[188:191], v[62:65]
	v_mfma_f32_16x16x32_bf16 v[58:61], v[138:141], v[188:191], v[58:61]
	v_mfma_f32_16x16x32_bf16 v[46:49], v[130:133], v[196:199], v[46:49]
	v_mfma_f32_16x16x32_bf16 v[42:45], v[138:141], v[196:199], v[42:45]
	v_mfma_f32_16x16x32_bf16 v[30:33], v[130:133], v[212:215], v[30:33]
	v_mfma_f32_16x16x32_bf16 v[26:29], v[138:141], v[212:215], v[26:29]
	v_mfma_f32_16x16x32_bf16 v[14:17], v[130:133], v[220:223], v[14:17]
	v_mfma_f32_16x16x32_bf16 v[10:13], v[138:141], v[220:223], v[10:13]
	v_mfma_f32_16x16x32_bf16 v[62:65], v[134:137], v[192:195], v[62:65]
	v_mfma_f32_16x16x32_bf16 v[58:61], v[154:157], v[192:195], v[58:61]
	v_mfma_f32_16x16x32_bf16 v[46:49], v[134:137], v[200:203], v[46:49]
	v_mfma_f32_16x16x32_bf16 v[42:45], v[154:157], v[200:203], v[42:45]
	v_mfma_f32_16x16x32_bf16 v[30:33], v[134:137], v[216:219], v[30:33]
	v_mfma_f32_16x16x32_bf16 v[26:29], v[154:157], v[216:219], v[26:29]
	v_mfma_f32_16x16x32_bf16 v[14:17], v[134:137], v[224:227], v[14:17]
	v_mfma_f32_16x16x32_bf16 v[10:13], v[154:157], v[224:227], v[10:13]
	s_setprio 0
	s_setprio 1
	v_mfma_f32_16x16x32_bf16 v[54:57], v[158:161], v[188:191], v[54:57]
	v_mfma_f32_16x16x32_bf16 v[50:53], v[174:177], v[188:191], v[50:53]
	v_mfma_f32_16x16x32_bf16 v[38:41], v[158:161], v[196:199], v[38:41]
	v_mfma_f32_16x16x32_bf16 v[34:37], v[174:177], v[196:199], v[34:37]
	v_mfma_f32_16x16x32_bf16 v[22:25], v[158:161], v[212:215], v[22:25]
	v_mfma_f32_16x16x32_bf16 v[18:21], v[174:177], v[212:215], v[18:21]
	v_mfma_f32_16x16x32_bf16 v[6:9], v[158:161], v[220:223], v[6:9]
	v_mfma_f32_16x16x32_bf16 v[2:5], v[174:177], v[220:223], v[2:5]
	v_mfma_f32_16x16x32_bf16 v[54:57], v[170:173], v[192:195], v[54:57]
	v_mfma_f32_16x16x32_bf16 v[50:53], v[184:187], v[192:195], v[50:53]
	v_mfma_f32_16x16x32_bf16 v[38:41], v[170:173], v[200:203], v[38:41]
	v_mfma_f32_16x16x32_bf16 v[34:37], v[184:187], v[200:203], v[34:37]
	v_mfma_f32_16x16x32_bf16 v[22:25], v[170:173], v[216:219], v[22:25]
	v_mfma_f32_16x16x32_bf16 v[18:21], v[184:187], v[216:219], v[18:21]
	v_mfma_f32_16x16x32_bf16 v[6:9], v[170:173], v[224:227], v[6:9]
	v_mfma_f32_16x16x32_bf16 v[2:5], v[184:187], v[224:227], v[2:5]
	s_setprio 0
	s_barrier
	s_add_i32 s2, 0, 0x18000
	s_add_i32 s3, 0, 0x1c000
	v_add_u32_e32 v154, s2, v179
	v_add_u32_e32 v183, s3, v179
	ds_read_b128 v[130:133], v154
	ds_read_b128 v[134:137], v154 offset:1024
	ds_read_b128 v[138:141], v154 offset:2048
	ds_read_b128 v[154:157], v154 offset:3072
	ds_read_b128 v[158:161], v183
	ds_read_b128 v[170:173], v183 offset:1024
	ds_read_b128 v[174:177], v183 offset:2048
	ds_read_b128 v[184:187], v183 offset:3072
	s_add_u32 s30, s74, 0x160000
	s_addc_u32 s31, s75, 0
	s_mov_b32 m0, s7
	s_nop 0
	global_load_lds_dwordx4 v142, s[30:31]
	s_mov_b32 m0, s77
	s_nop 0
	global_load_lds_dwordx4 v144, s[30:31]
	ds_read_b128 v[188:191], v181 offset:32768
	ds_read_b128 v[192:195], v181 offset:33792
	ds_read_b128 v[196:199], v181 offset:34816
	ds_read_b128 v[200:203], v181 offset:35840
	ds_read_b128 v[212:215], v181 offset:36864
	ds_read_b128 v[216:219], v181 offset:37888
	ds_read_b128 v[220:223], v181 offset:38912
	ds_read_b128 v[224:227], v181 offset:39936
	s_waitcnt vmcnt(8)
	s_waitcnt lgkmcnt(0)
	s_barrier
	s_setprio 1
	s_waitcnt lgkmcnt(0)
	v_mfma_f32_16x16x32_bf16 v[126:129], v[130:133], v[188:191], v[126:129]
	v_mfma_f32_16x16x32_bf16 v[122:125], v[138:141], v[188:191], v[122:125]
	v_mfma_f32_16x16x32_bf16 v[110:113], v[130:133], v[196:199], v[110:113]
	v_mfma_f32_16x16x32_bf16 v[106:109], v[138:141], v[196:199], v[106:109]
	v_mfma_f32_16x16x32_bf16 v[94:97], v[130:133], v[212:215], v[94:97]
	v_mfma_f32_16x16x32_bf16 v[90:93], v[138:141], v[212:215], v[90:93]
	v_mfma_f32_16x16x32_bf16 v[78:81], v[130:133], v[220:223], v[78:81]
	v_mfma_f32_16x16x32_bf16 v[74:77], v[138:141], v[220:223], v[74:77]
	v_mfma_f32_16x16x32_bf16 v[126:129], v[134:137], v[192:195], v[126:129]
	v_mfma_f32_16x16x32_bf16 v[122:125], v[154:157], v[192:195], v[122:125]
	v_mfma_f32_16x16x32_bf16 v[110:113], v[134:137], v[200:203], v[110:113]
	v_mfma_f32_16x16x32_bf16 v[106:109], v[154:157], v[200:203], v[106:109]
	v_mfma_f32_16x16x32_bf16 v[94:97], v[134:137], v[216:219], v[94:97]
	v_mfma_f32_16x16x32_bf16 v[90:93], v[154:157], v[216:219], v[90:93]
	v_mfma_f32_16x16x32_bf16 v[78:81], v[134:137], v[224:227], v[78:81]
	v_mfma_f32_16x16x32_bf16 v[74:77], v[154:157], v[224:227], v[74:77]
	s_setprio 0
	s_setprio 1
	v_mfma_f32_16x16x32_bf16 v[118:121], v[158:161], v[188:191], v[118:121]
	v_mfma_f32_16x16x32_bf16 v[114:117], v[174:177], v[188:191], v[114:117]
	v_mfma_f32_16x16x32_bf16 v[102:105], v[158:161], v[196:199], v[102:105]
	v_mfma_f32_16x16x32_bf16 v[98:101], v[174:177], v[196:199], v[98:101]
	v_mfma_f32_16x16x32_bf16 v[86:89], v[158:161], v[212:215], v[86:89]
	v_mfma_f32_16x16x32_bf16 v[82:85], v[174:177], v[212:215], v[82:85]
	v_mfma_f32_16x16x32_bf16 v[70:73], v[158:161], v[220:223], v[70:73]
	v_mfma_f32_16x16x32_bf16 v[66:69], v[174:177], v[220:223], v[66:69]
	v_mfma_f32_16x16x32_bf16 v[118:121], v[170:173], v[192:195], v[118:121]
	v_mfma_f32_16x16x32_bf16 v[114:117], v[184:187], v[192:195], v[114:117]
	v_mfma_f32_16x16x32_bf16 v[102:105], v[170:173], v[200:203], v[102:105]
	v_mfma_f32_16x16x32_bf16 v[98:101], v[184:187], v[200:203], v[98:101]
	v_mfma_f32_16x16x32_bf16 v[86:89], v[170:173], v[216:219], v[86:89]
	v_mfma_f32_16x16x32_bf16 v[82:85], v[184:187], v[216:219], v[82:85]
	v_mfma_f32_16x16x32_bf16 v[70:73], v[170:173], v[224:227], v[70:73]
	v_mfma_f32_16x16x32_bf16 v[66:69], v[184:187], v[224:227], v[66:69]
	s_setprio 0
	s_barrier
; #define PG8_STAGE(bufoff, gbase, voff) do { _Pragma("unroll") for (int _i = 0; _i < 2; ++_i) \
;         __builtin_amdgcn_global_load_lds((const unsigned*)((const char*)(gbase) + (voff)[_i]), (LAS unsigned*)(lds + (bufoff) + ldsw + _i * 8192), 16, 0, 0); } while (0)
; #define PG8_LDA(dst, b, h) do { _Pragma("unroll") for (int m = 0; m < 4; ++m) _Pragma("unroll") for (int k = 0; k < 2; ++k) dst[m][k] = *(const LAS bf16x8*)(lds + PG8_SA(b, h) + aoff + m * 2048 + k * 1024); } while (0)
; #define PG8_MMA(ai, bj, At, Bt) do { __builtin_amdgcn_s_setprio(1); _Pragma("unroll") for (int m = 0; m < 4; ++m) _Pragma("unroll") for (int n = 0; n < 2; ++n) _Pragma("unroll") for (int k = 0; k < 2; ++k) \
;         acc[ai][bj][m][n] = __builtin_amdgcn_mfma_f32_16x16x32_bf16(Bt[n][k], At[m][k], acc[ai][bj][m][n], 0, 0, 0); __builtin_amdgcn_s_setprio(0); } while (0)
; #define PG8_WAIT_V(n) asm volatile("s_waitcnt vmcnt(" #n ")" ::: "memory")
; #define PG8_WAIT_L(n) asm volatile("s_waitcnt lgkmcnt(" #n ")" ::: "memory")
; #define PG8_BAR __builtin_amdgcn_s_barrier()
; #define PG8_SCHED __builtin_amdgcn_sched_barrier(0)
; template <class Epi>
; __device__ __forceinline__ void gemm_phase(LAS unsigned char* lds, const int tid, const Gemm g, const StaticOrder& S, const Epi& E) {
;     ...
;             PG8_LDA(At, 1, 1); PG8_STAGE(PG8_SB(1, 0), b3, voffB); PG8_STAGE(PG8_SB(1, 1), b3 + hstepB, voffB); PG8_STAGE(PG8_SA(1, 0), a3, voffA);
;             PG8_WAIT_V(8); PG8_WAIT_L(0); PG8_BAR; PG8_MMA(1, 0, At, B0); PG8_MMA(1, 1, At, B1); PG8_BAR; PG8_SCHED;
;         }
;         if (wr == 0) PG8_BAR;
	s_add_i32 s2, s2, s4
	v_lshl_add_u64 v[162:163], v[162:163], 0, s[36:37]
	s_mov_b32 m0, s2
	s_nop 0
	global_load_lds_dwordx4 v[162:163], off
	s_add_i32 m0, s2, 0x2000
	s_add_u32 s30, s72, 0xb0080
	v_lshl_add_u64 v[162:163], v[164:165], 0, s[36:37]
	s_addc_u32 s31, s73, 0
	s_add_i32 s2, s3, s4
	global_load_lds_dwordx4 v[162:163], off
	s_mov_b32 m0, s2
	s_nop 0
	global_load_lds_dwordx4 v0, s[30:31]
	s_add_i32 m0, s2, 0x2000
	s_nop 0
	global_load_lds_dwordx4 v148, s[30:31]
	v_lshl_add_u64 v[162:163], v[206:207], 0, s[36:37]
	s_mov_b32 m0, s83
	s_nop 0
	global_load_lds_dwordx4 v[162:163], off
	v_lshl_add_u64 v[162:163], v[228:229], 0, s[36:37]
	s_mov_b32 m0, s88
	s_nop 0
	global_load_lds_dwordx4 v[162:163], off
	ds_read_b128 v[188:191], v181 offset:49152
	ds_read_b128 v[192:195], v181 offset:50176
	ds_read_b128 v[196:199], v181 offset:51200
	ds_read_b128 v[200:203], v181 offset:52224
	ds_read_b128 v[212:215], v181 offset:53248
	ds_read_b128 v[216:219], v181 offset:54272
	ds_read_b128 v[220:223], v181 offset:55296
	ds_read_b128 v[224:227], v181 offset:56320
	s_waitcnt vmcnt(8)
	s_waitcnt lgkmcnt(0)
	s_barrier
	s_setprio 1
	s_waitcnt lgkmcnt(0)
	v_mfma_f32_16x16x32_bf16 v[62:65], v[130:133], v[188:191], v[62:65]
	v_mfma_f32_16x16x32_bf16 v[58:61], v[138:141], v[188:191], v[58:61]
	v_mfma_f32_16x16x32_bf16 v[46:49], v[130:133], v[196:199], v[46:49]
	v_mfma_f32_16x16x32_bf16 v[42:45], v[138:141], v[196:199], v[42:45]
	v_mfma_f32_16x16x32_bf16 v[30:33], v[130:133], v[212:215], v[30:33]
	v_mfma_f32_16x16x32_bf16 v[26:29], v[138:141], v[212:215], v[26:29]
	v_mfma_f32_16x16x32_bf16 v[14:17], v[130:133], v[220:223], v[14:17]
	v_mfma_f32_16x16x32_bf16 v[10:13], v[138:141], v[220:223], v[10:13]
	v_mfma_f32_16x16x32_bf16 v[62:65], v[134:137], v[192:195], v[62:65]
	v_mfma_f32_16x16x32_bf16 v[58:61], v[154:157], v[192:195], v[58:61]
	v_mfma_f32_16x16x32_bf16 v[46:49], v[134:137], v[200:203], v[46:49]
	v_mfma_f32_16x16x32_bf16 v[42:45], v[154:157], v[200:203], v[42:45]
	v_mfma_f32_16x16x32_bf16 v[30:33], v[134:137], v[216:219], v[30:33]
	v_mfma_f32_16x16x32_bf16 v[26:29], v[154:157], v[216:219], v[26:29]
	v_mfma_f32_16x16x32_bf16 v[14:17], v[134:137], v[224:227], v[14:17]
	v_mfma_f32_16x16x32_bf16 v[10:13], v[154:157], v[224:227], v[10:13]
	s_setprio 0
	s_setprio 1
	v_mfma_f32_16x16x32_bf16 v[54:57], v[158:161], v[188:191], v[54:57]
	v_mfma_f32_16x16x32_bf16 v[50:53], v[174:177], v[188:191], v[50:53]
	v_mfma_f32_16x16x32_bf16 v[38:41], v[158:161], v[196:199], v[38:41]
	v_mfma_f32_16x16x32_bf16 v[34:37], v[174:177], v[196:199], v[34:37]
	v_mfma_f32_16x16x32_bf16 v[22:25], v[158:161], v[212:215], v[22:25]
	v_mfma_f32_16x16x32_bf16 v[18:21], v[174:177], v[212:215], v[18:21]
	v_mfma_f32_16x16x32_bf16 v[6:9], v[158:161], v[220:223], v[6:9]
	v_mfma_f32_16x16x32_bf16 v[2:5], v[174:177], v[220:223], v[2:5]
	v_mfma_f32_16x16x32_bf16 v[54:57], v[170:173], v[192:195], v[54:57]
	v_mfma_f32_16x16x32_bf16 v[50:53], v[184:187], v[192:195], v[50:53]
	v_mfma_f32_16x16x32_bf16 v[38:41], v[170:173], v[200:203], v[38:41]
	v_mfma_f32_16x16x32_bf16 v[34:37], v[184:187], v[200:203], v[34:37]
	v_mfma_f32_16x16x32_bf16 v[22:25], v[170:173], v[216:219], v[22:25]
	v_mfma_f32_16x16x32_bf16 v[18:21], v[184:187], v[216:219], v[18:21]
	v_mfma_f32_16x16x32_bf16 v[6:9], v[170:173], v[224:227], v[6:9]
	v_mfma_f32_16x16x32_bf16 v[2:5], v[184:187], v[224:227], v[2:5]
	s_setprio 0
	s_barrier
	s_add_i32 vcc_hi, vcc_hi, 2
	s_add_u32 s28, s28, 0x100
	s_addc_u32 vcc_lo, vcc_lo, 0
	s_cmp_gt_u32 vcc_hi, 41
	s_mov_b64 s[30:31], s[70:71]
	s_cbranch_scc0 .LBB0_2193
	s_and_b64 vcc, exec, s[26:27]
	s_cbranch_vccz .LBB0_2196
	s_barrier

; #define PG8_STAGE(bufoff, gbase, voff) do { _Pragma("unroll") for (int _i = 0; _i < 2; ++_i) \
;         __builtin_amdgcn_global_load_lds((const unsigned*)((const char*)(gbase) + (voff)[_i]), (LAS unsigned*)(lds + (bufoff) + ldsw + _i * 8192), 16, 0, 0); } while (0)
; #define PG8_LDA(dst, b, h) do { _Pragma("unroll") for (int m = 0; m < 4; ++m) _Pragma("unroll") for (int k = 0; k < 2; ++k) dst[m][k] = *(const LAS bf16x8*)(lds + PG8_SA(b, h) + aoff + m * 2048 + k * 1024); } while (0)
; #define PG8_LDB(dst, b, h) do { _Pragma("unroll") for (int n = 0; n < 2; ++n) _Pragma("unroll") for (int k = 0; k < 2; ++k) dst[n][k] = *(const LAS bf16x8*)(lds + PG8_SB(b, h) + boff + n * 2048 + k * 1024); } while (0)
; #define PG8_MMA(ai, bj, At, Bt) do { __builtin_amdgcn_s_setprio(1); _Pragma("unroll") for (int m = 0; m < 4; ++m) _Pragma("unroll") for (int n = 0; n < 2; ++n) _Pragma("unroll") for (int k = 0; k < 2; ++k) \
;         acc[ai][bj][m][n] = __builtin_amdgcn_mfma_f32_16x16x32_bf16(Bt[n][k], At[m][k], acc[ai][bj][m][n], 0, 0, 0); __builtin_amdgcn_s_setprio(0); } while (0)
; #define PG8_WAIT_V(n) asm volatile("s_waitcnt vmcnt(" #n ")" ::: "memory")
; #define PG8_WAIT_L(n) asm volatile("s_waitcnt lgkmcnt(" #n ")" ::: "memory")
; #define PG8_BAR __builtin_amdgcn_s_barrier()
; #define PG8_SCHED __builtin_amdgcn_sched_barrier(0)
; template <class Epi>
; __device__ __forceinline__ void gemm_phase(LAS unsigned char* lds, const int tid, const Gemm g, const StaticOrder& S, const Epi& E) {
;     ...
;         for (int t = 0; t < nt; t += 2) {
;             const bool last = (t == nt - 2);
;             const char* a1 = cA + (size_t)(t + 1) * kstep;
;             const char* a2 = last ? nA : cA + (size_t)(t + 2) * kstep; const char* b2 = last ? nB : cB + (size_t)(t + 2) * kstep;
;             const char* a3 = a2 + kstep; const char* b3 = b2 + kstep;
;             PG8_LDB(B0, 0, 0); PG8_LDB(B1, 0, 1); PG8_SCHED; PG8_LDA(At, 0, 0); PG8_STAGE(PG8_SA(1, 1), a1 + hstepA, voffA);
;             PG8_WAIT_V(8); PG8_WAIT_L(0); PG8_BAR; PG8_MMA(0, 0, At, B0); PG8_MMA(0, 1, At, B1); PG8_BAR; PG8_SCHED;
;             PG8_LDA(At, 0, 1); PG8_STAGE(PG8_SB(0, 0), b2, voffB); PG8_STAGE(PG8_SB(0, 1), b2 + hstepB, voffB); PG8_STAGE(PG8_SA(0, 0), a2, voffA);
;             PG8_WAIT_V(8); PG8_WAIT_L(0); PG8_BAR; PG8_MMA(1, 0, At, B0); PG8_MMA(1, 1, At, B1); PG8_BAR; PG8_SCHED;
.LBB0_2303:
	s_add_u32 s68, s66, 0x100
	s_addc_u32 s69, s67, 0
	s_add_i32 s76, 0, 0x10000
	s_cmp_eq_u32 s93, 40
	s_cselect_b32 s73, s1, s69
	s_cselect_b32 s72, s0, s68
	s_cselect_b32 s71, s31, s28
	s_cselect_b32 s70, s30, s11
	s_add_i32 vcc_lo, 0, 0x14000
	v_add_u32_e32 v70, s76, v212
	v_add_u32_e32 v162, vcc_lo, v212
	ds_read_b128 v[42:45], v70
	ds_read_b128 v[46:49], v70 offset:1024
	ds_read_b128 v[66:69], v70 offset:2048
	ds_read_b128 v[70:73], v70 offset:3072
	ds_read_b128 v[158:161], v162
	ds_read_b128 v[170:173], v162 offset:1024
	ds_read_b128 v[174:177], v162 offset:2048
	ds_read_b128 v[178:181], v162 offset:3072
	s_add_i32 m0, s5, 0xc000
	s_nop 0
	global_load_lds_dwordx4 v154, s[66:67]
	s_add_i32 m0, s5, 0xe000
	s_nop 0
	global_load_lds_dwordx4 v156, s[66:67]
	ds_read_b128 v[182:185], v214
	ds_read_b128 v[186:189], v214 offset:1024
	ds_read_b128 v[190:193], v214 offset:2048
	ds_read_b128 v[194:197], v214 offset:3072
	ds_read_b128 v[198:201], v214 offset:4096
	ds_read_b128 v[216:219], v214 offset:5120
	ds_read_b128 v[220:223], v214 offset:6144
	ds_read_b128 v[224:227], v214 offset:7168
	s_waitcnt vmcnt(8)
	s_waitcnt lgkmcnt(0)
	s_barrier
	s_setprio 1
	s_waitcnt lgkmcnt(0)
	v_mfma_f32_16x16x32_bf16 v[142:145], v[42:45], v[182:185], v[142:145]
	v_mfma_f32_16x16x32_bf16 v[138:141], v[66:69], v[182:185], v[138:141]
	v_mfma_f32_16x16x32_bf16 v[126:129], v[42:45], v[190:193], v[126:129]
	v_mfma_f32_16x16x32_bf16 v[122:125], v[66:69], v[190:193], v[122:125]
	v_mfma_f32_16x16x32_bf16 v[110:113], v[42:45], v[198:201], v[110:113]
	v_mfma_f32_16x16x32_bf16 v[106:109], v[66:69], v[198:201], v[106:109]
	v_mfma_f32_16x16x32_bf16 v[94:97], v[42:45], v[220:223], v[94:97]
	v_mfma_f32_16x16x32_bf16 v[90:93], v[66:69], v[220:223], v[90:93]
	v_mfma_f32_16x16x32_bf16 v[142:145], v[46:49], v[186:189], v[142:145]
	v_mfma_f32_16x16x32_bf16 v[138:141], v[70:73], v[186:189], v[138:141]
	v_mfma_f32_16x16x32_bf16 v[126:129], v[46:49], v[194:197], v[126:129]
	v_mfma_f32_16x16x32_bf16 v[122:125], v[70:73], v[194:197], v[122:125]
	v_mfma_f32_16x16x32_bf16 v[110:113], v[46:49], v[216:219], v[110:113]
	v_mfma_f32_16x16x32_bf16 v[106:109], v[70:73], v[216:219], v[106:109]
	v_mfma_f32_16x16x32_bf16 v[94:97], v[46:49], v[224:227], v[94:97]
	v_mfma_f32_16x16x32_bf16 v[90:93], v[70:73], v[224:227], v[90:93]
	s_setprio 0
	s_setprio 1
	v_mfma_f32_16x16x32_bf16 v[134:137], v[158:161], v[182:185], v[134:137]
	v_mfma_f32_16x16x32_bf16 v[130:133], v[174:177], v[182:185], v[130:133]
	v_mfma_f32_16x16x32_bf16 v[118:121], v[158:161], v[190:193], v[118:121]
	v_mfma_f32_16x16x32_bf16 v[114:117], v[174:177], v[190:193], v[114:117]
	v_mfma_f32_16x16x32_bf16 v[102:105], v[158:161], v[198:201], v[102:105]
	v_mfma_f32_16x16x32_bf16 v[98:101], v[174:177], v[198:201], v[98:101]
	v_mfma_f32_16x16x32_bf16 v[86:89], v[158:161], v[220:223], v[86:89]
	v_mfma_f32_16x16x32_bf16 v[82:85], v[174:177], v[220:223], v[82:85]
	v_mfma_f32_16x16x32_bf16 v[134:137], v[170:173], v[186:189], v[134:137]
	v_mfma_f32_16x16x32_bf16 v[130:133], v[178:181], v[186:189], v[130:133]
	v_mfma_f32_16x16x32_bf16 v[118:121], v[170:173], v[194:197], v[118:121]
	v_mfma_f32_16x16x32_bf16 v[114:117], v[178:181], v[194:197], v[114:117]
	v_mfma_f32_16x16x32_bf16 v[102:105], v[170:173], v[216:219], v[102:105]
	v_mfma_f32_16x16x32_bf16 v[98:101], v[178:181], v[216:219], v[98:101]
	v_mfma_f32_16x16x32_bf16 v[86:89], v[170:173], v[224:227], v[86:89]
	v_mfma_f32_16x16x32_bf16 v[82:85], v[178:181], v[224:227], v[82:85]
	s_setprio 0
	s_barrier
	s_add_i32 s66, s76, s4
	v_lshl_add_u64 v[162:163], s[70:71], 0, v[0:1]
	s_mov_b32 m0, s66
	s_nop 0
	global_load_lds_dwordx4 v[162:163], off
	s_add_i32 m0, s66, 0x2000
	s_add_u32 s66, s70, 0xb0000
	v_lshl_add_u64 v[164:165], s[70:71], 0, v[152:153]
	s_addc_u32 s67, s71, 0
	s_add_i32 s76, vcc_lo, s4
	global_load_lds_dwordx4 v[164:165], off
	s_mov_b32 m0, s76
	v_lshl_add_u64 v[206:207], s[72:73], 0, v[150:151]
	global_load_lds_dwordx4 v0, s[66:67]
	s_add_i32 m0, s76, 0x2000
	s_nop 0
	global_load_lds_dwordx4 v152, s[66:67]
	v_lshl_add_u64 v[202:203], s[72:73], 0, v[148:149]
	s_mov_b32 m0, s5
	s_nop 0
	global_load_lds_dwordx4 v[202:203], off
	s_mov_b32 m0, s6
	s_nop 0
	global_load_lds_dwordx4 v[206:207], off
	ds_read_b128 v[182:185], v214 offset:16384
	ds_read_b128 v[186:189], v214 offset:17408
	ds_read_b128 v[190:193], v214 offset:18432
	ds_read_b128 v[194:197], v214 offset:19456
	ds_read_b128 v[198:201], v214 offset:20480
	ds_read_b128 v[216:219], v214 offset:21504
	ds_read_b128 v[220:223], v214 offset:22528
	ds_read_b128 v[224:227], v214 offset:23552
	s_waitcnt vmcnt(8)
	s_waitcnt lgkmcnt(0)
	s_barrier
; #define PG8_STAGE(bufoff, gbase, voff) do { _Pragma("unroll") for (int _i = 0; _i < 2; ++_i) \
;         __builtin_amdgcn_global_load_lds((const unsigned*)((const char*)(gbase) + (voff)[_i]), (LAS unsigned*)(lds + (bufoff) + ldsw + _i * 8192), 16, 0, 0); } while (0)
; #define PG8_LDA(dst, b, h) do { _Pragma("unroll") for (int m = 0; m < 4; ++m) _Pragma("unroll") for (int k = 0; k < 2; ++k) dst[m][k] = *(const LAS bf16x8*)(lds + PG8_SA(b, h) + aoff + m * 2048 + k * 1024); } while (0)
; #define PG8_LDB(dst, b, h) do { _Pragma("unroll") for (int n = 0; n < 2; ++n) _Pragma("unroll") for (int k = 0; k < 2; ++k) dst[n][k] = *(const LAS bf16x8*)(lds + PG8_SB(b, h) + boff + n * 2048 + k * 1024); } while (0)
; #define PG8_MMA(ai, bj, At, Bt) do { __builtin_amdgcn_s_setprio(1); _Pragma("unroll") for (int m = 0; m < 4; ++m) _Pragma("unroll") for (int n = 0; n < 2; ++n) _Pragma("unroll") for (int k = 0; k < 2; ++k) \
;         acc[ai][bj][m][n] = __builtin_amdgcn_mfma_f32_16x16x32_bf16(Bt[n][k], At[m][k], acc[ai][bj][m][n], 0, 0, 0); __builtin_amdgcn_s_setprio(0); } while (0)
; #define PG8_WAIT_V(n) asm volatile("s_waitcnt vmcnt(" #n ")" ::: "memory")
; #define PG8_WAIT_L(n) asm volatile("s_waitcnt lgkmcnt(" #n ")" ::: "memory")
; #define PG8_BAR __builtin_amdgcn_s_barrier()
; #define PG8_SCHED __builtin_amdgcn_sched_barrier(0)
; template <class Epi>
; __device__ __forceinline__ void gemm_phase(LAS unsigned char* lds, const int tid, const Gemm g, const StaticOrder& S, const Epi& E) {
;     ...
;             PG8_WAIT_V(8); PG8_WAIT_L(0); PG8_BAR; PG8_MMA(1, 0, At, B0); PG8_MMA(1, 1, At, B1); PG8_BAR; PG8_SCHED;
;             PG8_LDB(B0, 1, 0); PG8_LDB(B1, 1, 1); PG8_SCHED; PG8_LDA(At, 1, 0); PG8_STAGE(PG8_SA(0, 1), a2 + hstepA, voffA);
;             PG8_WAIT_V(8); PG8_WAIT_L(0); PG8_BAR; PG8_MMA(0, 0, At, B0); PG8_MMA(0, 1, At, B1); PG8_BAR; PG8_SCHED;
	s_setprio 1
	s_waitcnt lgkmcnt(0)
	v_mfma_f32_16x16x32_bf16 v[78:81], v[42:45], v[182:185], v[78:81]
	v_mfma_f32_16x16x32_bf16 v[74:77], v[66:69], v[182:185], v[74:77]
	v_mfma_f32_16x16x32_bf16 v[54:57], v[42:45], v[190:193], v[54:57]
	v_mfma_f32_16x16x32_bf16 v[50:53], v[66:69], v[190:193], v[50:53]
	v_mfma_f32_16x16x32_bf16 v[30:33], v[42:45], v[198:201], v[30:33]
	v_mfma_f32_16x16x32_bf16 v[26:29], v[66:69], v[198:201], v[26:29]
	v_mfma_f32_16x16x32_bf16 v[14:17], v[42:45], v[220:223], v[14:17]
	v_mfma_f32_16x16x32_bf16 v[10:13], v[66:69], v[220:223], v[10:13]
	v_mfma_f32_16x16x32_bf16 v[78:81], v[46:49], v[186:189], v[78:81]
	v_mfma_f32_16x16x32_bf16 v[74:77], v[70:73], v[186:189], v[74:77]
	v_mfma_f32_16x16x32_bf16 v[54:57], v[46:49], v[194:197], v[54:57]
	v_mfma_f32_16x16x32_bf16 v[50:53], v[70:73], v[194:197], v[50:53]
	v_mfma_f32_16x16x32_bf16 v[30:33], v[46:49], v[216:219], v[30:33]
	v_mfma_f32_16x16x32_bf16 v[26:29], v[70:73], v[216:219], v[26:29]
	v_mfma_f32_16x16x32_bf16 v[14:17], v[46:49], v[224:227], v[14:17]
	v_mfma_f32_16x16x32_bf16 v[10:13], v[70:73], v[224:227], v[10:13]
	s_setprio 0
	s_setprio 1
	v_mfma_f32_16x16x32_bf16 v[38:41], v[158:161], v[190:193], v[38:41]
	v_mfma_f32_16x16x32_bf16 v[34:37], v[174:177], v[190:193], v[34:37]
	v_mfma_f32_16x16x32_bf16 v[22:25], v[158:161], v[198:201], v[22:25]
	v_mfma_f32_16x16x32_bf16 v[18:21], v[174:177], v[198:201], v[18:21]
	v_mfma_f32_16x16x32_bf16 v[6:9], v[158:161], v[220:223], v[6:9]
	v_mfma_f32_16x16x32_bf16 v[2:5], v[174:177], v[220:223], v[2:5]
	v_mfma_f32_16x16x32_bf16 v[42:45], v[158:161], v[182:185], v[62:65]
	v_mfma_f32_16x16x32_bf16 v[46:49], v[174:177], v[182:185], v[58:61]
	v_mfma_f32_16x16x32_bf16 v[38:41], v[170:173], v[194:197], v[38:41]
	v_mfma_f32_16x16x32_bf16 v[34:37], v[178:181], v[194:197], v[34:37]
	v_mfma_f32_16x16x32_bf16 v[22:25], v[170:173], v[216:219], v[22:25]
	v_mfma_f32_16x16x32_bf16 v[18:21], v[178:181], v[216:219], v[18:21]
	v_mfma_f32_16x16x32_bf16 v[6:9], v[170:173], v[224:227], v[6:9]
	v_mfma_f32_16x16x32_bf16 v[2:5], v[178:181], v[224:227], v[2:5]
	v_mfma_f32_16x16x32_bf16 v[42:45], v[170:173], v[186:189], v[42:45]
	v_mfma_f32_16x16x32_bf16 v[46:49], v[178:181], v[186:189], v[46:49]
	s_setprio 0
	s_barrier
	s_add_i32 s76, 0, 0x18000
	s_add_i32 vcc_lo, 0, 0x1c000
	v_add_u32_e32 v70, s76, v212
	v_add_u32_e32 v178, vcc_lo, v212
	ds_read_b128 v[58:61], v70
	ds_read_b128 v[62:65], v70 offset:1024
	ds_read_b128 v[66:69], v70 offset:2048
	ds_read_b128 v[70:73], v70 offset:3072
	ds_read_b128 v[158:161], v178
	ds_read_b128 v[170:173], v178 offset:1024
	ds_read_b128 v[174:177], v178 offset:2048
	ds_read_b128 v[178:181], v178 offset:3072
	s_add_u32 s66, s72, 0x160000
	s_addc_u32 s67, s73, 0
	s_mov_b32 m0, s7
	s_nop 0
	global_load_lds_dwordx4 v148, s[66:67]
	s_mov_b32 m0, s74
	s_nop 0
	global_load_lds_dwordx4 v150, s[66:67]
	ds_read_b128 v[182:185], v214 offset:32768
	ds_read_b128 v[186:189], v214 offset:33792
	ds_read_b128 v[190:193], v214 offset:34816
	ds_read_b128 v[194:197], v214 offset:35840
	ds_read_b128 v[198:201], v214 offset:36864
	ds_read_b128 v[216:219], v214 offset:37888
	ds_read_b128 v[220:223], v214 offset:38912
	ds_read_b128 v[224:227], v214 offset:39936
	s_waitcnt vmcnt(8)
	s_waitcnt lgkmcnt(0)
	s_barrier
	s_setprio 1
	s_waitcnt lgkmcnt(0)
	v_mfma_f32_16x16x32_bf16 v[142:145], v[58:61], v[182:185], v[142:145]
	v_mfma_f32_16x16x32_bf16 v[138:141], v[66:69], v[182:185], v[138:141]
	v_mfma_f32_16x16x32_bf16 v[126:129], v[58:61], v[190:193], v[126:129]
	v_mfma_f32_16x16x32_bf16 v[122:125], v[66:69], v[190:193], v[122:125]
	v_mfma_f32_16x16x32_bf16 v[110:113], v[58:61], v[198:201], v[110:113]
	v_mfma_f32_16x16x32_bf16 v[106:109], v[66:69], v[198:201], v[106:109]
	v_mfma_f32_16x16x32_bf16 v[94:97], v[58:61], v[220:223], v[94:97]
	v_mfma_f32_16x16x32_bf16 v[90:93], v[66:69], v[220:223], v[90:93]
	v_mfma_f32_16x16x32_bf16 v[142:145], v[62:65], v[186:189], v[142:145]
	v_mfma_f32_16x16x32_bf16 v[138:141], v[70:73], v[186:189], v[138:141]
	v_mfma_f32_16x16x32_bf16 v[126:129], v[62:65], v[194:197], v[126:129]
	v_mfma_f32_16x16x32_bf16 v[122:125], v[70:73], v[194:197], v[122:125]
	v_mfma_f32_16x16x32_bf16 v[110:113], v[62:65], v[216:219], v[110:113]
	v_mfma_f32_16x16x32_bf16 v[106:109], v[70:73], v[216:219], v[106:109]
	v_mfma_f32_16x16x32_bf16 v[94:97], v[62:65], v[224:227], v[94:97]
	v_mfma_f32_16x16x32_bf16 v[90:93], v[70:73], v[224:227], v[90:93]
	s_setprio 0
	s_setprio 1
	v_mfma_f32_16x16x32_bf16 v[134:137], v[158:161], v[182:185], v[134:137]
	v_mfma_f32_16x16x32_bf16 v[130:133], v[174:177], v[182:185], v[130:133]
	v_mfma_f32_16x16x32_bf16 v[118:121], v[158:161], v[190:193], v[118:121]
	v_mfma_f32_16x16x32_bf16 v[114:117], v[174:177], v[190:193], v[114:117]
	v_mfma_f32_16x16x32_bf16 v[102:105], v[158:161], v[198:201], v[102:105]
	v_mfma_f32_16x16x32_bf16 v[98:101], v[174:177], v[198:201], v[98:101]
	v_mfma_f32_16x16x32_bf16 v[86:89], v[158:161], v[220:223], v[86:89]
	v_mfma_f32_16x16x32_bf16 v[82:85], v[174:177], v[220:223], v[82:85]
	v_mfma_f32_16x16x32_bf16 v[134:137], v[170:173], v[186:189], v[134:137]
	v_mfma_f32_16x16x32_bf16 v[130:133], v[178:181], v[186:189], v[130:133]
	v_mfma_f32_16x16x32_bf16 v[118:121], v[170:173], v[194:197], v[118:121]
	v_mfma_f32_16x16x32_bf16 v[114:117], v[178:181], v[194:197], v[114:117]
	v_mfma_f32_16x16x32_bf16 v[102:105], v[170:173], v[216:219], v[102:105]
	v_mfma_f32_16x16x32_bf16 v[98:101], v[178:181], v[216:219], v[98:101]
	v_mfma_f32_16x16x32_bf16 v[86:89], v[170:173], v[224:227], v[86:89]
	v_mfma_f32_16x16x32_bf16 v[82:85], v[178:181], v[224:227], v[82:85]
	s_setprio 0
	s_barrier
; #define PG8_STAGE(bufoff, gbase, voff) do { _Pragma("unroll") for (int _i = 0; _i < 2; ++_i) \
;         __builtin_amdgcn_global_load_lds((const unsigned*)((const char*)(gbase) + (voff)[_i]), (LAS unsigned*)(lds + (bufoff) + ldsw + _i * 8192), 16, 0, 0); } while (0)
; #define PG8_LDA(dst, b, h) do { _Pragma("unroll") for (int m = 0; m < 4; ++m) _Pragma("unroll") for (int k = 0; k < 2; ++k) dst[m][k] = *(const LAS bf16x8*)(lds + PG8_SA(b, h) + aoff + m * 2048 + k * 1024); } while (0)
; #define PG8_MMA(ai, bj, At, Bt) do { __builtin_amdgcn_s_setprio(1); _Pragma("unroll") for (int m = 0; m < 4; ++m) _Pragma("unroll") for (int n = 0; n < 2; ++n) _Pragma("unroll") for (int k = 0; k < 2; ++k) \
;         acc[ai][bj][m][n] = __builtin_amdgcn_mfma_f32_16x16x32_bf16(Bt[n][k], At[m][k], acc[ai][bj][m][n], 0, 0, 0); __builtin_amdgcn_s_setprio(0); } while (0)
; #define PG8_WAIT_V(n) asm volatile("s_waitcnt vmcnt(" #n ")" ::: "memory")
; #define PG8_WAIT_L(n) asm volatile("s_waitcnt lgkmcnt(" #n ")" ::: "memory")
; #define PG8_BAR __builtin_amdgcn_s_barrier()
; #define PG8_SCHED __builtin_amdgcn_sched_barrier(0)
; template <class Epi>
; __device__ __forceinline__ void gemm_phase(LAS unsigned char* lds, const int tid, const Gemm g, const StaticOrder& S, const Epi& E) {
;     ...
;             PG8_LDA(At, 1, 1); PG8_STAGE(PG8_SB(1, 0), b3, voffB); PG8_STAGE(PG8_SB(1, 1), b3 + hstepB, voffB); PG8_STAGE(PG8_SA(1, 0), a3, voffA);
;             PG8_WAIT_V(8); PG8_WAIT_L(0); PG8_BAR; PG8_MMA(1, 0, At, B0); PG8_MMA(1, 1, At, B1); PG8_BAR; PG8_SCHED;
;         }
;         if (wr == 0) PG8_BAR;
	s_add_i32 s66, s76, s4
	v_lshl_add_u64 v[162:163], v[162:163], 0, s[36:37]
	s_mov_b32 m0, s66
	s_nop 0
	global_load_lds_dwordx4 v[162:163], off
	s_add_i32 m0, s66, 0x2000
	s_add_u32 s66, s70, 0xb0080
	v_lshl_add_u64 v[162:163], v[164:165], 0, s[36:37]
	s_addc_u32 s67, s71, 0
	s_add_i32 s70, vcc_lo, s4
	global_load_lds_dwordx4 v[162:163], off
	s_mov_b32 m0, s70
	s_nop 0
	global_load_lds_dwordx4 v0, s[66:67]
	s_add_i32 m0, s70, 0x2000
	s_nop 0
	global_load_lds_dwordx4 v152, s[66:67]
	v_lshl_add_u64 v[162:163], v[202:203], 0, s[36:37]
	s_mov_b32 m0, s77
	s_nop 0
	global_load_lds_dwordx4 v[162:163], off
	v_lshl_add_u64 v[162:163], v[206:207], 0, s[36:37]
	s_mov_b32 m0, s79
	s_nop 0
	global_load_lds_dwordx4 v[162:163], off
	ds_read_b128 v[182:185], v214 offset:49152
	ds_read_b128 v[186:189], v214 offset:50176
	ds_read_b128 v[190:193], v214 offset:51200
	ds_read_b128 v[194:197], v214 offset:52224
	ds_read_b128 v[198:201], v214 offset:53248
	ds_read_b128 v[216:219], v214 offset:54272
	ds_read_b128 v[220:223], v214 offset:55296
	ds_read_b128 v[224:227], v214 offset:56320
	s_waitcnt vmcnt(8)
	s_waitcnt lgkmcnt(0)
	s_barrier
	s_setprio 1
	s_waitcnt lgkmcnt(0)
	v_mfma_f32_16x16x32_bf16 v[78:81], v[58:61], v[182:185], v[78:81]
	v_mfma_f32_16x16x32_bf16 v[74:77], v[66:69], v[182:185], v[74:77]
	v_mfma_f32_16x16x32_bf16 v[54:57], v[58:61], v[190:193], v[54:57]
	v_mfma_f32_16x16x32_bf16 v[50:53], v[66:69], v[190:193], v[50:53]
	v_mfma_f32_16x16x32_bf16 v[30:33], v[58:61], v[198:201], v[30:33]
	v_mfma_f32_16x16x32_bf16 v[26:29], v[66:69], v[198:201], v[26:29]
	v_mfma_f32_16x16x32_bf16 v[14:17], v[58:61], v[220:223], v[14:17]
	v_mfma_f32_16x16x32_bf16 v[10:13], v[66:69], v[220:223], v[10:13]
	v_mfma_f32_16x16x32_bf16 v[78:81], v[62:65], v[186:189], v[78:81]
	v_mfma_f32_16x16x32_bf16 v[74:77], v[70:73], v[186:189], v[74:77]
	v_mfma_f32_16x16x32_bf16 v[54:57], v[62:65], v[194:197], v[54:57]
	v_mfma_f32_16x16x32_bf16 v[50:53], v[70:73], v[194:197], v[50:53]
	v_mfma_f32_16x16x32_bf16 v[30:33], v[62:65], v[216:219], v[30:33]
	v_mfma_f32_16x16x32_bf16 v[26:29], v[70:73], v[216:219], v[26:29]
	v_mfma_f32_16x16x32_bf16 v[14:17], v[62:65], v[224:227], v[14:17]
	v_mfma_f32_16x16x32_bf16 v[10:13], v[70:73], v[224:227], v[10:13]
	s_setprio 0
	s_setprio 1
	v_mfma_f32_16x16x32_bf16 v[42:45], v[158:161], v[182:185], v[42:45]
	v_mfma_f32_16x16x32_bf16 v[62:65], v[170:173], v[186:189], v[42:45]
	v_mfma_f32_16x16x32_bf16 v[42:45], v[174:177], v[182:185], v[46:49]
	v_mfma_f32_16x16x32_bf16 v[38:41], v[158:161], v[190:193], v[38:41]
	v_mfma_f32_16x16x32_bf16 v[34:37], v[174:177], v[190:193], v[34:37]
	v_mfma_f32_16x16x32_bf16 v[22:25], v[158:161], v[198:201], v[22:25]
	v_mfma_f32_16x16x32_bf16 v[18:21], v[174:177], v[198:201], v[18:21]
	v_mfma_f32_16x16x32_bf16 v[6:9], v[158:161], v[220:223], v[6:9]
	v_mfma_f32_16x16x32_bf16 v[2:5], v[174:177], v[220:223], v[2:5]
	v_mfma_f32_16x16x32_bf16 v[58:61], v[178:181], v[186:189], v[42:45]
	v_mfma_f32_16x16x32_bf16 v[38:41], v[170:173], v[194:197], v[38:41]
	v_mfma_f32_16x16x32_bf16 v[34:37], v[178:181], v[194:197], v[34:37]
	v_mfma_f32_16x16x32_bf16 v[22:25], v[170:173], v[216:219], v[22:25]
	v_mfma_f32_16x16x32_bf16 v[18:21], v[178:181], v[216:219], v[18:21]
	v_mfma_f32_16x16x32_bf16 v[6:9], v[170:173], v[224:227], v[6:9]
	v_mfma_f32_16x16x32_bf16 v[2:5], v[178:181], v[224:227], v[2:5]
	s_setprio 0
	s_barrier
	s_add_i32 s93, s93, 2
	s_add_u32 s11, s11, 0x100
	s_addc_u32 s28, s28, 0
	s_cmp_gt_u32 s93, 41
	s_mov_b64 s[66:67], s[68:69]
	s_cbranch_scc0 .LBB0_2303
	s_and_b64 vcc, exec, s[26:27]
	s_cbranch_vccz .LBB0_2306
	s_barrier

; #define PG8_STAGE(bufoff, gbase, voff) do { _Pragma("unroll") for (int _i = 0; _i < 2; ++_i) \
;         __builtin_amdgcn_global_load_lds((const unsigned*)((const char*)(gbase) + (voff)[_i]), (LAS unsigned*)(lds + (bufoff) + ldsw + _i * 8192), 16, 0, 0); } while (0)
; #define PG8_LDA(dst, b, h) do { _Pragma("unroll") for (int m = 0; m < 4; ++m) _Pragma("unroll") for (int k = 0; k < 2; ++k) dst[m][k] = *(const LAS bf16x8*)(lds + PG8_SA(b, h) + aoff + m * 2048 + k * 1024); } while (0)
; #define PG8_LDB(dst, b, h) do { _Pragma("unroll") for (int n = 0; n < 2; ++n) _Pragma("unroll") for (int k = 0; k < 2; ++k) dst[n][k] = *(const LAS bf16x8*)(lds + PG8_SB(b, h) + boff + n * 2048 + k * 1024); } while (0)
; #define PG8_MMA(ai, bj, At, Bt) do { __builtin_amdgcn_s_setprio(1); _Pragma("unroll") for (int m = 0; m < 4; ++m) _Pragma("unroll") for (int n = 0; n < 2; ++n) _Pragma("unroll") for (int k = 0; k < 2; ++k) \
;         acc[ai][bj][m][n] = __builtin_amdgcn_mfma_f32_16x16x32_bf16(Bt[n][k], At[m][k], acc[ai][bj][m][n], 0, 0, 0); __builtin_amdgcn_s_setprio(0); } while (0)
; #define PG8_WAIT_V(n) asm volatile("s_waitcnt vmcnt(" #n ")" ::: "memory")
; #define PG8_WAIT_L(n) asm volatile("s_waitcnt lgkmcnt(" #n ")" ::: "memory")
; #define PG8_BAR __builtin_amdgcn_s_barrier()
; #define PG8_SCHED __builtin_amdgcn_sched_barrier(0)
; template <class Epi>
; __device__ __forceinline__ void gemm_phase(LAS unsigned char* lds, const int tid, const Gemm g, const StaticOrder& S, const Epi& E) {
;     ...
;         for (int t = 0; t < nt; t += 2) {
;             const bool last = (t == nt - 2);
;             const char* a1 = cA + (size_t)(t + 1) * kstep;
;             const char* a2 = last ? nA : cA + (size_t)(t + 2) * kstep; const char* b2 = last ? nB : cB + (size_t)(t + 2) * kstep;
;             const char* a3 = a2 + kstep; const char* b3 = b2 + kstep;
;             PG8_LDB(B0, 0, 0); PG8_LDB(B1, 0, 1); PG8_SCHED; PG8_LDA(At, 0, 0); PG8_STAGE(PG8_SA(1, 1), a1 + hstepA, voffA);
;             PG8_WAIT_V(8); PG8_WAIT_L(0); PG8_BAR; PG8_MMA(0, 0, At, B0); PG8_MMA(0, 1, At, B1); PG8_BAR; PG8_SCHED;
;             PG8_LDA(At, 0, 1); PG8_STAGE(PG8_SB(0, 0), b2, voffB); PG8_STAGE(PG8_SB(0, 1), b2 + hstepB, voffB); PG8_STAGE(PG8_SA(0, 0), a2, voffA);
;             PG8_WAIT_V(8); PG8_WAIT_L(0); PG8_BAR; PG8_MMA(1, 0, At, B0); PG8_MMA(1, 1, At, B1); PG8_BAR; PG8_SCHED;
.LBB0_2353:
	s_add_u32 s70, s68, 0x100
	s_addc_u32 s71, s69, 0
	s_add_i32 s76, 0, 0x10000
	s_cmp_eq_u32 vcc_hi, 40
	s_cselect_b32 s75, s1, s71
	s_cselect_b32 s74, s0, s70
	s_cselect_b32 s73, s31, vcc_lo
	s_cselect_b32 s72, s30, s11
	s_add_i32 s2, 0, 0x14000
	v_add_u32_e32 v154, s76, v199
	v_add_u32_e32 v162, s2, v199
	ds_read_b128 v[130:133], v154
	ds_read_b128 v[134:137], v154 offset:1024
	ds_read_b128 v[138:141], v154 offset:2048
	ds_read_b128 v[154:157], v154 offset:3072
	ds_read_b128 v[158:161], v162
	ds_read_b128 v[170:173], v162 offset:1024
	ds_read_b128 v[174:177], v162 offset:2048
	ds_read_b128 v[212:215], v162 offset:3072
	s_add_i32 m0, s83, 0xc000
	s_nop 0
	global_load_lds_dwordx4 v150, s[68:69]
	s_add_i32 m0, s83, 0xe000
	s_nop 0
	global_load_lds_dwordx4 v152, s[68:69]
	ds_read_b128 v[216:219], v201
	ds_read_b128 v[220:223], v201 offset:1024
	ds_read_b128 v[224:227], v201 offset:2048
	ds_read_b128 v[228:231], v201 offset:3072
	ds_read_b128 v[232:235], v201 offset:4096
	ds_read_b128 v[236:239], v201 offset:5120
	ds_read_b128 v[240:243], v201 offset:6144
	ds_read_b128 v[244:247], v201 offset:7168
	s_waitcnt vmcnt(8)
	s_waitcnt lgkmcnt(0)
	s_barrier
	s_setprio 1
	s_waitcnt lgkmcnt(0)
	v_mfma_f32_16x16x32_bf16 v[126:129], v[130:133], v[216:219], v[126:129]
	v_mfma_f32_16x16x32_bf16 v[122:125], v[138:141], v[216:219], v[122:125]
	v_mfma_f32_16x16x32_bf16 v[110:113], v[130:133], v[224:227], v[110:113]
	v_mfma_f32_16x16x32_bf16 v[106:109], v[138:141], v[224:227], v[106:109]
	v_mfma_f32_16x16x32_bf16 v[94:97], v[130:133], v[232:235], v[94:97]
	v_mfma_f32_16x16x32_bf16 v[90:93], v[138:141], v[232:235], v[90:93]
	v_mfma_f32_16x16x32_bf16 v[78:81], v[130:133], v[240:243], v[78:81]
	v_mfma_f32_16x16x32_bf16 v[74:77], v[138:141], v[240:243], v[74:77]
	v_mfma_f32_16x16x32_bf16 v[126:129], v[134:137], v[220:223], v[126:129]
	v_mfma_f32_16x16x32_bf16 v[122:125], v[154:157], v[220:223], v[122:125]
	v_mfma_f32_16x16x32_bf16 v[110:113], v[134:137], v[228:231], v[110:113]
	v_mfma_f32_16x16x32_bf16 v[106:109], v[154:157], v[228:231], v[106:109]
	v_mfma_f32_16x16x32_bf16 v[94:97], v[134:137], v[236:239], v[94:97]
	v_mfma_f32_16x16x32_bf16 v[90:93], v[154:157], v[236:239], v[90:93]
	v_mfma_f32_16x16x32_bf16 v[78:81], v[134:137], v[244:247], v[78:81]
	v_mfma_f32_16x16x32_bf16 v[74:77], v[154:157], v[244:247], v[74:77]
	s_setprio 0
	s_setprio 1
	v_mfma_f32_16x16x32_bf16 v[118:121], v[158:161], v[216:219], v[118:121]
	v_mfma_f32_16x16x32_bf16 v[114:117], v[174:177], v[216:219], v[114:117]
	v_mfma_f32_16x16x32_bf16 v[102:105], v[158:161], v[224:227], v[102:105]
	v_mfma_f32_16x16x32_bf16 v[98:101], v[174:177], v[224:227], v[98:101]
	v_mfma_f32_16x16x32_bf16 v[86:89], v[158:161], v[232:235], v[86:89]
	v_mfma_f32_16x16x32_bf16 v[82:85], v[174:177], v[232:235], v[82:85]
	v_mfma_f32_16x16x32_bf16 v[70:73], v[158:161], v[240:243], v[70:73]
	v_mfma_f32_16x16x32_bf16 v[66:69], v[174:177], v[240:243], v[66:69]
	v_mfma_f32_16x16x32_bf16 v[118:121], v[170:173], v[220:223], v[118:121]
	v_mfma_f32_16x16x32_bf16 v[114:117], v[212:215], v[220:223], v[114:117]
	v_mfma_f32_16x16x32_bf16 v[102:105], v[170:173], v[228:231], v[102:105]
	v_mfma_f32_16x16x32_bf16 v[98:101], v[212:215], v[228:231], v[98:101]
	v_mfma_f32_16x16x32_bf16 v[86:89], v[170:173], v[236:239], v[86:89]
	v_mfma_f32_16x16x32_bf16 v[82:85], v[212:215], v[236:239], v[82:85]
	v_mfma_f32_16x16x32_bf16 v[70:73], v[170:173], v[244:247], v[70:73]
	v_mfma_f32_16x16x32_bf16 v[66:69], v[212:215], v[244:247], v[66:69]
	s_setprio 0
	s_barrier
	s_add_i32 s3, s76, s82
	v_lshl_add_u64 v[162:163], s[72:73], 0, v[0:1]
	s_mov_b32 m0, s3
	s_nop 0
	global_load_lds_dwordx4 v[162:163], off
	s_add_i32 m0, s3, 0x2000
	s_add_u32 s68, s72, 0xb0000
	v_lshl_add_u64 v[164:165], s[72:73], 0, v[142:143]
	s_addc_u32 s69, s73, 0
	s_add_i32 s2, s2, s82
	global_load_lds_dwordx4 v[164:165], off
	s_mov_b32 m0, s2
	v_lshl_add_u64 v[206:207], s[74:75], 0, v[148:149]
	global_load_lds_dwordx4 v0, s[68:69]
	s_add_i32 m0, s2, 0x2000
	s_nop 0
	global_load_lds_dwordx4 v142, s[68:69]
	v_lshl_add_u64 v[178:179], s[74:75], 0, v[144:145]
	s_mov_b32 m0, s83
	s_nop 0
	global_load_lds_dwordx4 v[178:179], off
	s_mov_b32 m0, s88
	s_nop 0
	global_load_lds_dwordx4 v[206:207], off
	ds_read_b128 v[216:219], v201 offset:16384
	ds_read_b128 v[220:223], v201 offset:17408
	ds_read_b128 v[224:227], v201 offset:18432
	ds_read_b128 v[228:231], v201 offset:19456
	ds_read_b128 v[232:235], v201 offset:20480
	ds_read_b128 v[236:239], v201 offset:21504
	ds_read_b128 v[240:243], v201 offset:22528
	ds_read_b128 v[244:247], v201 offset:23552
	s_waitcnt vmcnt(8)
	s_waitcnt lgkmcnt(0)
	s_barrier
; #define PG8_STAGE(bufoff, gbase, voff) do { _Pragma("unroll") for (int _i = 0; _i < 2; ++_i) \
;         __builtin_amdgcn_global_load_lds((const unsigned*)((const char*)(gbase) + (voff)[_i]), (LAS unsigned*)(lds + (bufoff) + ldsw + _i * 8192), 16, 0, 0); } while (0)
; #define PG8_LDA(dst, b, h) do { _Pragma("unroll") for (int m = 0; m < 4; ++m) _Pragma("unroll") for (int k = 0; k < 2; ++k) dst[m][k] = *(const LAS bf16x8*)(lds + PG8_SA(b, h) + aoff + m * 2048 + k * 1024); } while (0)
; #define PG8_LDB(dst, b, h) do { _Pragma("unroll") for (int n = 0; n < 2; ++n) _Pragma("unroll") for (int k = 0; k < 2; ++k) dst[n][k] = *(const LAS bf16x8*)(lds + PG8_SB(b, h) + boff + n * 2048 + k * 1024); } while (0)
; #define PG8_MMA(ai, bj, At, Bt) do { __builtin_amdgcn_s_setprio(1); _Pragma("unroll") for (int m = 0; m < 4; ++m) _Pragma("unroll") for (int n = 0; n < 2; ++n) _Pragma("unroll") for (int k = 0; k < 2; ++k) \
;         acc[ai][bj][m][n] = __builtin_amdgcn_mfma_f32_16x16x32_bf16(Bt[n][k], At[m][k], acc[ai][bj][m][n], 0, 0, 0); __builtin_amdgcn_s_setprio(0); } while (0)
; #define PG8_WAIT_V(n) asm volatile("s_waitcnt vmcnt(" #n ")" ::: "memory")
; #define PG8_WAIT_L(n) asm volatile("s_waitcnt lgkmcnt(" #n ")" ::: "memory")
; #define PG8_BAR __builtin_amdgcn_s_barrier()
; #define PG8_SCHED __builtin_amdgcn_sched_barrier(0)
; template <class Epi>
; __device__ __forceinline__ void gemm_phase(LAS unsigned char* lds, const int tid, const Gemm g, const StaticOrder& S, const Epi& E) {
;     ...
;             PG8_WAIT_V(8); PG8_WAIT_L(0); PG8_BAR; PG8_MMA(1, 0, At, B0); PG8_MMA(1, 1, At, B1); PG8_BAR; PG8_SCHED;
;             PG8_LDB(B0, 1, 0); PG8_LDB(B1, 1, 1); PG8_SCHED; PG8_LDA(At, 1, 0); PG8_STAGE(PG8_SA(0, 1), a2 + hstepA, voffA);
;             PG8_WAIT_V(8); PG8_WAIT_L(0); PG8_BAR; PG8_MMA(0, 0, At, B0); PG8_MMA(0, 1, At, B1); PG8_BAR; PG8_SCHED;
	s_setprio 1
	s_waitcnt lgkmcnt(0)
	v_mfma_f32_16x16x32_bf16 v[62:65], v[130:133], v[216:219], v[62:65]
	v_mfma_f32_16x16x32_bf16 v[58:61], v[138:141], v[216:219], v[58:61]
	v_mfma_f32_16x16x32_bf16 v[46:49], v[130:133], v[224:227], v[46:49]
	v_mfma_f32_16x16x32_bf16 v[42:45], v[138:141], v[224:227], v[42:45]
	v_mfma_f32_16x16x32_bf16 v[30:33], v[130:133], v[232:235], v[30:33]
	v_mfma_f32_16x16x32_bf16 v[26:29], v[138:141], v[232:235], v[26:29]
	v_mfma_f32_16x16x32_bf16 v[14:17], v[130:133], v[240:243], v[14:17]
	v_mfma_f32_16x16x32_bf16 v[10:13], v[138:141], v[240:243], v[10:13]
	v_mfma_f32_16x16x32_bf16 v[62:65], v[134:137], v[220:223], v[62:65]
	v_mfma_f32_16x16x32_bf16 v[58:61], v[154:157], v[220:223], v[58:61]
	v_mfma_f32_16x16x32_bf16 v[46:49], v[134:137], v[228:231], v[46:49]
	v_mfma_f32_16x16x32_bf16 v[42:45], v[154:157], v[228:231], v[42:45]
	v_mfma_f32_16x16x32_bf16 v[30:33], v[134:137], v[236:239], v[30:33]
	v_mfma_f32_16x16x32_bf16 v[26:29], v[154:157], v[236:239], v[26:29]
	v_mfma_f32_16x16x32_bf16 v[14:17], v[134:137], v[244:247], v[14:17]
	v_mfma_f32_16x16x32_bf16 v[10:13], v[154:157], v[244:247], v[10:13]
	s_setprio 0
	s_setprio 1
	v_mfma_f32_16x16x32_bf16 v[54:57], v[158:161], v[216:219], v[54:57]
	v_mfma_f32_16x16x32_bf16 v[50:53], v[174:177], v[216:219], v[50:53]
	v_mfma_f32_16x16x32_bf16 v[38:41], v[158:161], v[224:227], v[38:41]
	v_mfma_f32_16x16x32_bf16 v[34:37], v[174:177], v[224:227], v[34:37]
	v_mfma_f32_16x16x32_bf16 v[22:25], v[158:161], v[232:235], v[22:25]
	v_mfma_f32_16x16x32_bf16 v[18:21], v[174:177], v[232:235], v[18:21]
	v_mfma_f32_16x16x32_bf16 v[6:9], v[158:161], v[240:243], v[6:9]
	v_mfma_f32_16x16x32_bf16 v[2:5], v[174:177], v[240:243], v[2:5]
	v_mfma_f32_16x16x32_bf16 v[54:57], v[170:173], v[220:223], v[54:57]
	v_mfma_f32_16x16x32_bf16 v[50:53], v[212:215], v[220:223], v[50:53]
	v_mfma_f32_16x16x32_bf16 v[38:41], v[170:173], v[228:231], v[38:41]
	v_mfma_f32_16x16x32_bf16 v[34:37], v[212:215], v[228:231], v[34:37]
	v_mfma_f32_16x16x32_bf16 v[22:25], v[170:173], v[236:239], v[22:25]
	v_mfma_f32_16x16x32_bf16 v[18:21], v[212:215], v[236:239], v[18:21]
	v_mfma_f32_16x16x32_bf16 v[6:9], v[170:173], v[244:247], v[6:9]
	v_mfma_f32_16x16x32_bf16 v[2:5], v[212:215], v[244:247], v[2:5]
	s_setprio 0
	s_barrier
	s_add_i32 s2, 0, 0x18000
	s_add_i32 s3, 0, 0x1c000
	v_add_u32_e32 v154, s2, v199
	v_add_u32_e32 v192, s3, v199
	ds_read_b128 v[130:133], v154
	ds_read_b128 v[134:137], v154 offset:1024
	ds_read_b128 v[138:141], v154 offset:2048
	ds_read_b128 v[154:157], v154 offset:3072
	ds_read_b128 v[158:161], v192
	ds_read_b128 v[170:173], v192 offset:1024
	ds_read_b128 v[174:177], v192 offset:2048
	ds_read_b128 v[212:215], v192 offset:3072
	s_add_u32 s68, s74, 0x160000
	s_addc_u32 s69, s75, 0
	s_mov_b32 m0, s89
	s_nop 0
	global_load_lds_dwordx4 v144, s[68:69]
	v_lshl_add_u64 v[192:193], s[68:69], 0, v[148:149]
	s_mov_b32 m0, s92
	s_nop 0
	global_load_lds_dwordx4 v[192:193], off
	ds_read_b128 v[216:219], v201 offset:32768
	ds_read_b128 v[220:223], v201 offset:33792
	ds_read_b128 v[224:227], v201 offset:34816
	ds_read_b128 v[228:231], v201 offset:35840
	ds_read_b128 v[232:235], v201 offset:36864
	ds_read_b128 v[236:239], v201 offset:37888
	ds_read_b128 v[240:243], v201 offset:38912
	ds_read_b128 v[244:247], v201 offset:39936
	s_waitcnt vmcnt(8)
	s_waitcnt lgkmcnt(0)
	s_barrier
	s_setprio 1
	s_waitcnt lgkmcnt(0)
	v_mfma_f32_16x16x32_bf16 v[126:129], v[130:133], v[216:219], v[126:129]
	v_mfma_f32_16x16x32_bf16 v[122:125], v[138:141], v[216:219], v[122:125]
	v_mfma_f32_16x16x32_bf16 v[110:113], v[130:133], v[224:227], v[110:113]
	v_mfma_f32_16x16x32_bf16 v[106:109], v[138:141], v[224:227], v[106:109]
	v_mfma_f32_16x16x32_bf16 v[94:97], v[130:133], v[232:235], v[94:97]
	v_mfma_f32_16x16x32_bf16 v[90:93], v[138:141], v[232:235], v[90:93]
	v_mfma_f32_16x16x32_bf16 v[78:81], v[130:133], v[240:243], v[78:81]
	v_mfma_f32_16x16x32_bf16 v[74:77], v[138:141], v[240:243], v[74:77]
	v_mfma_f32_16x16x32_bf16 v[126:129], v[134:137], v[220:223], v[126:129]
	v_mfma_f32_16x16x32_bf16 v[122:125], v[154:157], v[220:223], v[122:125]
	v_mfma_f32_16x16x32_bf16 v[110:113], v[134:137], v[228:231], v[110:113]
	v_mfma_f32_16x16x32_bf16 v[106:109], v[154:157], v[228:231], v[106:109]
	v_mfma_f32_16x16x32_bf16 v[94:97], v[134:137], v[236:239], v[94:97]
	v_mfma_f32_16x16x32_bf16 v[90:93], v[154:157], v[236:239], v[90:93]
	v_mfma_f32_16x16x32_bf16 v[78:81], v[134:137], v[244:247], v[78:81]
	v_mfma_f32_16x16x32_bf16 v[74:77], v[154:157], v[244:247], v[74:77]
	s_setprio 0
	s_setprio 1
	v_mfma_f32_16x16x32_bf16 v[118:121], v[158:161], v[216:219], v[118:121]
	v_mfma_f32_16x16x32_bf16 v[114:117], v[174:177], v[216:219], v[114:117]
	v_mfma_f32_16x16x32_bf16 v[102:105], v[158:161], v[224:227], v[102:105]
	v_mfma_f32_16x16x32_bf16 v[98:101], v[174:177], v[224:227], v[98:101]
	v_mfma_f32_16x16x32_bf16 v[86:89], v[158:161], v[232:235], v[86:89]
	v_mfma_f32_16x16x32_bf16 v[82:85], v[174:177], v[232:235], v[82:85]
	v_mfma_f32_16x16x32_bf16 v[70:73], v[158:161], v[240:243], v[70:73]
	v_mfma_f32_16x16x32_bf16 v[66:69], v[174:177], v[240:243], v[66:69]
	v_mfma_f32_16x16x32_bf16 v[118:121], v[170:173], v[220:223], v[118:121]
	v_mfma_f32_16x16x32_bf16 v[114:117], v[212:215], v[220:223], v[114:117]
	v_mfma_f32_16x16x32_bf16 v[102:105], v[170:173], v[228:231], v[102:105]
	v_mfma_f32_16x16x32_bf16 v[98:101], v[212:215], v[228:231], v[98:101]
	v_mfma_f32_16x16x32_bf16 v[86:89], v[170:173], v[236:239], v[86:89]
	v_mfma_f32_16x16x32_bf16 v[82:85], v[212:215], v[236:239], v[82:85]
	v_mfma_f32_16x16x32_bf16 v[70:73], v[170:173], v[244:247], v[70:73]
	v_mfma_f32_16x16x32_bf16 v[66:69], v[212:215], v[244:247], v[66:69]
	s_setprio 0
	s_barrier
; #define PG8_STAGE(bufoff, gbase, voff) do { _Pragma("unroll") for (int _i = 0; _i < 2; ++_i) \
;         __builtin_amdgcn_global_load_lds((const unsigned*)((const char*)(gbase) + (voff)[_i]), (LAS unsigned*)(lds + (bufoff) + ldsw + _i * 8192), 16, 0, 0); } while (0)
; #define PG8_LDA(dst, b, h) do { _Pragma("unroll") for (int m = 0; m < 4; ++m) _Pragma("unroll") for (int k = 0; k < 2; ++k) dst[m][k] = *(const LAS bf16x8*)(lds + PG8_SA(b, h) + aoff + m * 2048 + k * 1024); } while (0)
; #define PG8_MMA(ai, bj, At, Bt) do { __builtin_amdgcn_s_setprio(1); _Pragma("unroll") for (int m = 0; m < 4; ++m) _Pragma("unroll") for (int n = 0; n < 2; ++n) _Pragma("unroll") for (int k = 0; k < 2; ++k) \
;         acc[ai][bj][m][n] = __builtin_amdgcn_mfma_f32_16x16x32_bf16(Bt[n][k], At[m][k], acc[ai][bj][m][n], 0, 0, 0); __builtin_amdgcn_s_setprio(0); } while (0)
; #define PG8_WAIT_V(n) asm volatile("s_waitcnt vmcnt(" #n ")" ::: "memory")
; #define PG8_WAIT_L(n) asm volatile("s_waitcnt lgkmcnt(" #n ")" ::: "memory")
; #define PG8_BAR __builtin_amdgcn_s_barrier()
; #define PG8_SCHED __builtin_amdgcn_sched_barrier(0)
; template <class Epi>
; __device__ __forceinline__ void gemm_phase(LAS unsigned char* lds, const int tid, const Gemm g, const StaticOrder& S, const Epi& E) {
;     ...
;             PG8_LDA(At, 1, 1); PG8_STAGE(PG8_SB(1, 0), b3, voffB); PG8_STAGE(PG8_SB(1, 1), b3 + hstepB, voffB); PG8_STAGE(PG8_SA(1, 0), a3, voffA);
;             PG8_WAIT_V(8); PG8_WAIT_L(0); PG8_BAR; PG8_MMA(1, 0, At, B0); PG8_MMA(1, 1, At, B1); PG8_BAR; PG8_SCHED;
;         }
	s_add_i32 s2, s2, s82
	v_lshl_add_u64 v[162:163], v[162:163], 0, s[36:37]
	s_mov_b32 m0, s2
	s_nop 0
	global_load_lds_dwordx4 v[162:163], off
	s_add_i32 m0, s2, 0x2000
	s_add_u32 s68, s72, 0xb0080
	v_lshl_add_u64 v[162:163], v[164:165], 0, s[36:37]
	s_addc_u32 s69, s73, 0
	s_add_i32 s2, s3, s82
	global_load_lds_dwordx4 v[162:163], off
	s_mov_b32 m0, s2
	s_nop 0
	global_load_lds_dwordx4 v0, s[68:69]
	s_add_i32 m0, s2, 0x2000
	s_nop 0
	global_load_lds_dwordx4 v142, s[68:69]
	v_lshl_add_u64 v[162:163], v[178:179], 0, s[36:37]
	s_mov_b32 m0, s4
	s_nop 0
	global_load_lds_dwordx4 v[162:163], off
	v_lshl_add_u64 v[162:163], v[206:207], 0, s[36:37]
	s_mov_b32 m0, s5
	s_nop 0
	global_load_lds_dwordx4 v[162:163], off
	ds_read_b128 v[216:219], v201 offset:49152
	ds_read_b128 v[220:223], v201 offset:50176
	ds_read_b128 v[224:227], v201 offset:51200
	ds_read_b128 v[228:231], v201 offset:52224
	ds_read_b128 v[232:235], v201 offset:53248
	ds_read_b128 v[236:239], v201 offset:54272
	ds_read_b128 v[240:243], v201 offset:55296
	ds_read_b128 v[244:247], v201 offset:56320
	s_waitcnt vmcnt(8)
	s_waitcnt lgkmcnt(0)
	s_barrier
	s_setprio 1
	s_waitcnt lgkmcnt(0)
	v_mfma_f32_16x16x32_bf16 v[62:65], v[130:133], v[216:219], v[62:65]
	v_mfma_f32_16x16x32_bf16 v[58:61], v[138:141], v[216:219], v[58:61]
	v_mfma_f32_16x16x32_bf16 v[46:49], v[130:133], v[224:227], v[46:49]
	v_mfma_f32_16x16x32_bf16 v[42:45], v[138:141], v[224:227], v[42:45]
	v_mfma_f32_16x16x32_bf16 v[30:33], v[130:133], v[232:235], v[30:33]
	v_mfma_f32_16x16x32_bf16 v[26:29], v[138:141], v[232:235], v[26:29]
	v_mfma_f32_16x16x32_bf16 v[14:17], v[130:133], v[240:243], v[14:17]
	v_mfma_f32_16x16x32_bf16 v[10:13], v[138:141], v[240:243], v[10:13]
	v_mfma_f32_16x16x32_bf16 v[62:65], v[134:137], v[220:223], v[62:65]
	v_mfma_f32_16x16x32_bf16 v[58:61], v[154:157], v[220:223], v[58:61]
	v_mfma_f32_16x16x32_bf16 v[46:49], v[134:137], v[228:231], v[46:49]
	v_mfma_f32_16x16x32_bf16 v[42:45], v[154:157], v[228:231], v[42:45]
	v_mfma_f32_16x16x32_bf16 v[30:33], v[134:137], v[236:239], v[30:33]
	v_mfma_f32_16x16x32_bf16 v[26:29], v[154:157], v[236:239], v[26:29]
	v_mfma_f32_16x16x32_bf16 v[14:17], v[134:137], v[244:247], v[14:17]
	v_mfma_f32_16x16x32_bf16 v[10:13], v[154:157], v[244:247], v[10:13]
	s_setprio 0
	s_setprio 1
	v_mfma_f32_16x16x32_bf16 v[54:57], v[158:161], v[216:219], v[54:57]
	v_mfma_f32_16x16x32_bf16 v[50:53], v[174:177], v[216:219], v[50:53]
	v_mfma_f32_16x16x32_bf16 v[38:41], v[158:161], v[224:227], v[38:41]
	v_mfma_f32_16x16x32_bf16 v[34:37], v[174:177], v[224:227], v[34:37]
	v_mfma_f32_16x16x32_bf16 v[22:25], v[158:161], v[232:235], v[22:25]
	v_mfma_f32_16x16x32_bf16 v[18:21], v[174:177], v[232:235], v[18:21]
	v_mfma_f32_16x16x32_bf16 v[6:9], v[158:161], v[240:243], v[6:9]
	v_mfma_f32_16x16x32_bf16 v[2:5], v[174:177], v[240:243], v[2:5]
	v_mfma_f32_16x16x32_bf16 v[54:57], v[170:173], v[220:223], v[54:57]
	v_mfma_f32_16x16x32_bf16 v[50:53], v[212:215], v[220:223], v[50:53]
	v_mfma_f32_16x16x32_bf16 v[38:41], v[170:173], v[228:231], v[38:41]
	v_mfma_f32_16x16x32_bf16 v[34:37], v[212:215], v[228:231], v[34:37]
	v_mfma_f32_16x16x32_bf16 v[22:25], v[170:173], v[236:239], v[22:25]
	v_mfma_f32_16x16x32_bf16 v[18:21], v[212:215], v[236:239], v[18:21]
	v_mfma_f32_16x16x32_bf16 v[6:9], v[170:173], v[244:247], v[6:9]
	v_mfma_f32_16x16x32_bf16 v[2:5], v[212:215], v[244:247], v[2:5]
	s_setprio 0
	s_barrier
	s_add_i32 vcc_hi, vcc_hi, 2
	s_add_u32 s11, s11, 0x100
	s_addc_u32 vcc_lo, vcc_lo, 0
	s_cmp_gt_u32 vcc_hi, 41
	s_mov_b64 s[68:69], s[70:71]
	s_cbranch_scc0 .LBB0_2353
	s_and_b64 vcc, exec, s[26:27]
	s_cbranch_vccz .LBB0_2356
	s_barrier
